# adds hand-written modulation GEMV (16 loads in flight per wave)
# speedup vs baseline: 1.0060x; 1.0060x over previous
.LBB0_74:
.LBB0_75:
	s_load_dwordx2 s[0:1], s[92:93], 0x28
	s_load_dwordx2 s[2:3], s[92:93], 0x30
	s_load_dwordx2 s[4:5], s[92:93], 0x18
	s_load_dwordx2 s[6:7], s[92:93], 0x20
	v_lshlrev_b32_e32 v1, 2, v154
	s_waitcnt lgkmcnt(0)
	s_add_u32 s12, s4, 0x0
	s_addc_u32 s13, s5, 0
	global_load_dword v32, v1, s[12:13]
	s_add_u32 s12, s4, 0x800
	s_addc_u32 s13, s5, 0
	global_load_dword v33, v1, s[12:13]
	s_add_u32 s12, s4, 0x1000
	s_addc_u32 s13, s5, 0
	global_load_dword v34, v1, s[12:13]
	s_add_u32 s12, s4, 0x1800
	s_addc_u32 s13, s5, 0
	global_load_dword v35, v1, s[12:13]
	s_add_u32 s12, s4, 0x2000
	s_addc_u32 s13, s5, 0
	global_load_dword v36, v1, s[12:13]
	s_add_u32 s12, s4, 0x2800
	s_addc_u32 s13, s5, 0
	global_load_dword v37, v1, s[12:13]
	s_add_u32 s12, s4, 0x3000
	s_addc_u32 s13, s5, 0
	global_load_dword v38, v1, s[12:13]
	s_add_u32 s12, s4, 0x3800
	s_addc_u32 s13, s5, 0
	global_load_dword v39, v1, s[12:13]
	s_add_u32 s12, s4, 0x4000
	s_addc_u32 s13, s5, 0
	global_load_dword v40, v1, s[12:13]
	s_add_u32 s12, s4, 0x4800
	s_addc_u32 s13, s5, 0
	global_load_dword v41, v1, s[12:13]
	s_add_u32 s12, s4, 0x5000
	s_addc_u32 s13, s5, 0
	global_load_dword v42, v1, s[12:13]
	s_add_u32 s12, s4, 0x5800
	s_addc_u32 s13, s5, 0
	global_load_dword v43, v1, s[12:13]
	s_add_u32 s12, s4, 0x6000
	s_addc_u32 s13, s5, 0
	global_load_dword v44, v1, s[12:13]
	s_add_u32 s12, s4, 0x6800
	s_addc_u32 s13, s5, 0
	global_load_dword v45, v1, s[12:13]
	s_add_u32 s12, s4, 0x7000
	s_addc_u32 s13, s5, 0
	global_load_dword v46, v1, s[12:13]
	s_add_u32 s12, s4, 0x7800
	s_addc_u32 s13, s5, 0
	global_load_dword v47, v1, s[12:13]
	s_add_u32 s12, s6, 0x0
	s_addc_u32 s13, s7, 0
	global_load_dword v48, v1, s[12:13]
	s_add_u32 s12, s6, 0x800
	s_addc_u32 s13, s7, 0
	global_load_dword v49, v1, s[12:13]
	s_add_u32 s12, s6, 0x1000
	s_addc_u32 s13, s7, 0
	global_load_dword v50, v1, s[12:13]
	s_add_u32 s12, s6, 0x1800
	s_addc_u32 s13, s7, 0
	global_load_dword v51, v1, s[12:13]
	v_mov_b32_e32 v2, 0xbfb8aa3b
	s_waitcnt vmcnt(0)
	v_mul_f32_e32 v3, v2, v32
	v_exp_f32_e32 v3, v3
	s_nop 0
	v_add_f32_e32 v3, 1.0, v3
	v_rcp_f32_e32 v3, v3
	s_nop 0
	v_mul_f32_e32 v3, v3, v32
	ds_write_b32 v1, v3 offset:0
	v_mul_f32_e32 v3, v2, v33
	v_exp_f32_e32 v3, v3
	s_nop 0
	v_add_f32_e32 v3, 1.0, v3
	v_rcp_f32_e32 v3, v3
	s_nop 0
	v_mul_f32_e32 v3, v3, v33
	ds_write_b32 v1, v3 offset:2048
	v_mul_f32_e32 v3, v2, v34
	v_exp_f32_e32 v3, v3
	s_nop 0
	v_add_f32_e32 v3, 1.0, v3
	v_rcp_f32_e32 v3, v3
	s_nop 0
	v_mul_f32_e32 v3, v3, v34
	ds_write_b32 v1, v3 offset:4096
	v_mul_f32_e32 v3, v2, v35
	v_exp_f32_e32 v3, v3
	s_nop 0
	v_add_f32_e32 v3, 1.0, v3
	v_rcp_f32_e32 v3, v3
	s_nop 0
	v_mul_f32_e32 v3, v3, v35
	ds_write_b32 v1, v3 offset:6144
	v_mul_f32_e32 v3, v2, v36
	v_exp_f32_e32 v3, v3
	s_nop 0
	v_add_f32_e32 v3, 1.0, v3
	v_rcp_f32_e32 v3, v3
	s_nop 0
	v_mul_f32_e32 v3, v3, v36
	ds_write_b32 v1, v3 offset:8192
	v_mul_f32_e32 v3, v2, v37
	v_exp_f32_e32 v3, v3
	s_nop 0
	v_add_f32_e32 v3, 1.0, v3
	v_rcp_f32_e32 v3, v3
	s_nop 0
	v_mul_f32_e32 v3, v3, v37
	ds_write_b32 v1, v3 offset:10240
	v_mul_f32_e32 v3, v2, v38
	v_exp_f32_e32 v3, v3
	s_nop 0
	v_add_f32_e32 v3, 1.0, v3
	v_rcp_f32_e32 v3, v3
	s_nop 0
	v_mul_f32_e32 v3, v3, v38
	ds_write_b32 v1, v3 offset:12288
	v_mul_f32_e32 v3, v2, v39
	v_exp_f32_e32 v3, v3
	s_nop 0
	v_add_f32_e32 v3, 1.0, v3
	v_rcp_f32_e32 v3, v3
	s_nop 0
	v_mul_f32_e32 v3, v3, v39
	ds_write_b32 v1, v3 offset:14336
	v_mul_f32_e32 v3, v2, v40
	v_exp_f32_e32 v3, v3
	s_nop 0
	v_add_f32_e32 v3, 1.0, v3
	v_rcp_f32_e32 v3, v3
	s_nop 0
	v_mul_f32_e32 v3, v3, v40
	ds_write_b32 v1, v3 offset:16384
	v_mul_f32_e32 v3, v2, v41
	v_exp_f32_e32 v3, v3
	s_nop 0
	v_add_f32_e32 v3, 1.0, v3
	v_rcp_f32_e32 v3, v3
	s_nop 0
	v_mul_f32_e32 v3, v3, v41
	ds_write_b32 v1, v3 offset:18432
	v_mul_f32_e32 v3, v2, v42
	v_exp_f32_e32 v3, v3
	s_nop 0
	v_add_f32_e32 v3, 1.0, v3
	v_rcp_f32_e32 v3, v3
	s_nop 0
	v_mul_f32_e32 v3, v3, v42
	ds_write_b32 v1, v3 offset:20480
	v_mul_f32_e32 v3, v2, v43
	v_exp_f32_e32 v3, v3
	s_nop 0
	v_add_f32_e32 v3, 1.0, v3
	v_rcp_f32_e32 v3, v3
	s_nop 0
	v_mul_f32_e32 v3, v3, v43
	ds_write_b32 v1, v3 offset:22528
	v_mul_f32_e32 v3, v2, v44
	v_exp_f32_e32 v3, v3
	s_nop 0
	v_add_f32_e32 v3, 1.0, v3
	v_rcp_f32_e32 v3, v3
	s_nop 0
	v_mul_f32_e32 v3, v3, v44
	ds_write_b32 v1, v3 offset:24576
	v_mul_f32_e32 v3, v2, v45
	v_exp_f32_e32 v3, v3
	s_nop 0
	v_add_f32_e32 v3, 1.0, v3
	v_rcp_f32_e32 v3, v3
	s_nop 0
	v_mul_f32_e32 v3, v3, v45
	ds_write_b32 v1, v3 offset:26624
	v_mul_f32_e32 v3, v2, v46
	v_exp_f32_e32 v3, v3
	s_nop 0
	v_add_f32_e32 v3, 1.0, v3
	v_rcp_f32_e32 v3, v3
	s_nop 0
	v_mul_f32_e32 v3, v3, v46
	ds_write_b32 v1, v3 offset:28672
	v_mul_f32_e32 v3, v2, v47
	v_exp_f32_e32 v3, v3
	s_nop 0
	v_add_f32_e32 v3, 1.0, v3
	v_rcp_f32_e32 v3, v3
	s_nop 0
	v_mul_f32_e32 v3, v3, v47
	ds_write_b32 v1, v3 offset:30720
	v_mul_f32_e32 v3, v2, v48
	v_exp_f32_e32 v3, v3
	s_nop 0
	v_add_f32_e32 v3, 1.0, v3
	v_rcp_f32_e32 v3, v3
	s_nop 0
	v_mul_f32_e32 v3, v3, v48
	ds_write_b32 v1, v3 offset:32768
	v_mul_f32_e32 v3, v2, v49
	v_exp_f32_e32 v3, v3
	s_nop 0
	v_add_f32_e32 v3, 1.0, v3
	v_rcp_f32_e32 v3, v3
	s_nop 0
	v_mul_f32_e32 v3, v3, v49
	ds_write_b32 v1, v3 offset:34816
	v_mul_f32_e32 v3, v2, v50
	v_exp_f32_e32 v3, v3
	s_nop 0
	v_add_f32_e32 v3, 1.0, v3
	v_rcp_f32_e32 v3, v3
	s_nop 0
	v_mul_f32_e32 v3, v3, v50
	ds_write_b32 v1, v3 offset:36864
	v_mul_f32_e32 v3, v2, v51
	v_exp_f32_e32 v3, v3
	s_nop 0
	v_add_f32_e32 v3, 1.0, v3
	v_rcp_f32_e32 v3, v3
	s_nop 0
	v_mul_f32_e32 v3, v3, v51
	ds_write_b32 v1, v3 offset:38912
	s_waitcnt lgkmcnt(0)
	s_barrier
	s_lshr_b32 s8, s96, 7
	s_and_b32 s9, s96, 127
	s_mul_i32 s9, s9, 96
	v_and_b32_e32 v1, 63, v154
	v_cmp_lt_u32_e32 vcc, 23, v1
	s_nop 1
	v_cndmask_b32_e64 v2, 0, 1, vcc
	v_mul_u32_u24_e32 v3, 24, v2
	v_sub_u32_e32 v3, v1, v3
	v_lshrrev_b32_e32 v4, 6, v154
	v_lshl_add_u32 v10, v4, 8, v2
	v_lshlrev_b32_e32 v10, 2, v10
	v_mul_u32_u24_e32 v11, 0xc000, v2
	v_lshl_add_u32 v11, v3, 4, v11
	v_readfirstlane_b32 s12, v4
	s_lshl_b32 s12, s12, 8
	s_lshl_b32 s13, s8, 11
	s_add_u32 s12, s12, s13
	s_mul_hi_u32 s14, s12, 0xc000
	s_mul_i32 s12, s12, 0xc000
	s_lshl_b32 s13, s9, 2
	s_add_u32 s12, s12, s13
	s_addc_u32 s14, s14, 0
	s_add_u32 s10, s0, s12
	s_addc_u32 s11, s1, s14
	v_mov_b32_e32 v12, 0
	v_mov_b32_e32 v13, 0
	v_mov_b32_e32 v14, 0
	v_mov_b32_e32 v15, 0
	v_mov_b32_e32 v16, 0
	v_mov_b32_e32 v17, 0
	v_mov_b32_e32 v18, 0
	v_mov_b32_e32 v19, 0
	v_mov_b32_e32 v20, 0
	v_mov_b32_e32 v21, 0
	v_mov_b32_e32 v22, 0
	v_mov_b32_e32 v23, 0
	v_mov_b32_e32 v24, 0
	v_mov_b32_e32 v25, 0
	v_mov_b32_e32 v26, 0
	v_mov_b32_e32 v27, 0
	v_mov_b32_e32 v28, 0
	v_mov_b32_e32 v29, 0
	v_mov_b32_e32 v30, 0
	v_mov_b32_e32 v31, 0
	s_mov_b64 s[20:21], exec
	s_mov_b32 exec_lo, -1
	s_mov_b32 exec_hi, 0xffff
	global_load_dwordx4 v[32:35], v11, s[10:11]
	s_add_u32 s10, s10, 0x18000
	s_addc_u32 s11, s11, 0
	global_load_dwordx4 v[36:39], v11, s[10:11]
	s_add_u32 s10, s10, 0x18000
	s_addc_u32 s11, s11, 0
	global_load_dwordx4 v[40:43], v11, s[10:11]
	s_add_u32 s10, s10, 0x18000
	s_addc_u32 s11, s11, 0
	global_load_dwordx4 v[44:47], v11, s[10:11]
	s_add_u32 s10, s10, 0x18000
	s_addc_u32 s11, s11, 0
	global_load_dwordx4 v[48:51], v11, s[10:11]
	s_add_u32 s10, s10, 0x18000
	s_addc_u32 s11, s11, 0
	global_load_dwordx4 v[52:55], v11, s[10:11]
	s_add_u32 s10, s10, 0x18000
	s_addc_u32 s11, s11, 0
	global_load_dwordx4 v[56:59], v11, s[10:11]
	s_add_u32 s10, s10, 0x18000
	s_addc_u32 s11, s11, 0
	global_load_dwordx4 v[60:63], v11, s[10:11]
	s_add_u32 s10, s10, 0x18000
	s_addc_u32 s11, s11, 0
	global_load_dwordx4 v[64:67], v11, s[10:11]
	s_add_u32 s10, s10, 0x18000
	s_addc_u32 s11, s11, 0
	global_load_dwordx4 v[68:71], v11, s[10:11]
	s_add_u32 s10, s10, 0x18000
	s_addc_u32 s11, s11, 0
	global_load_dwordx4 v[72:75], v11, s[10:11]
	s_add_u32 s10, s10, 0x18000
	s_addc_u32 s11, s11, 0
	global_load_dwordx4 v[76:79], v11, s[10:11]
	s_add_u32 s10, s10, 0x18000
	s_addc_u32 s11, s11, 0
	global_load_dwordx4 v[80:83], v11, s[10:11]
	s_add_u32 s10, s10, 0x18000
	s_addc_u32 s11, s11, 0
	global_load_dwordx4 v[84:87], v11, s[10:11]
	s_add_u32 s10, s10, 0x18000
	s_addc_u32 s11, s11, 0
	global_load_dwordx4 v[88:91], v11, s[10:11]
	s_add_u32 s10, s10, 0x18000
	s_addc_u32 s11, s11, 0
	global_load_dwordx4 v[92:95], v11, s[10:11]
	s_add_u32 s10, s10, 0x18000
	s_addc_u32 s11, s11, 0
	ds_read_b32 v96, v10 offset:0
	ds_read_b32 v97, v10 offset:8192
	ds_read_b32 v98, v10 offset:16384
	ds_read_b32 v99, v10 offset:24576
	ds_read_b32 v100, v10 offset:32768
	s_waitcnt vmcnt(15) lgkmcnt(0)
	v_fmac_f32_e32 v12, v96, v32
	v_fmac_f32_e32 v13, v96, v33
	v_fmac_f32_e32 v14, v96, v34
	v_fmac_f32_e32 v15, v96, v35
	v_fmac_f32_e32 v16, v97, v32
	v_fmac_f32_e32 v17, v97, v33
	v_fmac_f32_e32 v18, v97, v34
	v_fmac_f32_e32 v19, v97, v35
	v_fmac_f32_e32 v20, v98, v32
	v_fmac_f32_e32 v21, v98, v33
	v_fmac_f32_e32 v22, v98, v34
	v_fmac_f32_e32 v23, v98, v35
	v_fmac_f32_e32 v24, v99, v32
	v_fmac_f32_e32 v25, v99, v33
	v_fmac_f32_e32 v26, v99, v34
	v_fmac_f32_e32 v27, v99, v35
	v_fmac_f32_e32 v28, v100, v32
	v_fmac_f32_e32 v29, v100, v33
	v_fmac_f32_e32 v30, v100, v34
	v_fmac_f32_e32 v31, v100, v35
	global_load_dwordx4 v[32:35], v11, s[10:11]
	s_add_u32 s10, s10, 0x18000
	s_addc_u32 s11, s11, 0
	ds_read_b32 v96, v10 offset:8
	ds_read_b32 v97, v10 offset:8200
	ds_read_b32 v98, v10 offset:16392
	ds_read_b32 v99, v10 offset:24584
	ds_read_b32 v100, v10 offset:32776
	s_waitcnt vmcnt(15) lgkmcnt(0)
	v_fmac_f32_e32 v12, v96, v36
	v_fmac_f32_e32 v13, v96, v37
	v_fmac_f32_e32 v14, v96, v38
	v_fmac_f32_e32 v15, v96, v39
	v_fmac_f32_e32 v16, v97, v36
	v_fmac_f32_e32 v17, v97, v37
	v_fmac_f32_e32 v18, v97, v38
	v_fmac_f32_e32 v19, v97, v39
	v_fmac_f32_e32 v20, v98, v36
	v_fmac_f32_e32 v21, v98, v37
	v_fmac_f32_e32 v22, v98, v38
	v_fmac_f32_e32 v23, v98, v39
	v_fmac_f32_e32 v24, v99, v36
	v_fmac_f32_e32 v25, v99, v37
	v_fmac_f32_e32 v26, v99, v38
	v_fmac_f32_e32 v27, v99, v39
	v_fmac_f32_e32 v28, v100, v36
	v_fmac_f32_e32 v29, v100, v37
	v_fmac_f32_e32 v30, v100, v38
	v_fmac_f32_e32 v31, v100, v39
	global_load_dwordx4 v[36:39], v11, s[10:11]
	s_add_u32 s10, s10, 0x18000
	s_addc_u32 s11, s11, 0
	ds_read_b32 v96, v10 offset:16
	ds_read_b32 v97, v10 offset:8208
	ds_read_b32 v98, v10 offset:16400
	ds_read_b32 v99, v10 offset:24592
	ds_read_b32 v100, v10 offset:32784
	s_waitcnt vmcnt(15) lgkmcnt(0)
	v_fmac_f32_e32 v12, v96, v40
	v_fmac_f32_e32 v13, v96, v41
	v_fmac_f32_e32 v14, v96, v42
	v_fmac_f32_e32 v15, v96, v43
	v_fmac_f32_e32 v16, v97, v40
	v_fmac_f32_e32 v17, v97, v41
	v_fmac_f32_e32 v18, v97, v42
	v_fmac_f32_e32 v19, v97, v43
	v_fmac_f32_e32 v20, v98, v40
	v_fmac_f32_e32 v21, v98, v41
	v_fmac_f32_e32 v22, v98, v42
	v_fmac_f32_e32 v23, v98, v43
	v_fmac_f32_e32 v24, v99, v40
	v_fmac_f32_e32 v25, v99, v41
	v_fmac_f32_e32 v26, v99, v42
	v_fmac_f32_e32 v27, v99, v43
	v_fmac_f32_e32 v28, v100, v40
	v_fmac_f32_e32 v29, v100, v41
	v_fmac_f32_e32 v30, v100, v42
	v_fmac_f32_e32 v31, v100, v43
	global_load_dwordx4 v[40:43], v11, s[10:11]
	s_add_u32 s10, s10, 0x18000
	s_addc_u32 s11, s11, 0
	ds_read_b32 v96, v10 offset:24
	ds_read_b32 v97, v10 offset:8216
	ds_read_b32 v98, v10 offset:16408
	ds_read_b32 v99, v10 offset:24600
	ds_read_b32 v100, v10 offset:32792
	s_waitcnt vmcnt(15) lgkmcnt(0)
	v_fmac_f32_e32 v12, v96, v44
	v_fmac_f32_e32 v13, v96, v45
	v_fmac_f32_e32 v14, v96, v46
	v_fmac_f32_e32 v15, v96, v47
	v_fmac_f32_e32 v16, v97, v44
	v_fmac_f32_e32 v17, v97, v45
	v_fmac_f32_e32 v18, v97, v46
	v_fmac_f32_e32 v19, v97, v47
	v_fmac_f32_e32 v20, v98, v44
	v_fmac_f32_e32 v21, v98, v45
	v_fmac_f32_e32 v22, v98, v46
	v_fmac_f32_e32 v23, v98, v47
	v_fmac_f32_e32 v24, v99, v44
	v_fmac_f32_e32 v25, v99, v45
	v_fmac_f32_e32 v26, v99, v46
	v_fmac_f32_e32 v27, v99, v47
	v_fmac_f32_e32 v28, v100, v44
	v_fmac_f32_e32 v29, v100, v45
	v_fmac_f32_e32 v30, v100, v46
	v_fmac_f32_e32 v31, v100, v47
	global_load_dwordx4 v[44:47], v11, s[10:11]
	s_add_u32 s10, s10, 0x18000
	s_addc_u32 s11, s11, 0
	ds_read_b32 v96, v10 offset:32
	ds_read_b32 v97, v10 offset:8224
	ds_read_b32 v98, v10 offset:16416
	ds_read_b32 v99, v10 offset:24608
	ds_read_b32 v100, v10 offset:32800
	s_waitcnt vmcnt(15) lgkmcnt(0)
	v_fmac_f32_e32 v12, v96, v48
	v_fmac_f32_e32 v13, v96, v49
	v_fmac_f32_e32 v14, v96, v50
	v_fmac_f32_e32 v15, v96, v51
	v_fmac_f32_e32 v16, v97, v48
	v_fmac_f32_e32 v17, v97, v49
	v_fmac_f32_e32 v18, v97, v50
	v_fmac_f32_e32 v19, v97, v51
	v_fmac_f32_e32 v20, v98, v48
	v_fmac_f32_e32 v21, v98, v49
	v_fmac_f32_e32 v22, v98, v50
	v_fmac_f32_e32 v23, v98, v51
	v_fmac_f32_e32 v24, v99, v48
	v_fmac_f32_e32 v25, v99, v49
	v_fmac_f32_e32 v26, v99, v50
	v_fmac_f32_e32 v27, v99, v51
	v_fmac_f32_e32 v28, v100, v48
	v_fmac_f32_e32 v29, v100, v49
	v_fmac_f32_e32 v30, v100, v50
	v_fmac_f32_e32 v31, v100, v51
	global_load_dwordx4 v[48:51], v11, s[10:11]
	s_add_u32 s10, s10, 0x18000
	s_addc_u32 s11, s11, 0
	ds_read_b32 v96, v10 offset:40
	ds_read_b32 v97, v10 offset:8232
	ds_read_b32 v98, v10 offset:16424
	ds_read_b32 v99, v10 offset:24616
	ds_read_b32 v100, v10 offset:32808
	s_waitcnt vmcnt(15) lgkmcnt(0)
	v_fmac_f32_e32 v12, v96, v52
	v_fmac_f32_e32 v13, v96, v53
	v_fmac_f32_e32 v14, v96, v54
	v_fmac_f32_e32 v15, v96, v55
	v_fmac_f32_e32 v16, v97, v52
	v_fmac_f32_e32 v17, v97, v53
	v_fmac_f32_e32 v18, v97, v54
	v_fmac_f32_e32 v19, v97, v55
	v_fmac_f32_e32 v20, v98, v52
	v_fmac_f32_e32 v21, v98, v53
	v_fmac_f32_e32 v22, v98, v54
	v_fmac_f32_e32 v23, v98, v55
	v_fmac_f32_e32 v24, v99, v52
	v_fmac_f32_e32 v25, v99, v53
	v_fmac_f32_e32 v26, v99, v54
	v_fmac_f32_e32 v27, v99, v55
	v_fmac_f32_e32 v28, v100, v52
	v_fmac_f32_e32 v29, v100, v53
	v_fmac_f32_e32 v30, v100, v54
	v_fmac_f32_e32 v31, v100, v55
	global_load_dwordx4 v[52:55], v11, s[10:11]
	s_add_u32 s10, s10, 0x18000
	s_addc_u32 s11, s11, 0
	ds_read_b32 v96, v10 offset:48
	ds_read_b32 v97, v10 offset:8240
	ds_read_b32 v98, v10 offset:16432
	ds_read_b32 v99, v10 offset:24624
	ds_read_b32 v100, v10 offset:32816
	s_waitcnt vmcnt(15) lgkmcnt(0)
	v_fmac_f32_e32 v12, v96, v56
	v_fmac_f32_e32 v13, v96, v57
	v_fmac_f32_e32 v14, v96, v58
	v_fmac_f32_e32 v15, v96, v59
	v_fmac_f32_e32 v16, v97, v56
	v_fmac_f32_e32 v17, v97, v57
	v_fmac_f32_e32 v18, v97, v58
	v_fmac_f32_e32 v19, v97, v59
	v_fmac_f32_e32 v20, v98, v56
	v_fmac_f32_e32 v21, v98, v57
	v_fmac_f32_e32 v22, v98, v58
	v_fmac_f32_e32 v23, v98, v59
	v_fmac_f32_e32 v24, v99, v56
	v_fmac_f32_e32 v25, v99, v57
	v_fmac_f32_e32 v26, v99, v58
	v_fmac_f32_e32 v27, v99, v59
	v_fmac_f32_e32 v28, v100, v56
	v_fmac_f32_e32 v29, v100, v57
	v_fmac_f32_e32 v30, v100, v58
	v_fmac_f32_e32 v31, v100, v59
	global_load_dwordx4 v[56:59], v11, s[10:11]
	s_add_u32 s10, s10, 0x18000
	s_addc_u32 s11, s11, 0
	ds_read_b32 v96, v10 offset:56
	ds_read_b32 v97, v10 offset:8248
	ds_read_b32 v98, v10 offset:16440
	ds_read_b32 v99, v10 offset:24632
	ds_read_b32 v100, v10 offset:32824
	s_waitcnt vmcnt(15) lgkmcnt(0)
	v_fmac_f32_e32 v12, v96, v60
	v_fmac_f32_e32 v13, v96, v61
	v_fmac_f32_e32 v14, v96, v62
	v_fmac_f32_e32 v15, v96, v63
	v_fmac_f32_e32 v16, v97, v60
	v_fmac_f32_e32 v17, v97, v61
	v_fmac_f32_e32 v18, v97, v62
	v_fmac_f32_e32 v19, v97, v63
	v_fmac_f32_e32 v20, v98, v60
	v_fmac_f32_e32 v21, v98, v61
	v_fmac_f32_e32 v22, v98, v62
	v_fmac_f32_e32 v23, v98, v63
	v_fmac_f32_e32 v24, v99, v60
	v_fmac_f32_e32 v25, v99, v61
	v_fmac_f32_e32 v26, v99, v62
	v_fmac_f32_e32 v27, v99, v63
	v_fmac_f32_e32 v28, v100, v60
	v_fmac_f32_e32 v29, v100, v61
	v_fmac_f32_e32 v30, v100, v62
	v_fmac_f32_e32 v31, v100, v63
	global_load_dwordx4 v[60:63], v11, s[10:11]
	s_add_u32 s10, s10, 0x18000
	s_addc_u32 s11, s11, 0
	ds_read_b32 v96, v10 offset:64
	ds_read_b32 v97, v10 offset:8256
	ds_read_b32 v98, v10 offset:16448
	ds_read_b32 v99, v10 offset:24640
	ds_read_b32 v100, v10 offset:32832
	s_waitcnt vmcnt(15) lgkmcnt(0)
	v_fmac_f32_e32 v12, v96, v64
	v_fmac_f32_e32 v13, v96, v65
	v_fmac_f32_e32 v14, v96, v66
	v_fmac_f32_e32 v15, v96, v67
	v_fmac_f32_e32 v16, v97, v64
	v_fmac_f32_e32 v17, v97, v65
	v_fmac_f32_e32 v18, v97, v66
	v_fmac_f32_e32 v19, v97, v67
	v_fmac_f32_e32 v20, v98, v64
	v_fmac_f32_e32 v21, v98, v65
	v_fmac_f32_e32 v22, v98, v66
	v_fmac_f32_e32 v23, v98, v67
	v_fmac_f32_e32 v24, v99, v64
	v_fmac_f32_e32 v25, v99, v65
	v_fmac_f32_e32 v26, v99, v66
	v_fmac_f32_e32 v27, v99, v67
	v_fmac_f32_e32 v28, v100, v64
	v_fmac_f32_e32 v29, v100, v65
	v_fmac_f32_e32 v30, v100, v66
	v_fmac_f32_e32 v31, v100, v67
	global_load_dwordx4 v[64:67], v11, s[10:11]
	s_add_u32 s10, s10, 0x18000
	s_addc_u32 s11, s11, 0
	ds_read_b32 v96, v10 offset:72
	ds_read_b32 v97, v10 offset:8264
	ds_read_b32 v98, v10 offset:16456
	ds_read_b32 v99, v10 offset:24648
	ds_read_b32 v100, v10 offset:32840
	s_waitcnt vmcnt(15) lgkmcnt(0)
	v_fmac_f32_e32 v12, v96, v68
	v_fmac_f32_e32 v13, v96, v69
	v_fmac_f32_e32 v14, v96, v70
	v_fmac_f32_e32 v15, v96, v71
	v_fmac_f32_e32 v16, v97, v68
	v_fmac_f32_e32 v17, v97, v69
	v_fmac_f32_e32 v18, v97, v70
	v_fmac_f32_e32 v19, v97, v71
	v_fmac_f32_e32 v20, v98, v68
	v_fmac_f32_e32 v21, v98, v69
	v_fmac_f32_e32 v22, v98, v70
	v_fmac_f32_e32 v23, v98, v71
	v_fmac_f32_e32 v24, v99, v68
	v_fmac_f32_e32 v25, v99, v69
	v_fmac_f32_e32 v26, v99, v70
	v_fmac_f32_e32 v27, v99, v71
	v_fmac_f32_e32 v28, v100, v68
	v_fmac_f32_e32 v29, v100, v69
	v_fmac_f32_e32 v30, v100, v70
	v_fmac_f32_e32 v31, v100, v71
	global_load_dwordx4 v[68:71], v11, s[10:11]
	s_add_u32 s10, s10, 0x18000
	s_addc_u32 s11, s11, 0
	ds_read_b32 v96, v10 offset:80
	ds_read_b32 v97, v10 offset:8272
	ds_read_b32 v98, v10 offset:16464
	ds_read_b32 v99, v10 offset:24656
	ds_read_b32 v100, v10 offset:32848
	s_waitcnt vmcnt(15) lgkmcnt(0)
	v_fmac_f32_e32 v12, v96, v72
	v_fmac_f32_e32 v13, v96, v73
	v_fmac_f32_e32 v14, v96, v74
	v_fmac_f32_e32 v15, v96, v75
	v_fmac_f32_e32 v16, v97, v72
	v_fmac_f32_e32 v17, v97, v73
	v_fmac_f32_e32 v18, v97, v74
	v_fmac_f32_e32 v19, v97, v75
	v_fmac_f32_e32 v20, v98, v72
	v_fmac_f32_e32 v21, v98, v73
	v_fmac_f32_e32 v22, v98, v74
	v_fmac_f32_e32 v23, v98, v75
	v_fmac_f32_e32 v24, v99, v72
	v_fmac_f32_e32 v25, v99, v73
	v_fmac_f32_e32 v26, v99, v74
	v_fmac_f32_e32 v27, v99, v75
	v_fmac_f32_e32 v28, v100, v72
	v_fmac_f32_e32 v29, v100, v73
	v_fmac_f32_e32 v30, v100, v74
	v_fmac_f32_e32 v31, v100, v75
	global_load_dwordx4 v[72:75], v11, s[10:11]
	s_add_u32 s10, s10, 0x18000
	s_addc_u32 s11, s11, 0
	ds_read_b32 v96, v10 offset:88
	ds_read_b32 v97, v10 offset:8280
	ds_read_b32 v98, v10 offset:16472
	ds_read_b32 v99, v10 offset:24664
	ds_read_b32 v100, v10 offset:32856
	s_waitcnt vmcnt(15) lgkmcnt(0)
	v_fmac_f32_e32 v12, v96, v76
	v_fmac_f32_e32 v13, v96, v77
	v_fmac_f32_e32 v14, v96, v78
	v_fmac_f32_e32 v15, v96, v79
	v_fmac_f32_e32 v16, v97, v76
	v_fmac_f32_e32 v17, v97, v77
	v_fmac_f32_e32 v18, v97, v78
	v_fmac_f32_e32 v19, v97, v79
	v_fmac_f32_e32 v20, v98, v76
	v_fmac_f32_e32 v21, v98, v77
	v_fmac_f32_e32 v22, v98, v78
	v_fmac_f32_e32 v23, v98, v79
	v_fmac_f32_e32 v24, v99, v76
	v_fmac_f32_e32 v25, v99, v77
	v_fmac_f32_e32 v26, v99, v78
	v_fmac_f32_e32 v27, v99, v79
	v_fmac_f32_e32 v28, v100, v76
	v_fmac_f32_e32 v29, v100, v77
	v_fmac_f32_e32 v30, v100, v78
	v_fmac_f32_e32 v31, v100, v79
	global_load_dwordx4 v[76:79], v11, s[10:11]
	s_add_u32 s10, s10, 0x18000
	s_addc_u32 s11, s11, 0
	ds_read_b32 v96, v10 offset:96
	ds_read_b32 v97, v10 offset:8288
	ds_read_b32 v98, v10 offset:16480
	ds_read_b32 v99, v10 offset:24672
	ds_read_b32 v100, v10 offset:32864
	s_waitcnt vmcnt(15) lgkmcnt(0)
	v_fmac_f32_e32 v12, v96, v80
	v_fmac_f32_e32 v13, v96, v81
	v_fmac_f32_e32 v14, v96, v82
	v_fmac_f32_e32 v15, v96, v83
	v_fmac_f32_e32 v16, v97, v80
	v_fmac_f32_e32 v17, v97, v81
	v_fmac_f32_e32 v18, v97, v82
	v_fmac_f32_e32 v19, v97, v83
	v_fmac_f32_e32 v20, v98, v80
	v_fmac_f32_e32 v21, v98, v81
	v_fmac_f32_e32 v22, v98, v82
	v_fmac_f32_e32 v23, v98, v83
	v_fmac_f32_e32 v24, v99, v80
	v_fmac_f32_e32 v25, v99, v81
	v_fmac_f32_e32 v26, v99, v82
	v_fmac_f32_e32 v27, v99, v83
	v_fmac_f32_e32 v28, v100, v80
	v_fmac_f32_e32 v29, v100, v81
	v_fmac_f32_e32 v30, v100, v82
	v_fmac_f32_e32 v31, v100, v83
	global_load_dwordx4 v[80:83], v11, s[10:11]
	s_add_u32 s10, s10, 0x18000
	s_addc_u32 s11, s11, 0
	ds_read_b32 v96, v10 offset:104
	ds_read_b32 v97, v10 offset:8296
	ds_read_b32 v98, v10 offset:16488
	ds_read_b32 v99, v10 offset:24680
	ds_read_b32 v100, v10 offset:32872
	s_waitcnt vmcnt(15) lgkmcnt(0)
	v_fmac_f32_e32 v12, v96, v84
	v_fmac_f32_e32 v13, v96, v85
	v_fmac_f32_e32 v14, v96, v86
	v_fmac_f32_e32 v15, v96, v87
	v_fmac_f32_e32 v16, v97, v84
	v_fmac_f32_e32 v17, v97, v85
	v_fmac_f32_e32 v18, v97, v86
	v_fmac_f32_e32 v19, v97, v87
	v_fmac_f32_e32 v20, v98, v84
	v_fmac_f32_e32 v21, v98, v85
	v_fmac_f32_e32 v22, v98, v86
	v_fmac_f32_e32 v23, v98, v87
	v_fmac_f32_e32 v24, v99, v84
	v_fmac_f32_e32 v25, v99, v85
	v_fmac_f32_e32 v26, v99, v86
	v_fmac_f32_e32 v27, v99, v87
	v_fmac_f32_e32 v28, v100, v84
	v_fmac_f32_e32 v29, v100, v85
	v_fmac_f32_e32 v30, v100, v86
	v_fmac_f32_e32 v31, v100, v87
	global_load_dwordx4 v[84:87], v11, s[10:11]
	s_add_u32 s10, s10, 0x18000
	s_addc_u32 s11, s11, 0
	ds_read_b32 v96, v10 offset:112
	ds_read_b32 v97, v10 offset:8304
	ds_read_b32 v98, v10 offset:16496
	ds_read_b32 v99, v10 offset:24688
	ds_read_b32 v100, v10 offset:32880
	s_waitcnt vmcnt(15) lgkmcnt(0)
	v_fmac_f32_e32 v12, v96, v88
	v_fmac_f32_e32 v13, v96, v89
	v_fmac_f32_e32 v14, v96, v90
	v_fmac_f32_e32 v15, v96, v91
	v_fmac_f32_e32 v16, v97, v88
	v_fmac_f32_e32 v17, v97, v89
	v_fmac_f32_e32 v18, v97, v90
	v_fmac_f32_e32 v19, v97, v91
	v_fmac_f32_e32 v20, v98, v88
	v_fmac_f32_e32 v21, v98, v89
	v_fmac_f32_e32 v22, v98, v90
	v_fmac_f32_e32 v23, v98, v91
	v_fmac_f32_e32 v24, v99, v88
	v_fmac_f32_e32 v25, v99, v89
	v_fmac_f32_e32 v26, v99, v90
	v_fmac_f32_e32 v27, v99, v91
	v_fmac_f32_e32 v28, v100, v88
	v_fmac_f32_e32 v29, v100, v89
	v_fmac_f32_e32 v30, v100, v90
	v_fmac_f32_e32 v31, v100, v91
	global_load_dwordx4 v[88:91], v11, s[10:11]
	s_add_u32 s10, s10, 0x18000
	s_addc_u32 s11, s11, 0
	ds_read_b32 v96, v10 offset:120
	ds_read_b32 v97, v10 offset:8312
	ds_read_b32 v98, v10 offset:16504
	ds_read_b32 v99, v10 offset:24696
	ds_read_b32 v100, v10 offset:32888
	s_waitcnt vmcnt(15) lgkmcnt(0)
	v_fmac_f32_e32 v12, v96, v92
	v_fmac_f32_e32 v13, v96, v93
	v_fmac_f32_e32 v14, v96, v94
	v_fmac_f32_e32 v15, v96, v95
	v_fmac_f32_e32 v16, v97, v92
	v_fmac_f32_e32 v17, v97, v93
	v_fmac_f32_e32 v18, v97, v94
	v_fmac_f32_e32 v19, v97, v95
	v_fmac_f32_e32 v20, v98, v92
	v_fmac_f32_e32 v21, v98, v93
	v_fmac_f32_e32 v22, v98, v94
	v_fmac_f32_e32 v23, v98, v95
	v_fmac_f32_e32 v24, v99, v92
	v_fmac_f32_e32 v25, v99, v93
	v_fmac_f32_e32 v26, v99, v94
	v_fmac_f32_e32 v27, v99, v95
	v_fmac_f32_e32 v28, v100, v92
	v_fmac_f32_e32 v29, v100, v93
	v_fmac_f32_e32 v30, v100, v94
	v_fmac_f32_e32 v31, v100, v95
	global_load_dwordx4 v[92:95], v11, s[10:11]
	s_add_u32 s10, s10, 0x18000
	s_addc_u32 s11, s11, 0
	ds_read_b32 v96, v10 offset:128
	ds_read_b32 v97, v10 offset:8320
	ds_read_b32 v98, v10 offset:16512
	ds_read_b32 v99, v10 offset:24704
	ds_read_b32 v100, v10 offset:32896
	s_waitcnt vmcnt(15) lgkmcnt(0)
	v_fmac_f32_e32 v12, v96, v32
	v_fmac_f32_e32 v13, v96, v33
	v_fmac_f32_e32 v14, v96, v34
	v_fmac_f32_e32 v15, v96, v35
	v_fmac_f32_e32 v16, v97, v32
	v_fmac_f32_e32 v17, v97, v33
	v_fmac_f32_e32 v18, v97, v34
	v_fmac_f32_e32 v19, v97, v35
	v_fmac_f32_e32 v20, v98, v32
	v_fmac_f32_e32 v21, v98, v33
	v_fmac_f32_e32 v22, v98, v34
	v_fmac_f32_e32 v23, v98, v35
	v_fmac_f32_e32 v24, v99, v32
	v_fmac_f32_e32 v25, v99, v33
	v_fmac_f32_e32 v26, v99, v34
	v_fmac_f32_e32 v27, v99, v35
	v_fmac_f32_e32 v28, v100, v32
	v_fmac_f32_e32 v29, v100, v33
	v_fmac_f32_e32 v30, v100, v34
	v_fmac_f32_e32 v31, v100, v35
	global_load_dwordx4 v[32:35], v11, s[10:11]
	s_add_u32 s10, s10, 0x18000
	s_addc_u32 s11, s11, 0
	ds_read_b32 v96, v10 offset:136
	ds_read_b32 v97, v10 offset:8328
	ds_read_b32 v98, v10 offset:16520
	ds_read_b32 v99, v10 offset:24712
	ds_read_b32 v100, v10 offset:32904
	s_waitcnt vmcnt(15) lgkmcnt(0)
	v_fmac_f32_e32 v12, v96, v36
	v_fmac_f32_e32 v13, v96, v37
	v_fmac_f32_e32 v14, v96, v38
	v_fmac_f32_e32 v15, v96, v39
	v_fmac_f32_e32 v16, v97, v36
	v_fmac_f32_e32 v17, v97, v37
	v_fmac_f32_e32 v18, v97, v38
	v_fmac_f32_e32 v19, v97, v39
	v_fmac_f32_e32 v20, v98, v36
	v_fmac_f32_e32 v21, v98, v37
	v_fmac_f32_e32 v22, v98, v38
	v_fmac_f32_e32 v23, v98, v39
	v_fmac_f32_e32 v24, v99, v36
	v_fmac_f32_e32 v25, v99, v37
	v_fmac_f32_e32 v26, v99, v38
	v_fmac_f32_e32 v27, v99, v39
	v_fmac_f32_e32 v28, v100, v36
	v_fmac_f32_e32 v29, v100, v37
	v_fmac_f32_e32 v30, v100, v38
	v_fmac_f32_e32 v31, v100, v39
	global_load_dwordx4 v[36:39], v11, s[10:11]
	s_add_u32 s10, s10, 0x18000
	s_addc_u32 s11, s11, 0
	ds_read_b32 v96, v10 offset:144
	ds_read_b32 v97, v10 offset:8336
	ds_read_b32 v98, v10 offset:16528
	ds_read_b32 v99, v10 offset:24720
	ds_read_b32 v100, v10 offset:32912
	s_waitcnt vmcnt(15) lgkmcnt(0)
	v_fmac_f32_e32 v12, v96, v40
	v_fmac_f32_e32 v13, v96, v41
	v_fmac_f32_e32 v14, v96, v42
	v_fmac_f32_e32 v15, v96, v43
	v_fmac_f32_e32 v16, v97, v40
	v_fmac_f32_e32 v17, v97, v41
	v_fmac_f32_e32 v18, v97, v42
	v_fmac_f32_e32 v19, v97, v43
	v_fmac_f32_e32 v20, v98, v40
	v_fmac_f32_e32 v21, v98, v41
	v_fmac_f32_e32 v22, v98, v42
	v_fmac_f32_e32 v23, v98, v43
	v_fmac_f32_e32 v24, v99, v40
	v_fmac_f32_e32 v25, v99, v41
	v_fmac_f32_e32 v26, v99, v42
	v_fmac_f32_e32 v27, v99, v43
	v_fmac_f32_e32 v28, v100, v40
	v_fmac_f32_e32 v29, v100, v41
	v_fmac_f32_e32 v30, v100, v42
	v_fmac_f32_e32 v31, v100, v43
	global_load_dwordx4 v[40:43], v11, s[10:11]
	s_add_u32 s10, s10, 0x18000
	s_addc_u32 s11, s11, 0
	ds_read_b32 v96, v10 offset:152
	ds_read_b32 v97, v10 offset:8344
	ds_read_b32 v98, v10 offset:16536
	ds_read_b32 v99, v10 offset:24728
	ds_read_b32 v100, v10 offset:32920
	s_waitcnt vmcnt(15) lgkmcnt(0)
	v_fmac_f32_e32 v12, v96, v44
	v_fmac_f32_e32 v13, v96, v45
	v_fmac_f32_e32 v14, v96, v46
	v_fmac_f32_e32 v15, v96, v47
	v_fmac_f32_e32 v16, v97, v44
	v_fmac_f32_e32 v17, v97, v45
	v_fmac_f32_e32 v18, v97, v46
	v_fmac_f32_e32 v19, v97, v47
	v_fmac_f32_e32 v20, v98, v44
	v_fmac_f32_e32 v21, v98, v45
	v_fmac_f32_e32 v22, v98, v46
	v_fmac_f32_e32 v23, v98, v47
	v_fmac_f32_e32 v24, v99, v44
	v_fmac_f32_e32 v25, v99, v45
	v_fmac_f32_e32 v26, v99, v46
	v_fmac_f32_e32 v27, v99, v47
	v_fmac_f32_e32 v28, v100, v44
	v_fmac_f32_e32 v29, v100, v45
	v_fmac_f32_e32 v30, v100, v46
	v_fmac_f32_e32 v31, v100, v47
	global_load_dwordx4 v[44:47], v11, s[10:11]
	s_add_u32 s10, s10, 0x18000
	s_addc_u32 s11, s11, 0
	ds_read_b32 v96, v10 offset:160
	ds_read_b32 v97, v10 offset:8352
	ds_read_b32 v98, v10 offset:16544
	ds_read_b32 v99, v10 offset:24736
	ds_read_b32 v100, v10 offset:32928
	s_waitcnt vmcnt(15) lgkmcnt(0)
	v_fmac_f32_e32 v12, v96, v48
	v_fmac_f32_e32 v13, v96, v49
	v_fmac_f32_e32 v14, v96, v50
	v_fmac_f32_e32 v15, v96, v51
	v_fmac_f32_e32 v16, v97, v48
	v_fmac_f32_e32 v17, v97, v49
	v_fmac_f32_e32 v18, v97, v50
	v_fmac_f32_e32 v19, v97, v51
	v_fmac_f32_e32 v20, v98, v48
	v_fmac_f32_e32 v21, v98, v49
	v_fmac_f32_e32 v22, v98, v50
	v_fmac_f32_e32 v23, v98, v51
	v_fmac_f32_e32 v24, v99, v48
	v_fmac_f32_e32 v25, v99, v49
	v_fmac_f32_e32 v26, v99, v50
	v_fmac_f32_e32 v27, v99, v51
	v_fmac_f32_e32 v28, v100, v48
	v_fmac_f32_e32 v29, v100, v49
	v_fmac_f32_e32 v30, v100, v50
	v_fmac_f32_e32 v31, v100, v51
	global_load_dwordx4 v[48:51], v11, s[10:11]
	s_add_u32 s10, s10, 0x18000
	s_addc_u32 s11, s11, 0
	ds_read_b32 v96, v10 offset:168
	ds_read_b32 v97, v10 offset:8360
	ds_read_b32 v98, v10 offset:16552
	ds_read_b32 v99, v10 offset:24744
	ds_read_b32 v100, v10 offset:32936
	s_waitcnt vmcnt(15) lgkmcnt(0)
	v_fmac_f32_e32 v12, v96, v52
	v_fmac_f32_e32 v13, v96, v53
	v_fmac_f32_e32 v14, v96, v54
	v_fmac_f32_e32 v15, v96, v55
	v_fmac_f32_e32 v16, v97, v52
	v_fmac_f32_e32 v17, v97, v53
	v_fmac_f32_e32 v18, v97, v54
	v_fmac_f32_e32 v19, v97, v55
	v_fmac_f32_e32 v20, v98, v52
	v_fmac_f32_e32 v21, v98, v53
	v_fmac_f32_e32 v22, v98, v54
	v_fmac_f32_e32 v23, v98, v55
	v_fmac_f32_e32 v24, v99, v52
	v_fmac_f32_e32 v25, v99, v53
	v_fmac_f32_e32 v26, v99, v54
	v_fmac_f32_e32 v27, v99, v55
	v_fmac_f32_e32 v28, v100, v52
	v_fmac_f32_e32 v29, v100, v53
	v_fmac_f32_e32 v30, v100, v54
	v_fmac_f32_e32 v31, v100, v55
	global_load_dwordx4 v[52:55], v11, s[10:11]
	s_add_u32 s10, s10, 0x18000
	s_addc_u32 s11, s11, 0
	ds_read_b32 v96, v10 offset:176
	ds_read_b32 v97, v10 offset:8368
	ds_read_b32 v98, v10 offset:16560
	ds_read_b32 v99, v10 offset:24752
	ds_read_b32 v100, v10 offset:32944
	s_waitcnt vmcnt(15) lgkmcnt(0)
	v_fmac_f32_e32 v12, v96, v56
	v_fmac_f32_e32 v13, v96, v57
	v_fmac_f32_e32 v14, v96, v58
	v_fmac_f32_e32 v15, v96, v59
	v_fmac_f32_e32 v16, v97, v56
	v_fmac_f32_e32 v17, v97, v57
	v_fmac_f32_e32 v18, v97, v58
	v_fmac_f32_e32 v19, v97, v59
	v_fmac_f32_e32 v20, v98, v56
	v_fmac_f32_e32 v21, v98, v57
	v_fmac_f32_e32 v22, v98, v58
	v_fmac_f32_e32 v23, v98, v59
	v_fmac_f32_e32 v24, v99, v56
	v_fmac_f32_e32 v25, v99, v57
	v_fmac_f32_e32 v26, v99, v58
	v_fmac_f32_e32 v27, v99, v59
	v_fmac_f32_e32 v28, v100, v56
	v_fmac_f32_e32 v29, v100, v57
	v_fmac_f32_e32 v30, v100, v58
	v_fmac_f32_e32 v31, v100, v59
	global_load_dwordx4 v[56:59], v11, s[10:11]
	s_add_u32 s10, s10, 0x18000
	s_addc_u32 s11, s11, 0
	ds_read_b32 v96, v10 offset:184
	ds_read_b32 v97, v10 offset:8376
	ds_read_b32 v98, v10 offset:16568
	ds_read_b32 v99, v10 offset:24760
	ds_read_b32 v100, v10 offset:32952
	s_waitcnt vmcnt(15) lgkmcnt(0)
	v_fmac_f32_e32 v12, v96, v60
	v_fmac_f32_e32 v13, v96, v61
	v_fmac_f32_e32 v14, v96, v62
	v_fmac_f32_e32 v15, v96, v63
	v_fmac_f32_e32 v16, v97, v60
	v_fmac_f32_e32 v17, v97, v61
	v_fmac_f32_e32 v18, v97, v62
	v_fmac_f32_e32 v19, v97, v63
	v_fmac_f32_e32 v20, v98, v60
	v_fmac_f32_e32 v21, v98, v61
	v_fmac_f32_e32 v22, v98, v62
	v_fmac_f32_e32 v23, v98, v63
	v_fmac_f32_e32 v24, v99, v60
	v_fmac_f32_e32 v25, v99, v61
	v_fmac_f32_e32 v26, v99, v62
	v_fmac_f32_e32 v27, v99, v63
	v_fmac_f32_e32 v28, v100, v60
	v_fmac_f32_e32 v29, v100, v61
	v_fmac_f32_e32 v30, v100, v62
	v_fmac_f32_e32 v31, v100, v63
	global_load_dwordx4 v[60:63], v11, s[10:11]
	s_add_u32 s10, s10, 0x18000
	s_addc_u32 s11, s11, 0
	ds_read_b32 v96, v10 offset:192
	ds_read_b32 v97, v10 offset:8384
	ds_read_b32 v98, v10 offset:16576
	ds_read_b32 v99, v10 offset:24768
	ds_read_b32 v100, v10 offset:32960
	s_waitcnt vmcnt(15) lgkmcnt(0)
	v_fmac_f32_e32 v12, v96, v64
	v_fmac_f32_e32 v13, v96, v65
	v_fmac_f32_e32 v14, v96, v66
	v_fmac_f32_e32 v15, v96, v67
	v_fmac_f32_e32 v16, v97, v64
	v_fmac_f32_e32 v17, v97, v65
	v_fmac_f32_e32 v18, v97, v66
	v_fmac_f32_e32 v19, v97, v67
	v_fmac_f32_e32 v20, v98, v64
	v_fmac_f32_e32 v21, v98, v65
	v_fmac_f32_e32 v22, v98, v66
	v_fmac_f32_e32 v23, v98, v67
	v_fmac_f32_e32 v24, v99, v64
	v_fmac_f32_e32 v25, v99, v65
	v_fmac_f32_e32 v26, v99, v66
	v_fmac_f32_e32 v27, v99, v67
	v_fmac_f32_e32 v28, v100, v64
	v_fmac_f32_e32 v29, v100, v65
	v_fmac_f32_e32 v30, v100, v66
	v_fmac_f32_e32 v31, v100, v67
	global_load_dwordx4 v[64:67], v11, s[10:11]
	s_add_u32 s10, s10, 0x18000
	s_addc_u32 s11, s11, 0
	ds_read_b32 v96, v10 offset:200
	ds_read_b32 v97, v10 offset:8392
	ds_read_b32 v98, v10 offset:16584
	ds_read_b32 v99, v10 offset:24776
	ds_read_b32 v100, v10 offset:32968
	s_waitcnt vmcnt(15) lgkmcnt(0)
	v_fmac_f32_e32 v12, v96, v68
	v_fmac_f32_e32 v13, v96, v69
	v_fmac_f32_e32 v14, v96, v70
	v_fmac_f32_e32 v15, v96, v71
	v_fmac_f32_e32 v16, v97, v68
	v_fmac_f32_e32 v17, v97, v69
	v_fmac_f32_e32 v18, v97, v70
	v_fmac_f32_e32 v19, v97, v71
	v_fmac_f32_e32 v20, v98, v68
	v_fmac_f32_e32 v21, v98, v69
	v_fmac_f32_e32 v22, v98, v70
	v_fmac_f32_e32 v23, v98, v71
	v_fmac_f32_e32 v24, v99, v68
	v_fmac_f32_e32 v25, v99, v69
	v_fmac_f32_e32 v26, v99, v70
	v_fmac_f32_e32 v27, v99, v71
	v_fmac_f32_e32 v28, v100, v68
	v_fmac_f32_e32 v29, v100, v69
	v_fmac_f32_e32 v30, v100, v70
	v_fmac_f32_e32 v31, v100, v71
	global_load_dwordx4 v[68:71], v11, s[10:11]
	s_add_u32 s10, s10, 0x18000
	s_addc_u32 s11, s11, 0
	ds_read_b32 v96, v10 offset:208
	ds_read_b32 v97, v10 offset:8400
	ds_read_b32 v98, v10 offset:16592
	ds_read_b32 v99, v10 offset:24784
	ds_read_b32 v100, v10 offset:32976
	s_waitcnt vmcnt(15) lgkmcnt(0)
	v_fmac_f32_e32 v12, v96, v72
	v_fmac_f32_e32 v13, v96, v73
	v_fmac_f32_e32 v14, v96, v74
	v_fmac_f32_e32 v15, v96, v75
	v_fmac_f32_e32 v16, v97, v72
	v_fmac_f32_e32 v17, v97, v73
	v_fmac_f32_e32 v18, v97, v74
	v_fmac_f32_e32 v19, v97, v75
	v_fmac_f32_e32 v20, v98, v72
	v_fmac_f32_e32 v21, v98, v73
	v_fmac_f32_e32 v22, v98, v74
	v_fmac_f32_e32 v23, v98, v75
	v_fmac_f32_e32 v24, v99, v72
	v_fmac_f32_e32 v25, v99, v73
	v_fmac_f32_e32 v26, v99, v74
	v_fmac_f32_e32 v27, v99, v75
	v_fmac_f32_e32 v28, v100, v72
	v_fmac_f32_e32 v29, v100, v73
	v_fmac_f32_e32 v30, v100, v74
	v_fmac_f32_e32 v31, v100, v75
	global_load_dwordx4 v[72:75], v11, s[10:11]
	s_add_u32 s10, s10, 0x18000
	s_addc_u32 s11, s11, 0
	ds_read_b32 v96, v10 offset:216
	ds_read_b32 v97, v10 offset:8408
	ds_read_b32 v98, v10 offset:16600
	ds_read_b32 v99, v10 offset:24792
	ds_read_b32 v100, v10 offset:32984
	s_waitcnt vmcnt(15) lgkmcnt(0)
	v_fmac_f32_e32 v12, v96, v76
	v_fmac_f32_e32 v13, v96, v77
	v_fmac_f32_e32 v14, v96, v78
	v_fmac_f32_e32 v15, v96, v79
	v_fmac_f32_e32 v16, v97, v76
	v_fmac_f32_e32 v17, v97, v77
	v_fmac_f32_e32 v18, v97, v78
	v_fmac_f32_e32 v19, v97, v79
	v_fmac_f32_e32 v20, v98, v76
	v_fmac_f32_e32 v21, v98, v77
	v_fmac_f32_e32 v22, v98, v78
	v_fmac_f32_e32 v23, v98, v79
	v_fmac_f32_e32 v24, v99, v76
	v_fmac_f32_e32 v25, v99, v77
	v_fmac_f32_e32 v26, v99, v78
	v_fmac_f32_e32 v27, v99, v79
	v_fmac_f32_e32 v28, v100, v76
	v_fmac_f32_e32 v29, v100, v77
	v_fmac_f32_e32 v30, v100, v78
	v_fmac_f32_e32 v31, v100, v79
	global_load_dwordx4 v[76:79], v11, s[10:11]
	s_add_u32 s10, s10, 0x18000
	s_addc_u32 s11, s11, 0
	ds_read_b32 v96, v10 offset:224
	ds_read_b32 v97, v10 offset:8416
	ds_read_b32 v98, v10 offset:16608
	ds_read_b32 v99, v10 offset:24800
	ds_read_b32 v100, v10 offset:32992
	s_waitcnt vmcnt(15) lgkmcnt(0)
	v_fmac_f32_e32 v12, v96, v80
	v_fmac_f32_e32 v13, v96, v81
	v_fmac_f32_e32 v14, v96, v82
	v_fmac_f32_e32 v15, v96, v83
	v_fmac_f32_e32 v16, v97, v80
	v_fmac_f32_e32 v17, v97, v81
	v_fmac_f32_e32 v18, v97, v82
	v_fmac_f32_e32 v19, v97, v83
	v_fmac_f32_e32 v20, v98, v80
	v_fmac_f32_e32 v21, v98, v81
	v_fmac_f32_e32 v22, v98, v82
	v_fmac_f32_e32 v23, v98, v83
	v_fmac_f32_e32 v24, v99, v80
	v_fmac_f32_e32 v25, v99, v81
	v_fmac_f32_e32 v26, v99, v82
	v_fmac_f32_e32 v27, v99, v83
	v_fmac_f32_e32 v28, v100, v80
	v_fmac_f32_e32 v29, v100, v81
	v_fmac_f32_e32 v30, v100, v82
	v_fmac_f32_e32 v31, v100, v83
	global_load_dwordx4 v[80:83], v11, s[10:11]
	s_add_u32 s10, s10, 0x18000
	s_addc_u32 s11, s11, 0
	ds_read_b32 v96, v10 offset:232
	ds_read_b32 v97, v10 offset:8424
	ds_read_b32 v98, v10 offset:16616
	ds_read_b32 v99, v10 offset:24808
	ds_read_b32 v100, v10 offset:33000
	s_waitcnt vmcnt(15) lgkmcnt(0)
	v_fmac_f32_e32 v12, v96, v84
	v_fmac_f32_e32 v13, v96, v85
	v_fmac_f32_e32 v14, v96, v86
	v_fmac_f32_e32 v15, v96, v87
	v_fmac_f32_e32 v16, v97, v84
	v_fmac_f32_e32 v17, v97, v85
	v_fmac_f32_e32 v18, v97, v86
	v_fmac_f32_e32 v19, v97, v87
	v_fmac_f32_e32 v20, v98, v84
	v_fmac_f32_e32 v21, v98, v85
	v_fmac_f32_e32 v22, v98, v86
	v_fmac_f32_e32 v23, v98, v87
	v_fmac_f32_e32 v24, v99, v84
	v_fmac_f32_e32 v25, v99, v85
	v_fmac_f32_e32 v26, v99, v86
	v_fmac_f32_e32 v27, v99, v87
	v_fmac_f32_e32 v28, v100, v84
	v_fmac_f32_e32 v29, v100, v85
	v_fmac_f32_e32 v30, v100, v86
	v_fmac_f32_e32 v31, v100, v87
	global_load_dwordx4 v[84:87], v11, s[10:11]
	s_add_u32 s10, s10, 0x18000
	s_addc_u32 s11, s11, 0
	ds_read_b32 v96, v10 offset:240
	ds_read_b32 v97, v10 offset:8432
	ds_read_b32 v98, v10 offset:16624
	ds_read_b32 v99, v10 offset:24816
	ds_read_b32 v100, v10 offset:33008
	s_waitcnt vmcnt(15) lgkmcnt(0)
	v_fmac_f32_e32 v12, v96, v88
	v_fmac_f32_e32 v13, v96, v89
	v_fmac_f32_e32 v14, v96, v90
	v_fmac_f32_e32 v15, v96, v91
	v_fmac_f32_e32 v16, v97, v88
	v_fmac_f32_e32 v17, v97, v89
	v_fmac_f32_e32 v18, v97, v90
	v_fmac_f32_e32 v19, v97, v91
	v_fmac_f32_e32 v20, v98, v88
	v_fmac_f32_e32 v21, v98, v89
	v_fmac_f32_e32 v22, v98, v90
	v_fmac_f32_e32 v23, v98, v91
	v_fmac_f32_e32 v24, v99, v88
	v_fmac_f32_e32 v25, v99, v89
	v_fmac_f32_e32 v26, v99, v90
	v_fmac_f32_e32 v27, v99, v91
	v_fmac_f32_e32 v28, v100, v88
	v_fmac_f32_e32 v29, v100, v89
	v_fmac_f32_e32 v30, v100, v90
	v_fmac_f32_e32 v31, v100, v91
	global_load_dwordx4 v[88:91], v11, s[10:11]
	s_add_u32 s10, s10, 0x18000
	s_addc_u32 s11, s11, 0
	ds_read_b32 v96, v10 offset:248
	ds_read_b32 v97, v10 offset:8440
	ds_read_b32 v98, v10 offset:16632
	ds_read_b32 v99, v10 offset:24824
	ds_read_b32 v100, v10 offset:33016
	s_waitcnt vmcnt(15) lgkmcnt(0)
	v_fmac_f32_e32 v12, v96, v92
	v_fmac_f32_e32 v13, v96, v93
	v_fmac_f32_e32 v14, v96, v94
	v_fmac_f32_e32 v15, v96, v95
	v_fmac_f32_e32 v16, v97, v92
	v_fmac_f32_e32 v17, v97, v93
	v_fmac_f32_e32 v18, v97, v94
	v_fmac_f32_e32 v19, v97, v95
	v_fmac_f32_e32 v20, v98, v92
	v_fmac_f32_e32 v21, v98, v93
	v_fmac_f32_e32 v22, v98, v94
	v_fmac_f32_e32 v23, v98, v95
	v_fmac_f32_e32 v24, v99, v92
	v_fmac_f32_e32 v25, v99, v93
	v_fmac_f32_e32 v26, v99, v94
	v_fmac_f32_e32 v27, v99, v95
	v_fmac_f32_e32 v28, v100, v92
	v_fmac_f32_e32 v29, v100, v93
	v_fmac_f32_e32 v30, v100, v94
	v_fmac_f32_e32 v31, v100, v95
	global_load_dwordx4 v[92:95], v11, s[10:11]
	s_add_u32 s10, s10, 0x18000
	s_addc_u32 s11, s11, 0
	ds_read_b32 v96, v10 offset:256
	ds_read_b32 v97, v10 offset:8448
	ds_read_b32 v98, v10 offset:16640
	ds_read_b32 v99, v10 offset:24832
	ds_read_b32 v100, v10 offset:33024
	s_waitcnt vmcnt(15) lgkmcnt(0)
	v_fmac_f32_e32 v12, v96, v32
	v_fmac_f32_e32 v13, v96, v33
	v_fmac_f32_e32 v14, v96, v34
	v_fmac_f32_e32 v15, v96, v35
	v_fmac_f32_e32 v16, v97, v32
	v_fmac_f32_e32 v17, v97, v33
	v_fmac_f32_e32 v18, v97, v34
	v_fmac_f32_e32 v19, v97, v35
	v_fmac_f32_e32 v20, v98, v32
	v_fmac_f32_e32 v21, v98, v33
	v_fmac_f32_e32 v22, v98, v34
	v_fmac_f32_e32 v23, v98, v35
	v_fmac_f32_e32 v24, v99, v32
	v_fmac_f32_e32 v25, v99, v33
	v_fmac_f32_e32 v26, v99, v34
	v_fmac_f32_e32 v27, v99, v35
	v_fmac_f32_e32 v28, v100, v32
	v_fmac_f32_e32 v29, v100, v33
	v_fmac_f32_e32 v30, v100, v34
	v_fmac_f32_e32 v31, v100, v35
	global_load_dwordx4 v[32:35], v11, s[10:11]
	s_add_u32 s10, s10, 0x18000
	s_addc_u32 s11, s11, 0
	ds_read_b32 v96, v10 offset:264
	ds_read_b32 v97, v10 offset:8456
	ds_read_b32 v98, v10 offset:16648
	ds_read_b32 v99, v10 offset:24840
	ds_read_b32 v100, v10 offset:33032
	s_waitcnt vmcnt(15) lgkmcnt(0)
	v_fmac_f32_e32 v12, v96, v36
	v_fmac_f32_e32 v13, v96, v37
	v_fmac_f32_e32 v14, v96, v38
	v_fmac_f32_e32 v15, v96, v39
	v_fmac_f32_e32 v16, v97, v36
	v_fmac_f32_e32 v17, v97, v37
	v_fmac_f32_e32 v18, v97, v38
	v_fmac_f32_e32 v19, v97, v39
	v_fmac_f32_e32 v20, v98, v36
	v_fmac_f32_e32 v21, v98, v37
	v_fmac_f32_e32 v22, v98, v38
	v_fmac_f32_e32 v23, v98, v39
	v_fmac_f32_e32 v24, v99, v36
	v_fmac_f32_e32 v25, v99, v37
	v_fmac_f32_e32 v26, v99, v38
	v_fmac_f32_e32 v27, v99, v39
	v_fmac_f32_e32 v28, v100, v36
	v_fmac_f32_e32 v29, v100, v37
	v_fmac_f32_e32 v30, v100, v38
	v_fmac_f32_e32 v31, v100, v39
	global_load_dwordx4 v[36:39], v11, s[10:11]
	s_add_u32 s10, s10, 0x18000
	s_addc_u32 s11, s11, 0
	ds_read_b32 v96, v10 offset:272
	ds_read_b32 v97, v10 offset:8464
	ds_read_b32 v98, v10 offset:16656
	ds_read_b32 v99, v10 offset:24848
	ds_read_b32 v100, v10 offset:33040
	s_waitcnt vmcnt(15) lgkmcnt(0)
	v_fmac_f32_e32 v12, v96, v40
	v_fmac_f32_e32 v13, v96, v41
	v_fmac_f32_e32 v14, v96, v42
	v_fmac_f32_e32 v15, v96, v43
	v_fmac_f32_e32 v16, v97, v40
	v_fmac_f32_e32 v17, v97, v41
	v_fmac_f32_e32 v18, v97, v42
	v_fmac_f32_e32 v19, v97, v43
	v_fmac_f32_e32 v20, v98, v40
	v_fmac_f32_e32 v21, v98, v41
	v_fmac_f32_e32 v22, v98, v42
	v_fmac_f32_e32 v23, v98, v43
	v_fmac_f32_e32 v24, v99, v40
	v_fmac_f32_e32 v25, v99, v41
	v_fmac_f32_e32 v26, v99, v42
	v_fmac_f32_e32 v27, v99, v43
	v_fmac_f32_e32 v28, v100, v40
	v_fmac_f32_e32 v29, v100, v41
	v_fmac_f32_e32 v30, v100, v42
	v_fmac_f32_e32 v31, v100, v43
	global_load_dwordx4 v[40:43], v11, s[10:11]
	s_add_u32 s10, s10, 0x18000
	s_addc_u32 s11, s11, 0
	ds_read_b32 v96, v10 offset:280
	ds_read_b32 v97, v10 offset:8472
	ds_read_b32 v98, v10 offset:16664
	ds_read_b32 v99, v10 offset:24856
	ds_read_b32 v100, v10 offset:33048
	s_waitcnt vmcnt(15) lgkmcnt(0)
	v_fmac_f32_e32 v12, v96, v44
	v_fmac_f32_e32 v13, v96, v45
	v_fmac_f32_e32 v14, v96, v46
	v_fmac_f32_e32 v15, v96, v47
	v_fmac_f32_e32 v16, v97, v44
	v_fmac_f32_e32 v17, v97, v45
	v_fmac_f32_e32 v18, v97, v46
	v_fmac_f32_e32 v19, v97, v47
	v_fmac_f32_e32 v20, v98, v44
	v_fmac_f32_e32 v21, v98, v45
	v_fmac_f32_e32 v22, v98, v46
	v_fmac_f32_e32 v23, v98, v47
	v_fmac_f32_e32 v24, v99, v44
	v_fmac_f32_e32 v25, v99, v45
	v_fmac_f32_e32 v26, v99, v46
	v_fmac_f32_e32 v27, v99, v47
	v_fmac_f32_e32 v28, v100, v44
	v_fmac_f32_e32 v29, v100, v45
	v_fmac_f32_e32 v30, v100, v46
	v_fmac_f32_e32 v31, v100, v47
	global_load_dwordx4 v[44:47], v11, s[10:11]
	s_add_u32 s10, s10, 0x18000
	s_addc_u32 s11, s11, 0
	ds_read_b32 v96, v10 offset:288
	ds_read_b32 v97, v10 offset:8480
	ds_read_b32 v98, v10 offset:16672
	ds_read_b32 v99, v10 offset:24864
	ds_read_b32 v100, v10 offset:33056
	s_waitcnt vmcnt(15) lgkmcnt(0)
	v_fmac_f32_e32 v12, v96, v48
	v_fmac_f32_e32 v13, v96, v49
	v_fmac_f32_e32 v14, v96, v50
	v_fmac_f32_e32 v15, v96, v51
	v_fmac_f32_e32 v16, v97, v48
	v_fmac_f32_e32 v17, v97, v49
	v_fmac_f32_e32 v18, v97, v50
	v_fmac_f32_e32 v19, v97, v51
	v_fmac_f32_e32 v20, v98, v48
	v_fmac_f32_e32 v21, v98, v49
	v_fmac_f32_e32 v22, v98, v50
	v_fmac_f32_e32 v23, v98, v51
	v_fmac_f32_e32 v24, v99, v48
	v_fmac_f32_e32 v25, v99, v49
	v_fmac_f32_e32 v26, v99, v50
	v_fmac_f32_e32 v27, v99, v51
	v_fmac_f32_e32 v28, v100, v48
	v_fmac_f32_e32 v29, v100, v49
	v_fmac_f32_e32 v30, v100, v50
	v_fmac_f32_e32 v31, v100, v51
	global_load_dwordx4 v[48:51], v11, s[10:11]
	s_add_u32 s10, s10, 0x18000
	s_addc_u32 s11, s11, 0
	ds_read_b32 v96, v10 offset:296
	ds_read_b32 v97, v10 offset:8488
	ds_read_b32 v98, v10 offset:16680
	ds_read_b32 v99, v10 offset:24872
	ds_read_b32 v100, v10 offset:33064
	s_waitcnt vmcnt(15) lgkmcnt(0)
	v_fmac_f32_e32 v12, v96, v52
	v_fmac_f32_e32 v13, v96, v53
	v_fmac_f32_e32 v14, v96, v54
	v_fmac_f32_e32 v15, v96, v55
	v_fmac_f32_e32 v16, v97, v52
	v_fmac_f32_e32 v17, v97, v53
	v_fmac_f32_e32 v18, v97, v54
	v_fmac_f32_e32 v19, v97, v55
	v_fmac_f32_e32 v20, v98, v52
	v_fmac_f32_e32 v21, v98, v53
	v_fmac_f32_e32 v22, v98, v54
	v_fmac_f32_e32 v23, v98, v55
	v_fmac_f32_e32 v24, v99, v52
	v_fmac_f32_e32 v25, v99, v53
	v_fmac_f32_e32 v26, v99, v54
	v_fmac_f32_e32 v27, v99, v55
	v_fmac_f32_e32 v28, v100, v52
	v_fmac_f32_e32 v29, v100, v53
	v_fmac_f32_e32 v30, v100, v54
	v_fmac_f32_e32 v31, v100, v55
	global_load_dwordx4 v[52:55], v11, s[10:11]
	s_add_u32 s10, s10, 0x18000
	s_addc_u32 s11, s11, 0
	ds_read_b32 v96, v10 offset:304
	ds_read_b32 v97, v10 offset:8496
	ds_read_b32 v98, v10 offset:16688
	ds_read_b32 v99, v10 offset:24880
	ds_read_b32 v100, v10 offset:33072
	s_waitcnt vmcnt(15) lgkmcnt(0)
	v_fmac_f32_e32 v12, v96, v56
	v_fmac_f32_e32 v13, v96, v57
	v_fmac_f32_e32 v14, v96, v58
	v_fmac_f32_e32 v15, v96, v59
	v_fmac_f32_e32 v16, v97, v56
	v_fmac_f32_e32 v17, v97, v57
	v_fmac_f32_e32 v18, v97, v58
	v_fmac_f32_e32 v19, v97, v59
	v_fmac_f32_e32 v20, v98, v56
	v_fmac_f32_e32 v21, v98, v57
	v_fmac_f32_e32 v22, v98, v58
	v_fmac_f32_e32 v23, v98, v59
	v_fmac_f32_e32 v24, v99, v56
	v_fmac_f32_e32 v25, v99, v57
	v_fmac_f32_e32 v26, v99, v58
	v_fmac_f32_e32 v27, v99, v59
	v_fmac_f32_e32 v28, v100, v56
	v_fmac_f32_e32 v29, v100, v57
	v_fmac_f32_e32 v30, v100, v58
	v_fmac_f32_e32 v31, v100, v59
	global_load_dwordx4 v[56:59], v11, s[10:11]
	s_add_u32 s10, s10, 0x18000
	s_addc_u32 s11, s11, 0
	ds_read_b32 v96, v10 offset:312
	ds_read_b32 v97, v10 offset:8504
	ds_read_b32 v98, v10 offset:16696
	ds_read_b32 v99, v10 offset:24888
	ds_read_b32 v100, v10 offset:33080
	s_waitcnt vmcnt(15) lgkmcnt(0)
	v_fmac_f32_e32 v12, v96, v60
	v_fmac_f32_e32 v13, v96, v61
	v_fmac_f32_e32 v14, v96, v62
	v_fmac_f32_e32 v15, v96, v63
	v_fmac_f32_e32 v16, v97, v60
	v_fmac_f32_e32 v17, v97, v61
	v_fmac_f32_e32 v18, v97, v62
	v_fmac_f32_e32 v19, v97, v63
	v_fmac_f32_e32 v20, v98, v60
	v_fmac_f32_e32 v21, v98, v61
	v_fmac_f32_e32 v22, v98, v62
	v_fmac_f32_e32 v23, v98, v63
	v_fmac_f32_e32 v24, v99, v60
	v_fmac_f32_e32 v25, v99, v61
	v_fmac_f32_e32 v26, v99, v62
	v_fmac_f32_e32 v27, v99, v63
	v_fmac_f32_e32 v28, v100, v60
	v_fmac_f32_e32 v29, v100, v61
	v_fmac_f32_e32 v30, v100, v62
	v_fmac_f32_e32 v31, v100, v63
	global_load_dwordx4 v[60:63], v11, s[10:11]
	s_add_u32 s10, s10, 0x18000
	s_addc_u32 s11, s11, 0
	ds_read_b32 v96, v10 offset:320
	ds_read_b32 v97, v10 offset:8512
	ds_read_b32 v98, v10 offset:16704
	ds_read_b32 v99, v10 offset:24896
	ds_read_b32 v100, v10 offset:33088
	s_waitcnt vmcnt(15) lgkmcnt(0)
	v_fmac_f32_e32 v12, v96, v64
	v_fmac_f32_e32 v13, v96, v65
	v_fmac_f32_e32 v14, v96, v66
	v_fmac_f32_e32 v15, v96, v67
	v_fmac_f32_e32 v16, v97, v64
	v_fmac_f32_e32 v17, v97, v65
	v_fmac_f32_e32 v18, v97, v66
	v_fmac_f32_e32 v19, v97, v67
	v_fmac_f32_e32 v20, v98, v64
	v_fmac_f32_e32 v21, v98, v65
	v_fmac_f32_e32 v22, v98, v66
	v_fmac_f32_e32 v23, v98, v67
	v_fmac_f32_e32 v24, v99, v64
	v_fmac_f32_e32 v25, v99, v65
	v_fmac_f32_e32 v26, v99, v66
	v_fmac_f32_e32 v27, v99, v67
	v_fmac_f32_e32 v28, v100, v64
	v_fmac_f32_e32 v29, v100, v65
	v_fmac_f32_e32 v30, v100, v66
	v_fmac_f32_e32 v31, v100, v67
	global_load_dwordx4 v[64:67], v11, s[10:11]
	s_add_u32 s10, s10, 0x18000
	s_addc_u32 s11, s11, 0
	ds_read_b32 v96, v10 offset:328
	ds_read_b32 v97, v10 offset:8520
	ds_read_b32 v98, v10 offset:16712
	ds_read_b32 v99, v10 offset:24904
	ds_read_b32 v100, v10 offset:33096
	s_waitcnt vmcnt(15) lgkmcnt(0)
	v_fmac_f32_e32 v12, v96, v68
	v_fmac_f32_e32 v13, v96, v69
	v_fmac_f32_e32 v14, v96, v70
	v_fmac_f32_e32 v15, v96, v71
	v_fmac_f32_e32 v16, v97, v68
	v_fmac_f32_e32 v17, v97, v69
	v_fmac_f32_e32 v18, v97, v70
	v_fmac_f32_e32 v19, v97, v71
	v_fmac_f32_e32 v20, v98, v68
	v_fmac_f32_e32 v21, v98, v69
	v_fmac_f32_e32 v22, v98, v70
	v_fmac_f32_e32 v23, v98, v71
	v_fmac_f32_e32 v24, v99, v68
	v_fmac_f32_e32 v25, v99, v69
	v_fmac_f32_e32 v26, v99, v70
	v_fmac_f32_e32 v27, v99, v71
	v_fmac_f32_e32 v28, v100, v68
	v_fmac_f32_e32 v29, v100, v69
	v_fmac_f32_e32 v30, v100, v70
	v_fmac_f32_e32 v31, v100, v71
	global_load_dwordx4 v[68:71], v11, s[10:11]
	s_add_u32 s10, s10, 0x18000
	s_addc_u32 s11, s11, 0
	ds_read_b32 v96, v10 offset:336
	ds_read_b32 v97, v10 offset:8528
	ds_read_b32 v98, v10 offset:16720
	ds_read_b32 v99, v10 offset:24912
	ds_read_b32 v100, v10 offset:33104
	s_waitcnt vmcnt(15) lgkmcnt(0)
	v_fmac_f32_e32 v12, v96, v72
	v_fmac_f32_e32 v13, v96, v73
	v_fmac_f32_e32 v14, v96, v74
	v_fmac_f32_e32 v15, v96, v75
	v_fmac_f32_e32 v16, v97, v72
	v_fmac_f32_e32 v17, v97, v73
	v_fmac_f32_e32 v18, v97, v74
	v_fmac_f32_e32 v19, v97, v75
	v_fmac_f32_e32 v20, v98, v72
	v_fmac_f32_e32 v21, v98, v73
	v_fmac_f32_e32 v22, v98, v74
	v_fmac_f32_e32 v23, v98, v75
	v_fmac_f32_e32 v24, v99, v72
	v_fmac_f32_e32 v25, v99, v73
	v_fmac_f32_e32 v26, v99, v74
	v_fmac_f32_e32 v27, v99, v75
	v_fmac_f32_e32 v28, v100, v72
	v_fmac_f32_e32 v29, v100, v73
	v_fmac_f32_e32 v30, v100, v74
	v_fmac_f32_e32 v31, v100, v75
	global_load_dwordx4 v[72:75], v11, s[10:11]
	s_add_u32 s10, s10, 0x18000
	s_addc_u32 s11, s11, 0
	ds_read_b32 v96, v10 offset:344
	ds_read_b32 v97, v10 offset:8536
	ds_read_b32 v98, v10 offset:16728
	ds_read_b32 v99, v10 offset:24920
	ds_read_b32 v100, v10 offset:33112
	s_waitcnt vmcnt(15) lgkmcnt(0)
	v_fmac_f32_e32 v12, v96, v76
	v_fmac_f32_e32 v13, v96, v77
	v_fmac_f32_e32 v14, v96, v78
	v_fmac_f32_e32 v15, v96, v79
	v_fmac_f32_e32 v16, v97, v76
	v_fmac_f32_e32 v17, v97, v77
	v_fmac_f32_e32 v18, v97, v78
	v_fmac_f32_e32 v19, v97, v79
	v_fmac_f32_e32 v20, v98, v76
	v_fmac_f32_e32 v21, v98, v77
	v_fmac_f32_e32 v22, v98, v78
	v_fmac_f32_e32 v23, v98, v79
	v_fmac_f32_e32 v24, v99, v76
	v_fmac_f32_e32 v25, v99, v77
	v_fmac_f32_e32 v26, v99, v78
	v_fmac_f32_e32 v27, v99, v79
	v_fmac_f32_e32 v28, v100, v76
	v_fmac_f32_e32 v29, v100, v77
	v_fmac_f32_e32 v30, v100, v78
	v_fmac_f32_e32 v31, v100, v79
	global_load_dwordx4 v[76:79], v11, s[10:11]
	s_add_u32 s10, s10, 0x18000
	s_addc_u32 s11, s11, 0
	ds_read_b32 v96, v10 offset:352
	ds_read_b32 v97, v10 offset:8544
	ds_read_b32 v98, v10 offset:16736
	ds_read_b32 v99, v10 offset:24928
	ds_read_b32 v100, v10 offset:33120
	s_waitcnt vmcnt(15) lgkmcnt(0)
	v_fmac_f32_e32 v12, v96, v80
	v_fmac_f32_e32 v13, v96, v81
	v_fmac_f32_e32 v14, v96, v82
	v_fmac_f32_e32 v15, v96, v83
	v_fmac_f32_e32 v16, v97, v80
	v_fmac_f32_e32 v17, v97, v81
	v_fmac_f32_e32 v18, v97, v82
	v_fmac_f32_e32 v19, v97, v83
	v_fmac_f32_e32 v20, v98, v80
	v_fmac_f32_e32 v21, v98, v81
	v_fmac_f32_e32 v22, v98, v82
	v_fmac_f32_e32 v23, v98, v83
	v_fmac_f32_e32 v24, v99, v80
	v_fmac_f32_e32 v25, v99, v81
	v_fmac_f32_e32 v26, v99, v82
	v_fmac_f32_e32 v27, v99, v83
	v_fmac_f32_e32 v28, v100, v80
	v_fmac_f32_e32 v29, v100, v81
	v_fmac_f32_e32 v30, v100, v82
	v_fmac_f32_e32 v31, v100, v83
	global_load_dwordx4 v[80:83], v11, s[10:11]
	s_add_u32 s10, s10, 0x18000
	s_addc_u32 s11, s11, 0
	ds_read_b32 v96, v10 offset:360
	ds_read_b32 v97, v10 offset:8552
	ds_read_b32 v98, v10 offset:16744
	ds_read_b32 v99, v10 offset:24936
	ds_read_b32 v100, v10 offset:33128
	s_waitcnt vmcnt(15) lgkmcnt(0)
	v_fmac_f32_e32 v12, v96, v84
	v_fmac_f32_e32 v13, v96, v85
	v_fmac_f32_e32 v14, v96, v86
	v_fmac_f32_e32 v15, v96, v87
	v_fmac_f32_e32 v16, v97, v84
	v_fmac_f32_e32 v17, v97, v85
	v_fmac_f32_e32 v18, v97, v86
	v_fmac_f32_e32 v19, v97, v87
	v_fmac_f32_e32 v20, v98, v84
	v_fmac_f32_e32 v21, v98, v85
	v_fmac_f32_e32 v22, v98, v86
	v_fmac_f32_e32 v23, v98, v87
	v_fmac_f32_e32 v24, v99, v84
	v_fmac_f32_e32 v25, v99, v85
	v_fmac_f32_e32 v26, v99, v86
	v_fmac_f32_e32 v27, v99, v87
	v_fmac_f32_e32 v28, v100, v84
	v_fmac_f32_e32 v29, v100, v85
	v_fmac_f32_e32 v30, v100, v86
	v_fmac_f32_e32 v31, v100, v87
	global_load_dwordx4 v[84:87], v11, s[10:11]
	s_add_u32 s10, s10, 0x18000
	s_addc_u32 s11, s11, 0
	ds_read_b32 v96, v10 offset:368
	ds_read_b32 v97, v10 offset:8560
	ds_read_b32 v98, v10 offset:16752
	ds_read_b32 v99, v10 offset:24944
	ds_read_b32 v100, v10 offset:33136
	s_waitcnt vmcnt(15) lgkmcnt(0)
	v_fmac_f32_e32 v12, v96, v88
	v_fmac_f32_e32 v13, v96, v89
	v_fmac_f32_e32 v14, v96, v90
	v_fmac_f32_e32 v15, v96, v91
	v_fmac_f32_e32 v16, v97, v88
	v_fmac_f32_e32 v17, v97, v89
	v_fmac_f32_e32 v18, v97, v90
	v_fmac_f32_e32 v19, v97, v91
	v_fmac_f32_e32 v20, v98, v88
	v_fmac_f32_e32 v21, v98, v89
	v_fmac_f32_e32 v22, v98, v90
	v_fmac_f32_e32 v23, v98, v91
	v_fmac_f32_e32 v24, v99, v88
	v_fmac_f32_e32 v25, v99, v89
	v_fmac_f32_e32 v26, v99, v90
	v_fmac_f32_e32 v27, v99, v91
	v_fmac_f32_e32 v28, v100, v88
	v_fmac_f32_e32 v29, v100, v89
	v_fmac_f32_e32 v30, v100, v90
	v_fmac_f32_e32 v31, v100, v91
	global_load_dwordx4 v[88:91], v11, s[10:11]
	s_add_u32 s10, s10, 0x18000
	s_addc_u32 s11, s11, 0
	ds_read_b32 v96, v10 offset:376
	ds_read_b32 v97, v10 offset:8568
	ds_read_b32 v98, v10 offset:16760
	ds_read_b32 v99, v10 offset:24952
	ds_read_b32 v100, v10 offset:33144
	s_waitcnt vmcnt(15) lgkmcnt(0)
	v_fmac_f32_e32 v12, v96, v92
	v_fmac_f32_e32 v13, v96, v93
	v_fmac_f32_e32 v14, v96, v94
	v_fmac_f32_e32 v15, v96, v95
	v_fmac_f32_e32 v16, v97, v92
	v_fmac_f32_e32 v17, v97, v93
	v_fmac_f32_e32 v18, v97, v94
	v_fmac_f32_e32 v19, v97, v95
	v_fmac_f32_e32 v20, v98, v92
	v_fmac_f32_e32 v21, v98, v93
	v_fmac_f32_e32 v22, v98, v94
	v_fmac_f32_e32 v23, v98, v95
	v_fmac_f32_e32 v24, v99, v92
	v_fmac_f32_e32 v25, v99, v93
	v_fmac_f32_e32 v26, v99, v94
	v_fmac_f32_e32 v27, v99, v95
	v_fmac_f32_e32 v28, v100, v92
	v_fmac_f32_e32 v29, v100, v93
	v_fmac_f32_e32 v30, v100, v94
	v_fmac_f32_e32 v31, v100, v95
	global_load_dwordx4 v[92:95], v11, s[10:11]
	s_add_u32 s10, s10, 0x18000
	s_addc_u32 s11, s11, 0
	ds_read_b32 v96, v10 offset:384
	ds_read_b32 v97, v10 offset:8576
	ds_read_b32 v98, v10 offset:16768
	ds_read_b32 v99, v10 offset:24960
	ds_read_b32 v100, v10 offset:33152
	s_waitcnt vmcnt(15) lgkmcnt(0)
	v_fmac_f32_e32 v12, v96, v32
	v_fmac_f32_e32 v13, v96, v33
	v_fmac_f32_e32 v14, v96, v34
	v_fmac_f32_e32 v15, v96, v35
	v_fmac_f32_e32 v16, v97, v32
	v_fmac_f32_e32 v17, v97, v33
	v_fmac_f32_e32 v18, v97, v34
	v_fmac_f32_e32 v19, v97, v35
	v_fmac_f32_e32 v20, v98, v32
	v_fmac_f32_e32 v21, v98, v33
	v_fmac_f32_e32 v22, v98, v34
	v_fmac_f32_e32 v23, v98, v35
	v_fmac_f32_e32 v24, v99, v32
	v_fmac_f32_e32 v25, v99, v33
	v_fmac_f32_e32 v26, v99, v34
	v_fmac_f32_e32 v27, v99, v35
	v_fmac_f32_e32 v28, v100, v32
	v_fmac_f32_e32 v29, v100, v33
	v_fmac_f32_e32 v30, v100, v34
	v_fmac_f32_e32 v31, v100, v35
	global_load_dwordx4 v[32:35], v11, s[10:11]
	s_add_u32 s10, s10, 0x18000
	s_addc_u32 s11, s11, 0
	ds_read_b32 v96, v10 offset:392
	ds_read_b32 v97, v10 offset:8584
	ds_read_b32 v98, v10 offset:16776
	ds_read_b32 v99, v10 offset:24968
	ds_read_b32 v100, v10 offset:33160
	s_waitcnt vmcnt(15) lgkmcnt(0)
	v_fmac_f32_e32 v12, v96, v36
	v_fmac_f32_e32 v13, v96, v37
	v_fmac_f32_e32 v14, v96, v38
	v_fmac_f32_e32 v15, v96, v39
	v_fmac_f32_e32 v16, v97, v36
	v_fmac_f32_e32 v17, v97, v37
	v_fmac_f32_e32 v18, v97, v38
	v_fmac_f32_e32 v19, v97, v39
	v_fmac_f32_e32 v20, v98, v36
	v_fmac_f32_e32 v21, v98, v37
	v_fmac_f32_e32 v22, v98, v38
	v_fmac_f32_e32 v23, v98, v39
	v_fmac_f32_e32 v24, v99, v36
	v_fmac_f32_e32 v25, v99, v37
	v_fmac_f32_e32 v26, v99, v38
	v_fmac_f32_e32 v27, v99, v39
	v_fmac_f32_e32 v28, v100, v36
	v_fmac_f32_e32 v29, v100, v37
	v_fmac_f32_e32 v30, v100, v38
	v_fmac_f32_e32 v31, v100, v39
	global_load_dwordx4 v[36:39], v11, s[10:11]
	s_add_u32 s10, s10, 0x18000
	s_addc_u32 s11, s11, 0
	ds_read_b32 v96, v10 offset:400
	ds_read_b32 v97, v10 offset:8592
	ds_read_b32 v98, v10 offset:16784
	ds_read_b32 v99, v10 offset:24976
	ds_read_b32 v100, v10 offset:33168
	s_waitcnt vmcnt(15) lgkmcnt(0)
	v_fmac_f32_e32 v12, v96, v40
	v_fmac_f32_e32 v13, v96, v41
	v_fmac_f32_e32 v14, v96, v42
	v_fmac_f32_e32 v15, v96, v43
	v_fmac_f32_e32 v16, v97, v40
	v_fmac_f32_e32 v17, v97, v41
	v_fmac_f32_e32 v18, v97, v42
	v_fmac_f32_e32 v19, v97, v43
	v_fmac_f32_e32 v20, v98, v40
	v_fmac_f32_e32 v21, v98, v41
	v_fmac_f32_e32 v22, v98, v42
	v_fmac_f32_e32 v23, v98, v43
	v_fmac_f32_e32 v24, v99, v40
	v_fmac_f32_e32 v25, v99, v41
	v_fmac_f32_e32 v26, v99, v42
	v_fmac_f32_e32 v27, v99, v43
	v_fmac_f32_e32 v28, v100, v40
	v_fmac_f32_e32 v29, v100, v41
	v_fmac_f32_e32 v30, v100, v42
	v_fmac_f32_e32 v31, v100, v43
	global_load_dwordx4 v[40:43], v11, s[10:11]
	s_add_u32 s10, s10, 0x18000
	s_addc_u32 s11, s11, 0
	ds_read_b32 v96, v10 offset:408
	ds_read_b32 v97, v10 offset:8600
	ds_read_b32 v98, v10 offset:16792
	ds_read_b32 v99, v10 offset:24984
	ds_read_b32 v100, v10 offset:33176
	s_waitcnt vmcnt(15) lgkmcnt(0)
	v_fmac_f32_e32 v12, v96, v44
	v_fmac_f32_e32 v13, v96, v45
	v_fmac_f32_e32 v14, v96, v46
	v_fmac_f32_e32 v15, v96, v47
	v_fmac_f32_e32 v16, v97, v44
	v_fmac_f32_e32 v17, v97, v45
	v_fmac_f32_e32 v18, v97, v46
	v_fmac_f32_e32 v19, v97, v47
	v_fmac_f32_e32 v20, v98, v44
	v_fmac_f32_e32 v21, v98, v45
	v_fmac_f32_e32 v22, v98, v46
	v_fmac_f32_e32 v23, v98, v47
	v_fmac_f32_e32 v24, v99, v44
	v_fmac_f32_e32 v25, v99, v45
	v_fmac_f32_e32 v26, v99, v46
	v_fmac_f32_e32 v27, v99, v47
	v_fmac_f32_e32 v28, v100, v44
	v_fmac_f32_e32 v29, v100, v45
	v_fmac_f32_e32 v30, v100, v46
	v_fmac_f32_e32 v31, v100, v47
	global_load_dwordx4 v[44:47], v11, s[10:11]
	s_add_u32 s10, s10, 0x18000
	s_addc_u32 s11, s11, 0
	ds_read_b32 v96, v10 offset:416
	ds_read_b32 v97, v10 offset:8608
	ds_read_b32 v98, v10 offset:16800
	ds_read_b32 v99, v10 offset:24992
	ds_read_b32 v100, v10 offset:33184
	s_waitcnt vmcnt(15) lgkmcnt(0)
	v_fmac_f32_e32 v12, v96, v48
	v_fmac_f32_e32 v13, v96, v49
	v_fmac_f32_e32 v14, v96, v50
	v_fmac_f32_e32 v15, v96, v51
	v_fmac_f32_e32 v16, v97, v48
	v_fmac_f32_e32 v17, v97, v49
	v_fmac_f32_e32 v18, v97, v50
	v_fmac_f32_e32 v19, v97, v51
	v_fmac_f32_e32 v20, v98, v48
	v_fmac_f32_e32 v21, v98, v49
	v_fmac_f32_e32 v22, v98, v50
	v_fmac_f32_e32 v23, v98, v51
	v_fmac_f32_e32 v24, v99, v48
	v_fmac_f32_e32 v25, v99, v49
	v_fmac_f32_e32 v26, v99, v50
	v_fmac_f32_e32 v27, v99, v51
	v_fmac_f32_e32 v28, v100, v48
	v_fmac_f32_e32 v29, v100, v49
	v_fmac_f32_e32 v30, v100, v50
	v_fmac_f32_e32 v31, v100, v51
	global_load_dwordx4 v[48:51], v11, s[10:11]
	s_add_u32 s10, s10, 0x18000
	s_addc_u32 s11, s11, 0
	ds_read_b32 v96, v10 offset:424
	ds_read_b32 v97, v10 offset:8616
	ds_read_b32 v98, v10 offset:16808
	ds_read_b32 v99, v10 offset:25000
	ds_read_b32 v100, v10 offset:33192
	s_waitcnt vmcnt(15) lgkmcnt(0)
	v_fmac_f32_e32 v12, v96, v52
	v_fmac_f32_e32 v13, v96, v53
	v_fmac_f32_e32 v14, v96, v54
	v_fmac_f32_e32 v15, v96, v55
	v_fmac_f32_e32 v16, v97, v52
	v_fmac_f32_e32 v17, v97, v53
	v_fmac_f32_e32 v18, v97, v54
	v_fmac_f32_e32 v19, v97, v55
	v_fmac_f32_e32 v20, v98, v52
	v_fmac_f32_e32 v21, v98, v53
	v_fmac_f32_e32 v22, v98, v54
	v_fmac_f32_e32 v23, v98, v55
	v_fmac_f32_e32 v24, v99, v52
	v_fmac_f32_e32 v25, v99, v53
	v_fmac_f32_e32 v26, v99, v54
	v_fmac_f32_e32 v27, v99, v55
	v_fmac_f32_e32 v28, v100, v52
	v_fmac_f32_e32 v29, v100, v53
	v_fmac_f32_e32 v30, v100, v54
	v_fmac_f32_e32 v31, v100, v55
	global_load_dwordx4 v[52:55], v11, s[10:11]
	s_add_u32 s10, s10, 0x18000
	s_addc_u32 s11, s11, 0
	ds_read_b32 v96, v10 offset:432
	ds_read_b32 v97, v10 offset:8624
	ds_read_b32 v98, v10 offset:16816
	ds_read_b32 v99, v10 offset:25008
	ds_read_b32 v100, v10 offset:33200
	s_waitcnt vmcnt(15) lgkmcnt(0)
	v_fmac_f32_e32 v12, v96, v56
	v_fmac_f32_e32 v13, v96, v57
	v_fmac_f32_e32 v14, v96, v58
	v_fmac_f32_e32 v15, v96, v59
	v_fmac_f32_e32 v16, v97, v56
	v_fmac_f32_e32 v17, v97, v57
	v_fmac_f32_e32 v18, v97, v58
	v_fmac_f32_e32 v19, v97, v59
	v_fmac_f32_e32 v20, v98, v56
	v_fmac_f32_e32 v21, v98, v57
	v_fmac_f32_e32 v22, v98, v58
	v_fmac_f32_e32 v23, v98, v59
	v_fmac_f32_e32 v24, v99, v56
	v_fmac_f32_e32 v25, v99, v57
	v_fmac_f32_e32 v26, v99, v58
	v_fmac_f32_e32 v27, v99, v59
	v_fmac_f32_e32 v28, v100, v56
	v_fmac_f32_e32 v29, v100, v57
	v_fmac_f32_e32 v30, v100, v58
	v_fmac_f32_e32 v31, v100, v59
	global_load_dwordx4 v[56:59], v11, s[10:11]
	s_add_u32 s10, s10, 0x18000
	s_addc_u32 s11, s11, 0
	ds_read_b32 v96, v10 offset:440
	ds_read_b32 v97, v10 offset:8632
	ds_read_b32 v98, v10 offset:16824
	ds_read_b32 v99, v10 offset:25016
	ds_read_b32 v100, v10 offset:33208
	s_waitcnt vmcnt(15) lgkmcnt(0)
	v_fmac_f32_e32 v12, v96, v60
	v_fmac_f32_e32 v13, v96, v61
	v_fmac_f32_e32 v14, v96, v62
	v_fmac_f32_e32 v15, v96, v63
	v_fmac_f32_e32 v16, v97, v60
	v_fmac_f32_e32 v17, v97, v61
	v_fmac_f32_e32 v18, v97, v62
	v_fmac_f32_e32 v19, v97, v63
	v_fmac_f32_e32 v20, v98, v60
	v_fmac_f32_e32 v21, v98, v61
	v_fmac_f32_e32 v22, v98, v62
	v_fmac_f32_e32 v23, v98, v63
	v_fmac_f32_e32 v24, v99, v60
	v_fmac_f32_e32 v25, v99, v61
	v_fmac_f32_e32 v26, v99, v62
	v_fmac_f32_e32 v27, v99, v63
	v_fmac_f32_e32 v28, v100, v60
	v_fmac_f32_e32 v29, v100, v61
	v_fmac_f32_e32 v30, v100, v62
	v_fmac_f32_e32 v31, v100, v63
	global_load_dwordx4 v[60:63], v11, s[10:11]
	s_add_u32 s10, s10, 0x18000
	s_addc_u32 s11, s11, 0
	ds_read_b32 v96, v10 offset:448
	ds_read_b32 v97, v10 offset:8640
	ds_read_b32 v98, v10 offset:16832
	ds_read_b32 v99, v10 offset:25024
	ds_read_b32 v100, v10 offset:33216
	s_waitcnt vmcnt(15) lgkmcnt(0)
	v_fmac_f32_e32 v12, v96, v64
	v_fmac_f32_e32 v13, v96, v65
	v_fmac_f32_e32 v14, v96, v66
	v_fmac_f32_e32 v15, v96, v67
	v_fmac_f32_e32 v16, v97, v64
	v_fmac_f32_e32 v17, v97, v65
	v_fmac_f32_e32 v18, v97, v66
	v_fmac_f32_e32 v19, v97, v67
	v_fmac_f32_e32 v20, v98, v64
	v_fmac_f32_e32 v21, v98, v65
	v_fmac_f32_e32 v22, v98, v66
	v_fmac_f32_e32 v23, v98, v67
	v_fmac_f32_e32 v24, v99, v64
	v_fmac_f32_e32 v25, v99, v65
	v_fmac_f32_e32 v26, v99, v66
	v_fmac_f32_e32 v27, v99, v67
	v_fmac_f32_e32 v28, v100, v64
	v_fmac_f32_e32 v29, v100, v65
	v_fmac_f32_e32 v30, v100, v66
	v_fmac_f32_e32 v31, v100, v67
	global_load_dwordx4 v[64:67], v11, s[10:11]
	s_add_u32 s10, s10, 0x18000
	s_addc_u32 s11, s11, 0
	ds_read_b32 v96, v10 offset:456
	ds_read_b32 v97, v10 offset:8648
	ds_read_b32 v98, v10 offset:16840
	ds_read_b32 v99, v10 offset:25032
	ds_read_b32 v100, v10 offset:33224
	s_waitcnt vmcnt(15) lgkmcnt(0)
	v_fmac_f32_e32 v12, v96, v68
	v_fmac_f32_e32 v13, v96, v69
	v_fmac_f32_e32 v14, v96, v70
	v_fmac_f32_e32 v15, v96, v71
	v_fmac_f32_e32 v16, v97, v68
	v_fmac_f32_e32 v17, v97, v69
	v_fmac_f32_e32 v18, v97, v70
	v_fmac_f32_e32 v19, v97, v71
	v_fmac_f32_e32 v20, v98, v68
	v_fmac_f32_e32 v21, v98, v69
	v_fmac_f32_e32 v22, v98, v70
	v_fmac_f32_e32 v23, v98, v71
	v_fmac_f32_e32 v24, v99, v68
	v_fmac_f32_e32 v25, v99, v69
	v_fmac_f32_e32 v26, v99, v70
	v_fmac_f32_e32 v27, v99, v71
	v_fmac_f32_e32 v28, v100, v68
	v_fmac_f32_e32 v29, v100, v69
	v_fmac_f32_e32 v30, v100, v70
	v_fmac_f32_e32 v31, v100, v71
	global_load_dwordx4 v[68:71], v11, s[10:11]
	s_add_u32 s10, s10, 0x18000
	s_addc_u32 s11, s11, 0
	ds_read_b32 v96, v10 offset:464
	ds_read_b32 v97, v10 offset:8656
	ds_read_b32 v98, v10 offset:16848
	ds_read_b32 v99, v10 offset:25040
	ds_read_b32 v100, v10 offset:33232
	s_waitcnt vmcnt(15) lgkmcnt(0)
	v_fmac_f32_e32 v12, v96, v72
	v_fmac_f32_e32 v13, v96, v73
	v_fmac_f32_e32 v14, v96, v74
	v_fmac_f32_e32 v15, v96, v75
	v_fmac_f32_e32 v16, v97, v72
	v_fmac_f32_e32 v17, v97, v73
	v_fmac_f32_e32 v18, v97, v74
	v_fmac_f32_e32 v19, v97, v75
	v_fmac_f32_e32 v20, v98, v72
	v_fmac_f32_e32 v21, v98, v73
	v_fmac_f32_e32 v22, v98, v74
	v_fmac_f32_e32 v23, v98, v75
	v_fmac_f32_e32 v24, v99, v72
	v_fmac_f32_e32 v25, v99, v73
	v_fmac_f32_e32 v26, v99, v74
	v_fmac_f32_e32 v27, v99, v75
	v_fmac_f32_e32 v28, v100, v72
	v_fmac_f32_e32 v29, v100, v73
	v_fmac_f32_e32 v30, v100, v74
	v_fmac_f32_e32 v31, v100, v75
	global_load_dwordx4 v[72:75], v11, s[10:11]
	s_add_u32 s10, s10, 0x18000
	s_addc_u32 s11, s11, 0
	ds_read_b32 v96, v10 offset:472
	ds_read_b32 v97, v10 offset:8664
	ds_read_b32 v98, v10 offset:16856
	ds_read_b32 v99, v10 offset:25048
	ds_read_b32 v100, v10 offset:33240
	s_waitcnt vmcnt(15) lgkmcnt(0)
	v_fmac_f32_e32 v12, v96, v76
	v_fmac_f32_e32 v13, v96, v77
	v_fmac_f32_e32 v14, v96, v78
	v_fmac_f32_e32 v15, v96, v79
	v_fmac_f32_e32 v16, v97, v76
	v_fmac_f32_e32 v17, v97, v77
	v_fmac_f32_e32 v18, v97, v78
	v_fmac_f32_e32 v19, v97, v79
	v_fmac_f32_e32 v20, v98, v76
	v_fmac_f32_e32 v21, v98, v77
	v_fmac_f32_e32 v22, v98, v78
	v_fmac_f32_e32 v23, v98, v79
	v_fmac_f32_e32 v24, v99, v76
	v_fmac_f32_e32 v25, v99, v77
	v_fmac_f32_e32 v26, v99, v78
	v_fmac_f32_e32 v27, v99, v79
	v_fmac_f32_e32 v28, v100, v76
	v_fmac_f32_e32 v29, v100, v77
	v_fmac_f32_e32 v30, v100, v78
	v_fmac_f32_e32 v31, v100, v79
	global_load_dwordx4 v[76:79], v11, s[10:11]
	s_add_u32 s10, s10, 0x18000
	s_addc_u32 s11, s11, 0
	ds_read_b32 v96, v10 offset:480
	ds_read_b32 v97, v10 offset:8672
	ds_read_b32 v98, v10 offset:16864
	ds_read_b32 v99, v10 offset:25056
	ds_read_b32 v100, v10 offset:33248
	s_waitcnt vmcnt(15) lgkmcnt(0)
	v_fmac_f32_e32 v12, v96, v80
	v_fmac_f32_e32 v13, v96, v81
	v_fmac_f32_e32 v14, v96, v82
	v_fmac_f32_e32 v15, v96, v83
	v_fmac_f32_e32 v16, v97, v80
	v_fmac_f32_e32 v17, v97, v81
	v_fmac_f32_e32 v18, v97, v82
	v_fmac_f32_e32 v19, v97, v83
	v_fmac_f32_e32 v20, v98, v80
	v_fmac_f32_e32 v21, v98, v81
	v_fmac_f32_e32 v22, v98, v82
	v_fmac_f32_e32 v23, v98, v83
	v_fmac_f32_e32 v24, v99, v80
	v_fmac_f32_e32 v25, v99, v81
	v_fmac_f32_e32 v26, v99, v82
	v_fmac_f32_e32 v27, v99, v83
	v_fmac_f32_e32 v28, v100, v80
	v_fmac_f32_e32 v29, v100, v81
	v_fmac_f32_e32 v30, v100, v82
	v_fmac_f32_e32 v31, v100, v83
	global_load_dwordx4 v[80:83], v11, s[10:11]
	s_add_u32 s10, s10, 0x18000
	s_addc_u32 s11, s11, 0
	ds_read_b32 v96, v10 offset:488
	ds_read_b32 v97, v10 offset:8680
	ds_read_b32 v98, v10 offset:16872
	ds_read_b32 v99, v10 offset:25064
	ds_read_b32 v100, v10 offset:33256
	s_waitcnt vmcnt(15) lgkmcnt(0)
	v_fmac_f32_e32 v12, v96, v84
	v_fmac_f32_e32 v13, v96, v85
	v_fmac_f32_e32 v14, v96, v86
	v_fmac_f32_e32 v15, v96, v87
	v_fmac_f32_e32 v16, v97, v84
	v_fmac_f32_e32 v17, v97, v85
	v_fmac_f32_e32 v18, v97, v86
	v_fmac_f32_e32 v19, v97, v87
	v_fmac_f32_e32 v20, v98, v84
	v_fmac_f32_e32 v21, v98, v85
	v_fmac_f32_e32 v22, v98, v86
	v_fmac_f32_e32 v23, v98, v87
	v_fmac_f32_e32 v24, v99, v84
	v_fmac_f32_e32 v25, v99, v85
	v_fmac_f32_e32 v26, v99, v86
	v_fmac_f32_e32 v27, v99, v87
	v_fmac_f32_e32 v28, v100, v84
	v_fmac_f32_e32 v29, v100, v85
	v_fmac_f32_e32 v30, v100, v86
	v_fmac_f32_e32 v31, v100, v87
	global_load_dwordx4 v[84:87], v11, s[10:11]
	s_add_u32 s10, s10, 0x18000
	s_addc_u32 s11, s11, 0
	ds_read_b32 v96, v10 offset:496
	ds_read_b32 v97, v10 offset:8688
	ds_read_b32 v98, v10 offset:16880
	ds_read_b32 v99, v10 offset:25072
	ds_read_b32 v100, v10 offset:33264
	s_waitcnt vmcnt(15) lgkmcnt(0)
	v_fmac_f32_e32 v12, v96, v88
	v_fmac_f32_e32 v13, v96, v89
	v_fmac_f32_e32 v14, v96, v90
	v_fmac_f32_e32 v15, v96, v91
	v_fmac_f32_e32 v16, v97, v88
	v_fmac_f32_e32 v17, v97, v89
	v_fmac_f32_e32 v18, v97, v90
	v_fmac_f32_e32 v19, v97, v91
	v_fmac_f32_e32 v20, v98, v88
	v_fmac_f32_e32 v21, v98, v89
	v_fmac_f32_e32 v22, v98, v90
	v_fmac_f32_e32 v23, v98, v91
	v_fmac_f32_e32 v24, v99, v88
	v_fmac_f32_e32 v25, v99, v89
	v_fmac_f32_e32 v26, v99, v90
	v_fmac_f32_e32 v27, v99, v91
	v_fmac_f32_e32 v28, v100, v88
	v_fmac_f32_e32 v29, v100, v89
	v_fmac_f32_e32 v30, v100, v90
	v_fmac_f32_e32 v31, v100, v91
	global_load_dwordx4 v[88:91], v11, s[10:11]
	s_add_u32 s10, s10, 0x18000
	s_addc_u32 s11, s11, 0
	ds_read_b32 v96, v10 offset:504
	ds_read_b32 v97, v10 offset:8696
	ds_read_b32 v98, v10 offset:16888
	ds_read_b32 v99, v10 offset:25080
	ds_read_b32 v100, v10 offset:33272
	s_waitcnt vmcnt(15) lgkmcnt(0)
	v_fmac_f32_e32 v12, v96, v92
	v_fmac_f32_e32 v13, v96, v93
	v_fmac_f32_e32 v14, v96, v94
	v_fmac_f32_e32 v15, v96, v95
	v_fmac_f32_e32 v16, v97, v92
	v_fmac_f32_e32 v17, v97, v93
	v_fmac_f32_e32 v18, v97, v94
	v_fmac_f32_e32 v19, v97, v95
	v_fmac_f32_e32 v20, v98, v92
	v_fmac_f32_e32 v21, v98, v93
	v_fmac_f32_e32 v22, v98, v94
	v_fmac_f32_e32 v23, v98, v95
	v_fmac_f32_e32 v24, v99, v92
	v_fmac_f32_e32 v25, v99, v93
	v_fmac_f32_e32 v26, v99, v94
	v_fmac_f32_e32 v27, v99, v95
	v_fmac_f32_e32 v28, v100, v92
	v_fmac_f32_e32 v29, v100, v93
	v_fmac_f32_e32 v30, v100, v94
	v_fmac_f32_e32 v31, v100, v95
	global_load_dwordx4 v[92:95], v11, s[10:11]
	s_add_u32 s10, s10, 0x18000
	s_addc_u32 s11, s11, 0
	ds_read_b32 v96, v10 offset:512
	ds_read_b32 v97, v10 offset:8704
	ds_read_b32 v98, v10 offset:16896
	ds_read_b32 v99, v10 offset:25088
	ds_read_b32 v100, v10 offset:33280
	s_waitcnt vmcnt(15) lgkmcnt(0)
	v_fmac_f32_e32 v12, v96, v32
	v_fmac_f32_e32 v13, v96, v33
	v_fmac_f32_e32 v14, v96, v34
	v_fmac_f32_e32 v15, v96, v35
	v_fmac_f32_e32 v16, v97, v32
	v_fmac_f32_e32 v17, v97, v33
	v_fmac_f32_e32 v18, v97, v34
	v_fmac_f32_e32 v19, v97, v35
	v_fmac_f32_e32 v20, v98, v32
	v_fmac_f32_e32 v21, v98, v33
	v_fmac_f32_e32 v22, v98, v34
	v_fmac_f32_e32 v23, v98, v35
	v_fmac_f32_e32 v24, v99, v32
	v_fmac_f32_e32 v25, v99, v33
	v_fmac_f32_e32 v26, v99, v34
	v_fmac_f32_e32 v27, v99, v35
	v_fmac_f32_e32 v28, v100, v32
	v_fmac_f32_e32 v29, v100, v33
	v_fmac_f32_e32 v30, v100, v34
	v_fmac_f32_e32 v31, v100, v35
	global_load_dwordx4 v[32:35], v11, s[10:11]
	s_add_u32 s10, s10, 0x18000
	s_addc_u32 s11, s11, 0
	ds_read_b32 v96, v10 offset:520
	ds_read_b32 v97, v10 offset:8712
	ds_read_b32 v98, v10 offset:16904
	ds_read_b32 v99, v10 offset:25096
	ds_read_b32 v100, v10 offset:33288
	s_waitcnt vmcnt(15) lgkmcnt(0)
	v_fmac_f32_e32 v12, v96, v36
	v_fmac_f32_e32 v13, v96, v37
	v_fmac_f32_e32 v14, v96, v38
	v_fmac_f32_e32 v15, v96, v39
	v_fmac_f32_e32 v16, v97, v36
	v_fmac_f32_e32 v17, v97, v37
	v_fmac_f32_e32 v18, v97, v38
	v_fmac_f32_e32 v19, v97, v39
	v_fmac_f32_e32 v20, v98, v36
	v_fmac_f32_e32 v21, v98, v37
	v_fmac_f32_e32 v22, v98, v38
	v_fmac_f32_e32 v23, v98, v39
	v_fmac_f32_e32 v24, v99, v36
	v_fmac_f32_e32 v25, v99, v37
	v_fmac_f32_e32 v26, v99, v38
	v_fmac_f32_e32 v27, v99, v39
	v_fmac_f32_e32 v28, v100, v36
	v_fmac_f32_e32 v29, v100, v37
	v_fmac_f32_e32 v30, v100, v38
	v_fmac_f32_e32 v31, v100, v39
	global_load_dwordx4 v[36:39], v11, s[10:11]
	s_add_u32 s10, s10, 0x18000
	s_addc_u32 s11, s11, 0
	ds_read_b32 v96, v10 offset:528
	ds_read_b32 v97, v10 offset:8720
	ds_read_b32 v98, v10 offset:16912
	ds_read_b32 v99, v10 offset:25104
	ds_read_b32 v100, v10 offset:33296
	s_waitcnt vmcnt(15) lgkmcnt(0)
	v_fmac_f32_e32 v12, v96, v40
	v_fmac_f32_e32 v13, v96, v41
	v_fmac_f32_e32 v14, v96, v42
	v_fmac_f32_e32 v15, v96, v43
	v_fmac_f32_e32 v16, v97, v40
	v_fmac_f32_e32 v17, v97, v41
	v_fmac_f32_e32 v18, v97, v42
	v_fmac_f32_e32 v19, v97, v43
	v_fmac_f32_e32 v20, v98, v40
	v_fmac_f32_e32 v21, v98, v41
	v_fmac_f32_e32 v22, v98, v42
	v_fmac_f32_e32 v23, v98, v43
	v_fmac_f32_e32 v24, v99, v40
	v_fmac_f32_e32 v25, v99, v41
	v_fmac_f32_e32 v26, v99, v42
	v_fmac_f32_e32 v27, v99, v43
	v_fmac_f32_e32 v28, v100, v40
	v_fmac_f32_e32 v29, v100, v41
	v_fmac_f32_e32 v30, v100, v42
	v_fmac_f32_e32 v31, v100, v43
	global_load_dwordx4 v[40:43], v11, s[10:11]
	s_add_u32 s10, s10, 0x18000
	s_addc_u32 s11, s11, 0
	ds_read_b32 v96, v10 offset:536
	ds_read_b32 v97, v10 offset:8728
	ds_read_b32 v98, v10 offset:16920
	ds_read_b32 v99, v10 offset:25112
	ds_read_b32 v100, v10 offset:33304
	s_waitcnt vmcnt(15) lgkmcnt(0)
	v_fmac_f32_e32 v12, v96, v44
	v_fmac_f32_e32 v13, v96, v45
	v_fmac_f32_e32 v14, v96, v46
	v_fmac_f32_e32 v15, v96, v47
	v_fmac_f32_e32 v16, v97, v44
	v_fmac_f32_e32 v17, v97, v45
	v_fmac_f32_e32 v18, v97, v46
	v_fmac_f32_e32 v19, v97, v47
	v_fmac_f32_e32 v20, v98, v44
	v_fmac_f32_e32 v21, v98, v45
	v_fmac_f32_e32 v22, v98, v46
	v_fmac_f32_e32 v23, v98, v47
	v_fmac_f32_e32 v24, v99, v44
	v_fmac_f32_e32 v25, v99, v45
	v_fmac_f32_e32 v26, v99, v46
	v_fmac_f32_e32 v27, v99, v47
	v_fmac_f32_e32 v28, v100, v44
	v_fmac_f32_e32 v29, v100, v45
	v_fmac_f32_e32 v30, v100, v46
	v_fmac_f32_e32 v31, v100, v47
	global_load_dwordx4 v[44:47], v11, s[10:11]
	s_add_u32 s10, s10, 0x18000
	s_addc_u32 s11, s11, 0
	ds_read_b32 v96, v10 offset:544
	ds_read_b32 v97, v10 offset:8736
	ds_read_b32 v98, v10 offset:16928
	ds_read_b32 v99, v10 offset:25120
	ds_read_b32 v100, v10 offset:33312
	s_waitcnt vmcnt(15) lgkmcnt(0)
	v_fmac_f32_e32 v12, v96, v48
	v_fmac_f32_e32 v13, v96, v49
	v_fmac_f32_e32 v14, v96, v50
	v_fmac_f32_e32 v15, v96, v51
	v_fmac_f32_e32 v16, v97, v48
	v_fmac_f32_e32 v17, v97, v49
	v_fmac_f32_e32 v18, v97, v50
	v_fmac_f32_e32 v19, v97, v51
	v_fmac_f32_e32 v20, v98, v48
	v_fmac_f32_e32 v21, v98, v49
	v_fmac_f32_e32 v22, v98, v50
	v_fmac_f32_e32 v23, v98, v51
	v_fmac_f32_e32 v24, v99, v48
	v_fmac_f32_e32 v25, v99, v49
	v_fmac_f32_e32 v26, v99, v50
	v_fmac_f32_e32 v27, v99, v51
	v_fmac_f32_e32 v28, v100, v48
	v_fmac_f32_e32 v29, v100, v49
	v_fmac_f32_e32 v30, v100, v50
	v_fmac_f32_e32 v31, v100, v51
	global_load_dwordx4 v[48:51], v11, s[10:11]
	s_add_u32 s10, s10, 0x18000
	s_addc_u32 s11, s11, 0
	ds_read_b32 v96, v10 offset:552
	ds_read_b32 v97, v10 offset:8744
	ds_read_b32 v98, v10 offset:16936
	ds_read_b32 v99, v10 offset:25128
	ds_read_b32 v100, v10 offset:33320
	s_waitcnt vmcnt(15) lgkmcnt(0)
	v_fmac_f32_e32 v12, v96, v52
	v_fmac_f32_e32 v13, v96, v53
	v_fmac_f32_e32 v14, v96, v54
	v_fmac_f32_e32 v15, v96, v55
	v_fmac_f32_e32 v16, v97, v52
	v_fmac_f32_e32 v17, v97, v53
	v_fmac_f32_e32 v18, v97, v54
	v_fmac_f32_e32 v19, v97, v55
	v_fmac_f32_e32 v20, v98, v52
	v_fmac_f32_e32 v21, v98, v53
	v_fmac_f32_e32 v22, v98, v54
	v_fmac_f32_e32 v23, v98, v55
	v_fmac_f32_e32 v24, v99, v52
	v_fmac_f32_e32 v25, v99, v53
	v_fmac_f32_e32 v26, v99, v54
	v_fmac_f32_e32 v27, v99, v55
	v_fmac_f32_e32 v28, v100, v52
	v_fmac_f32_e32 v29, v100, v53
	v_fmac_f32_e32 v30, v100, v54
	v_fmac_f32_e32 v31, v100, v55
	global_load_dwordx4 v[52:55], v11, s[10:11]
	s_add_u32 s10, s10, 0x18000
	s_addc_u32 s11, s11, 0
	ds_read_b32 v96, v10 offset:560
	ds_read_b32 v97, v10 offset:8752
	ds_read_b32 v98, v10 offset:16944
	ds_read_b32 v99, v10 offset:25136
	ds_read_b32 v100, v10 offset:33328
	s_waitcnt vmcnt(15) lgkmcnt(0)
	v_fmac_f32_e32 v12, v96, v56
	v_fmac_f32_e32 v13, v96, v57
	v_fmac_f32_e32 v14, v96, v58
	v_fmac_f32_e32 v15, v96, v59
	v_fmac_f32_e32 v16, v97, v56
	v_fmac_f32_e32 v17, v97, v57
	v_fmac_f32_e32 v18, v97, v58
	v_fmac_f32_e32 v19, v97, v59
	v_fmac_f32_e32 v20, v98, v56
	v_fmac_f32_e32 v21, v98, v57
	v_fmac_f32_e32 v22, v98, v58
	v_fmac_f32_e32 v23, v98, v59
	v_fmac_f32_e32 v24, v99, v56
	v_fmac_f32_e32 v25, v99, v57
	v_fmac_f32_e32 v26, v99, v58
	v_fmac_f32_e32 v27, v99, v59
	v_fmac_f32_e32 v28, v100, v56
	v_fmac_f32_e32 v29, v100, v57
	v_fmac_f32_e32 v30, v100, v58
	v_fmac_f32_e32 v31, v100, v59
	global_load_dwordx4 v[56:59], v11, s[10:11]
	s_add_u32 s10, s10, 0x18000
	s_addc_u32 s11, s11, 0
	ds_read_b32 v96, v10 offset:568
	ds_read_b32 v97, v10 offset:8760
	ds_read_b32 v98, v10 offset:16952
	ds_read_b32 v99, v10 offset:25144
	ds_read_b32 v100, v10 offset:33336
	s_waitcnt vmcnt(15) lgkmcnt(0)
	v_fmac_f32_e32 v12, v96, v60
	v_fmac_f32_e32 v13, v96, v61
	v_fmac_f32_e32 v14, v96, v62
	v_fmac_f32_e32 v15, v96, v63
	v_fmac_f32_e32 v16, v97, v60
	v_fmac_f32_e32 v17, v97, v61
	v_fmac_f32_e32 v18, v97, v62
	v_fmac_f32_e32 v19, v97, v63
	v_fmac_f32_e32 v20, v98, v60
	v_fmac_f32_e32 v21, v98, v61
	v_fmac_f32_e32 v22, v98, v62
	v_fmac_f32_e32 v23, v98, v63
	v_fmac_f32_e32 v24, v99, v60
	v_fmac_f32_e32 v25, v99, v61
	v_fmac_f32_e32 v26, v99, v62
	v_fmac_f32_e32 v27, v99, v63
	v_fmac_f32_e32 v28, v100, v60
	v_fmac_f32_e32 v29, v100, v61
	v_fmac_f32_e32 v30, v100, v62
	v_fmac_f32_e32 v31, v100, v63
	global_load_dwordx4 v[60:63], v11, s[10:11]
	s_add_u32 s10, s10, 0x18000
	s_addc_u32 s11, s11, 0
	ds_read_b32 v96, v10 offset:576
	ds_read_b32 v97, v10 offset:8768
	ds_read_b32 v98, v10 offset:16960
	ds_read_b32 v99, v10 offset:25152
	ds_read_b32 v100, v10 offset:33344
	s_waitcnt vmcnt(15) lgkmcnt(0)
	v_fmac_f32_e32 v12, v96, v64
	v_fmac_f32_e32 v13, v96, v65
	v_fmac_f32_e32 v14, v96, v66
	v_fmac_f32_e32 v15, v96, v67
	v_fmac_f32_e32 v16, v97, v64
	v_fmac_f32_e32 v17, v97, v65
	v_fmac_f32_e32 v18, v97, v66
	v_fmac_f32_e32 v19, v97, v67
	v_fmac_f32_e32 v20, v98, v64
	v_fmac_f32_e32 v21, v98, v65
	v_fmac_f32_e32 v22, v98, v66
	v_fmac_f32_e32 v23, v98, v67
	v_fmac_f32_e32 v24, v99, v64
	v_fmac_f32_e32 v25, v99, v65
	v_fmac_f32_e32 v26, v99, v66
	v_fmac_f32_e32 v27, v99, v67
	v_fmac_f32_e32 v28, v100, v64
	v_fmac_f32_e32 v29, v100, v65
	v_fmac_f32_e32 v30, v100, v66
	v_fmac_f32_e32 v31, v100, v67
	global_load_dwordx4 v[64:67], v11, s[10:11]
	s_add_u32 s10, s10, 0x18000
	s_addc_u32 s11, s11, 0
	ds_read_b32 v96, v10 offset:584
	ds_read_b32 v97, v10 offset:8776
	ds_read_b32 v98, v10 offset:16968
	ds_read_b32 v99, v10 offset:25160
	ds_read_b32 v100, v10 offset:33352
	s_waitcnt vmcnt(15) lgkmcnt(0)
	v_fmac_f32_e32 v12, v96, v68
	v_fmac_f32_e32 v13, v96, v69
	v_fmac_f32_e32 v14, v96, v70
	v_fmac_f32_e32 v15, v96, v71
	v_fmac_f32_e32 v16, v97, v68
	v_fmac_f32_e32 v17, v97, v69
	v_fmac_f32_e32 v18, v97, v70
	v_fmac_f32_e32 v19, v97, v71
	v_fmac_f32_e32 v20, v98, v68
	v_fmac_f32_e32 v21, v98, v69
	v_fmac_f32_e32 v22, v98, v70
	v_fmac_f32_e32 v23, v98, v71
	v_fmac_f32_e32 v24, v99, v68
	v_fmac_f32_e32 v25, v99, v69
	v_fmac_f32_e32 v26, v99, v70
	v_fmac_f32_e32 v27, v99, v71
	v_fmac_f32_e32 v28, v100, v68
	v_fmac_f32_e32 v29, v100, v69
	v_fmac_f32_e32 v30, v100, v70
	v_fmac_f32_e32 v31, v100, v71
	global_load_dwordx4 v[68:71], v11, s[10:11]
	s_add_u32 s10, s10, 0x18000
	s_addc_u32 s11, s11, 0
	ds_read_b32 v96, v10 offset:592
	ds_read_b32 v97, v10 offset:8784
	ds_read_b32 v98, v10 offset:16976
	ds_read_b32 v99, v10 offset:25168
	ds_read_b32 v100, v10 offset:33360
	s_waitcnt vmcnt(15) lgkmcnt(0)
	v_fmac_f32_e32 v12, v96, v72
	v_fmac_f32_e32 v13, v96, v73
	v_fmac_f32_e32 v14, v96, v74
	v_fmac_f32_e32 v15, v96, v75
	v_fmac_f32_e32 v16, v97, v72
	v_fmac_f32_e32 v17, v97, v73
	v_fmac_f32_e32 v18, v97, v74
	v_fmac_f32_e32 v19, v97, v75
	v_fmac_f32_e32 v20, v98, v72
	v_fmac_f32_e32 v21, v98, v73
	v_fmac_f32_e32 v22, v98, v74
	v_fmac_f32_e32 v23, v98, v75
	v_fmac_f32_e32 v24, v99, v72
	v_fmac_f32_e32 v25, v99, v73
	v_fmac_f32_e32 v26, v99, v74
	v_fmac_f32_e32 v27, v99, v75
	v_fmac_f32_e32 v28, v100, v72
	v_fmac_f32_e32 v29, v100, v73
	v_fmac_f32_e32 v30, v100, v74
	v_fmac_f32_e32 v31, v100, v75
	global_load_dwordx4 v[72:75], v11, s[10:11]
	s_add_u32 s10, s10, 0x18000
	s_addc_u32 s11, s11, 0
	ds_read_b32 v96, v10 offset:600
	ds_read_b32 v97, v10 offset:8792
	ds_read_b32 v98, v10 offset:16984
	ds_read_b32 v99, v10 offset:25176
	ds_read_b32 v100, v10 offset:33368
	s_waitcnt vmcnt(15) lgkmcnt(0)
	v_fmac_f32_e32 v12, v96, v76
	v_fmac_f32_e32 v13, v96, v77
	v_fmac_f32_e32 v14, v96, v78
	v_fmac_f32_e32 v15, v96, v79
	v_fmac_f32_e32 v16, v97, v76
	v_fmac_f32_e32 v17, v97, v77
	v_fmac_f32_e32 v18, v97, v78
	v_fmac_f32_e32 v19, v97, v79
	v_fmac_f32_e32 v20, v98, v76
	v_fmac_f32_e32 v21, v98, v77
	v_fmac_f32_e32 v22, v98, v78
	v_fmac_f32_e32 v23, v98, v79
	v_fmac_f32_e32 v24, v99, v76
	v_fmac_f32_e32 v25, v99, v77
	v_fmac_f32_e32 v26, v99, v78
	v_fmac_f32_e32 v27, v99, v79
	v_fmac_f32_e32 v28, v100, v76
	v_fmac_f32_e32 v29, v100, v77
	v_fmac_f32_e32 v30, v100, v78
	v_fmac_f32_e32 v31, v100, v79
	global_load_dwordx4 v[76:79], v11, s[10:11]
	s_add_u32 s10, s10, 0x18000
	s_addc_u32 s11, s11, 0
	ds_read_b32 v96, v10 offset:608
	ds_read_b32 v97, v10 offset:8800
	ds_read_b32 v98, v10 offset:16992
	ds_read_b32 v99, v10 offset:25184
	ds_read_b32 v100, v10 offset:33376
	s_waitcnt vmcnt(15) lgkmcnt(0)
	v_fmac_f32_e32 v12, v96, v80
	v_fmac_f32_e32 v13, v96, v81
	v_fmac_f32_e32 v14, v96, v82
	v_fmac_f32_e32 v15, v96, v83
	v_fmac_f32_e32 v16, v97, v80
	v_fmac_f32_e32 v17, v97, v81
	v_fmac_f32_e32 v18, v97, v82
	v_fmac_f32_e32 v19, v97, v83
	v_fmac_f32_e32 v20, v98, v80
	v_fmac_f32_e32 v21, v98, v81
	v_fmac_f32_e32 v22, v98, v82
	v_fmac_f32_e32 v23, v98, v83
	v_fmac_f32_e32 v24, v99, v80
	v_fmac_f32_e32 v25, v99, v81
	v_fmac_f32_e32 v26, v99, v82
	v_fmac_f32_e32 v27, v99, v83
	v_fmac_f32_e32 v28, v100, v80
	v_fmac_f32_e32 v29, v100, v81
	v_fmac_f32_e32 v30, v100, v82
	v_fmac_f32_e32 v31, v100, v83
	global_load_dwordx4 v[80:83], v11, s[10:11]
	s_add_u32 s10, s10, 0x18000
	s_addc_u32 s11, s11, 0
	ds_read_b32 v96, v10 offset:616
	ds_read_b32 v97, v10 offset:8808
	ds_read_b32 v98, v10 offset:17000
	ds_read_b32 v99, v10 offset:25192
	ds_read_b32 v100, v10 offset:33384
	s_waitcnt vmcnt(15) lgkmcnt(0)
	v_fmac_f32_e32 v12, v96, v84
	v_fmac_f32_e32 v13, v96, v85
	v_fmac_f32_e32 v14, v96, v86
	v_fmac_f32_e32 v15, v96, v87
	v_fmac_f32_e32 v16, v97, v84
	v_fmac_f32_e32 v17, v97, v85
	v_fmac_f32_e32 v18, v97, v86
	v_fmac_f32_e32 v19, v97, v87
	v_fmac_f32_e32 v20, v98, v84
	v_fmac_f32_e32 v21, v98, v85
	v_fmac_f32_e32 v22, v98, v86
	v_fmac_f32_e32 v23, v98, v87
	v_fmac_f32_e32 v24, v99, v84
	v_fmac_f32_e32 v25, v99, v85
	v_fmac_f32_e32 v26, v99, v86
	v_fmac_f32_e32 v27, v99, v87
	v_fmac_f32_e32 v28, v100, v84
	v_fmac_f32_e32 v29, v100, v85
	v_fmac_f32_e32 v30, v100, v86
	v_fmac_f32_e32 v31, v100, v87
	global_load_dwordx4 v[84:87], v11, s[10:11]
	s_add_u32 s10, s10, 0x18000
	s_addc_u32 s11, s11, 0
	ds_read_b32 v96, v10 offset:624
	ds_read_b32 v97, v10 offset:8816
	ds_read_b32 v98, v10 offset:17008
	ds_read_b32 v99, v10 offset:25200
	ds_read_b32 v100, v10 offset:33392
	s_waitcnt vmcnt(15) lgkmcnt(0)
	v_fmac_f32_e32 v12, v96, v88
	v_fmac_f32_e32 v13, v96, v89
	v_fmac_f32_e32 v14, v96, v90
	v_fmac_f32_e32 v15, v96, v91
	v_fmac_f32_e32 v16, v97, v88
	v_fmac_f32_e32 v17, v97, v89
	v_fmac_f32_e32 v18, v97, v90
	v_fmac_f32_e32 v19, v97, v91
	v_fmac_f32_e32 v20, v98, v88
	v_fmac_f32_e32 v21, v98, v89
	v_fmac_f32_e32 v22, v98, v90
	v_fmac_f32_e32 v23, v98, v91
	v_fmac_f32_e32 v24, v99, v88
	v_fmac_f32_e32 v25, v99, v89
	v_fmac_f32_e32 v26, v99, v90
	v_fmac_f32_e32 v27, v99, v91
	v_fmac_f32_e32 v28, v100, v88
	v_fmac_f32_e32 v29, v100, v89
	v_fmac_f32_e32 v30, v100, v90
	v_fmac_f32_e32 v31, v100, v91
	global_load_dwordx4 v[88:91], v11, s[10:11]
	s_add_u32 s10, s10, 0x18000
	s_addc_u32 s11, s11, 0
	ds_read_b32 v96, v10 offset:632
	ds_read_b32 v97, v10 offset:8824
	ds_read_b32 v98, v10 offset:17016
	ds_read_b32 v99, v10 offset:25208
	ds_read_b32 v100, v10 offset:33400
	s_waitcnt vmcnt(15) lgkmcnt(0)
	v_fmac_f32_e32 v12, v96, v92
	v_fmac_f32_e32 v13, v96, v93
	v_fmac_f32_e32 v14, v96, v94
	v_fmac_f32_e32 v15, v96, v95
	v_fmac_f32_e32 v16, v97, v92
	v_fmac_f32_e32 v17, v97, v93
	v_fmac_f32_e32 v18, v97, v94
	v_fmac_f32_e32 v19, v97, v95
	v_fmac_f32_e32 v20, v98, v92
	v_fmac_f32_e32 v21, v98, v93
	v_fmac_f32_e32 v22, v98, v94
	v_fmac_f32_e32 v23, v98, v95
	v_fmac_f32_e32 v24, v99, v92
	v_fmac_f32_e32 v25, v99, v93
	v_fmac_f32_e32 v26, v99, v94
	v_fmac_f32_e32 v27, v99, v95
	v_fmac_f32_e32 v28, v100, v92
	v_fmac_f32_e32 v29, v100, v93
	v_fmac_f32_e32 v30, v100, v94
	v_fmac_f32_e32 v31, v100, v95
	global_load_dwordx4 v[92:95], v11, s[10:11]
	s_add_u32 s10, s10, 0x18000
	s_addc_u32 s11, s11, 0
	ds_read_b32 v96, v10 offset:640
	ds_read_b32 v97, v10 offset:8832
	ds_read_b32 v98, v10 offset:17024
	ds_read_b32 v99, v10 offset:25216
	ds_read_b32 v100, v10 offset:33408
	s_waitcnt vmcnt(15) lgkmcnt(0)
	v_fmac_f32_e32 v12, v96, v32
	v_fmac_f32_e32 v13, v96, v33
	v_fmac_f32_e32 v14, v96, v34
	v_fmac_f32_e32 v15, v96, v35
	v_fmac_f32_e32 v16, v97, v32
	v_fmac_f32_e32 v17, v97, v33
	v_fmac_f32_e32 v18, v97, v34
	v_fmac_f32_e32 v19, v97, v35
	v_fmac_f32_e32 v20, v98, v32
	v_fmac_f32_e32 v21, v98, v33
	v_fmac_f32_e32 v22, v98, v34
	v_fmac_f32_e32 v23, v98, v35
	v_fmac_f32_e32 v24, v99, v32
	v_fmac_f32_e32 v25, v99, v33
	v_fmac_f32_e32 v26, v99, v34
	v_fmac_f32_e32 v27, v99, v35
	v_fmac_f32_e32 v28, v100, v32
	v_fmac_f32_e32 v29, v100, v33
	v_fmac_f32_e32 v30, v100, v34
	v_fmac_f32_e32 v31, v100, v35
	global_load_dwordx4 v[32:35], v11, s[10:11]
	s_add_u32 s10, s10, 0x18000
	s_addc_u32 s11, s11, 0
	ds_read_b32 v96, v10 offset:648
	ds_read_b32 v97, v10 offset:8840
	ds_read_b32 v98, v10 offset:17032
	ds_read_b32 v99, v10 offset:25224
	ds_read_b32 v100, v10 offset:33416
	s_waitcnt vmcnt(15) lgkmcnt(0)
	v_fmac_f32_e32 v12, v96, v36
	v_fmac_f32_e32 v13, v96, v37
	v_fmac_f32_e32 v14, v96, v38
	v_fmac_f32_e32 v15, v96, v39
	v_fmac_f32_e32 v16, v97, v36
	v_fmac_f32_e32 v17, v97, v37
	v_fmac_f32_e32 v18, v97, v38
	v_fmac_f32_e32 v19, v97, v39
	v_fmac_f32_e32 v20, v98, v36
	v_fmac_f32_e32 v21, v98, v37
	v_fmac_f32_e32 v22, v98, v38
	v_fmac_f32_e32 v23, v98, v39
	v_fmac_f32_e32 v24, v99, v36
	v_fmac_f32_e32 v25, v99, v37
	v_fmac_f32_e32 v26, v99, v38
	v_fmac_f32_e32 v27, v99, v39
	v_fmac_f32_e32 v28, v100, v36
	v_fmac_f32_e32 v29, v100, v37
	v_fmac_f32_e32 v30, v100, v38
	v_fmac_f32_e32 v31, v100, v39
	global_load_dwordx4 v[36:39], v11, s[10:11]
	s_add_u32 s10, s10, 0x18000
	s_addc_u32 s11, s11, 0
	ds_read_b32 v96, v10 offset:656
	ds_read_b32 v97, v10 offset:8848
	ds_read_b32 v98, v10 offset:17040
	ds_read_b32 v99, v10 offset:25232
	ds_read_b32 v100, v10 offset:33424
	s_waitcnt vmcnt(15) lgkmcnt(0)
	v_fmac_f32_e32 v12, v96, v40
	v_fmac_f32_e32 v13, v96, v41
	v_fmac_f32_e32 v14, v96, v42
	v_fmac_f32_e32 v15, v96, v43
	v_fmac_f32_e32 v16, v97, v40
	v_fmac_f32_e32 v17, v97, v41
	v_fmac_f32_e32 v18, v97, v42
	v_fmac_f32_e32 v19, v97, v43
	v_fmac_f32_e32 v20, v98, v40
	v_fmac_f32_e32 v21, v98, v41
	v_fmac_f32_e32 v22, v98, v42
	v_fmac_f32_e32 v23, v98, v43
	v_fmac_f32_e32 v24, v99, v40
	v_fmac_f32_e32 v25, v99, v41
	v_fmac_f32_e32 v26, v99, v42
	v_fmac_f32_e32 v27, v99, v43
	v_fmac_f32_e32 v28, v100, v40
	v_fmac_f32_e32 v29, v100, v41
	v_fmac_f32_e32 v30, v100, v42
	v_fmac_f32_e32 v31, v100, v43
	global_load_dwordx4 v[40:43], v11, s[10:11]
	s_add_u32 s10, s10, 0x18000
	s_addc_u32 s11, s11, 0
	ds_read_b32 v96, v10 offset:664
	ds_read_b32 v97, v10 offset:8856
	ds_read_b32 v98, v10 offset:17048
	ds_read_b32 v99, v10 offset:25240
	ds_read_b32 v100, v10 offset:33432
	s_waitcnt vmcnt(15) lgkmcnt(0)
	v_fmac_f32_e32 v12, v96, v44
	v_fmac_f32_e32 v13, v96, v45
	v_fmac_f32_e32 v14, v96, v46
	v_fmac_f32_e32 v15, v96, v47
	v_fmac_f32_e32 v16, v97, v44
	v_fmac_f32_e32 v17, v97, v45
	v_fmac_f32_e32 v18, v97, v46
	v_fmac_f32_e32 v19, v97, v47
	v_fmac_f32_e32 v20, v98, v44
	v_fmac_f32_e32 v21, v98, v45
	v_fmac_f32_e32 v22, v98, v46
	v_fmac_f32_e32 v23, v98, v47
	v_fmac_f32_e32 v24, v99, v44
	v_fmac_f32_e32 v25, v99, v45
	v_fmac_f32_e32 v26, v99, v46
	v_fmac_f32_e32 v27, v99, v47
	v_fmac_f32_e32 v28, v100, v44
	v_fmac_f32_e32 v29, v100, v45
	v_fmac_f32_e32 v30, v100, v46
	v_fmac_f32_e32 v31, v100, v47
	global_load_dwordx4 v[44:47], v11, s[10:11]
	s_add_u32 s10, s10, 0x18000
	s_addc_u32 s11, s11, 0
	ds_read_b32 v96, v10 offset:672
	ds_read_b32 v97, v10 offset:8864
	ds_read_b32 v98, v10 offset:17056
	ds_read_b32 v99, v10 offset:25248
	ds_read_b32 v100, v10 offset:33440
	s_waitcnt vmcnt(15) lgkmcnt(0)
	v_fmac_f32_e32 v12, v96, v48
	v_fmac_f32_e32 v13, v96, v49
	v_fmac_f32_e32 v14, v96, v50
	v_fmac_f32_e32 v15, v96, v51
	v_fmac_f32_e32 v16, v97, v48
	v_fmac_f32_e32 v17, v97, v49
	v_fmac_f32_e32 v18, v97, v50
	v_fmac_f32_e32 v19, v97, v51
	v_fmac_f32_e32 v20, v98, v48
	v_fmac_f32_e32 v21, v98, v49
	v_fmac_f32_e32 v22, v98, v50
	v_fmac_f32_e32 v23, v98, v51
	v_fmac_f32_e32 v24, v99, v48
	v_fmac_f32_e32 v25, v99, v49
	v_fmac_f32_e32 v26, v99, v50
	v_fmac_f32_e32 v27, v99, v51
	v_fmac_f32_e32 v28, v100, v48
	v_fmac_f32_e32 v29, v100, v49
	v_fmac_f32_e32 v30, v100, v50
	v_fmac_f32_e32 v31, v100, v51
	global_load_dwordx4 v[48:51], v11, s[10:11]
	s_add_u32 s10, s10, 0x18000
	s_addc_u32 s11, s11, 0
	ds_read_b32 v96, v10 offset:680
	ds_read_b32 v97, v10 offset:8872
	ds_read_b32 v98, v10 offset:17064
	ds_read_b32 v99, v10 offset:25256
	ds_read_b32 v100, v10 offset:33448
	s_waitcnt vmcnt(15) lgkmcnt(0)
	v_fmac_f32_e32 v12, v96, v52
	v_fmac_f32_e32 v13, v96, v53
	v_fmac_f32_e32 v14, v96, v54
	v_fmac_f32_e32 v15, v96, v55
	v_fmac_f32_e32 v16, v97, v52
	v_fmac_f32_e32 v17, v97, v53
	v_fmac_f32_e32 v18, v97, v54
	v_fmac_f32_e32 v19, v97, v55
	v_fmac_f32_e32 v20, v98, v52
	v_fmac_f32_e32 v21, v98, v53
	v_fmac_f32_e32 v22, v98, v54
	v_fmac_f32_e32 v23, v98, v55
	v_fmac_f32_e32 v24, v99, v52
	v_fmac_f32_e32 v25, v99, v53
	v_fmac_f32_e32 v26, v99, v54
	v_fmac_f32_e32 v27, v99, v55
	v_fmac_f32_e32 v28, v100, v52
	v_fmac_f32_e32 v29, v100, v53
	v_fmac_f32_e32 v30, v100, v54
	v_fmac_f32_e32 v31, v100, v55
	global_load_dwordx4 v[52:55], v11, s[10:11]
	s_add_u32 s10, s10, 0x18000
	s_addc_u32 s11, s11, 0
	ds_read_b32 v96, v10 offset:688
	ds_read_b32 v97, v10 offset:8880
	ds_read_b32 v98, v10 offset:17072
	ds_read_b32 v99, v10 offset:25264
	ds_read_b32 v100, v10 offset:33456
	s_waitcnt vmcnt(15) lgkmcnt(0)
	v_fmac_f32_e32 v12, v96, v56
	v_fmac_f32_e32 v13, v96, v57
	v_fmac_f32_e32 v14, v96, v58
	v_fmac_f32_e32 v15, v96, v59
	v_fmac_f32_e32 v16, v97, v56
	v_fmac_f32_e32 v17, v97, v57
	v_fmac_f32_e32 v18, v97, v58
	v_fmac_f32_e32 v19, v97, v59
	v_fmac_f32_e32 v20, v98, v56
	v_fmac_f32_e32 v21, v98, v57
	v_fmac_f32_e32 v22, v98, v58
	v_fmac_f32_e32 v23, v98, v59
	v_fmac_f32_e32 v24, v99, v56
	v_fmac_f32_e32 v25, v99, v57
	v_fmac_f32_e32 v26, v99, v58
	v_fmac_f32_e32 v27, v99, v59
	v_fmac_f32_e32 v28, v100, v56
	v_fmac_f32_e32 v29, v100, v57
	v_fmac_f32_e32 v30, v100, v58
	v_fmac_f32_e32 v31, v100, v59
	global_load_dwordx4 v[56:59], v11, s[10:11]
	s_add_u32 s10, s10, 0x18000
	s_addc_u32 s11, s11, 0
	ds_read_b32 v96, v10 offset:696
	ds_read_b32 v97, v10 offset:8888
	ds_read_b32 v98, v10 offset:17080
	ds_read_b32 v99, v10 offset:25272
	ds_read_b32 v100, v10 offset:33464
	s_waitcnt vmcnt(15) lgkmcnt(0)
	v_fmac_f32_e32 v12, v96, v60
	v_fmac_f32_e32 v13, v96, v61
	v_fmac_f32_e32 v14, v96, v62
	v_fmac_f32_e32 v15, v96, v63
	v_fmac_f32_e32 v16, v97, v60
	v_fmac_f32_e32 v17, v97, v61
	v_fmac_f32_e32 v18, v97, v62
	v_fmac_f32_e32 v19, v97, v63
	v_fmac_f32_e32 v20, v98, v60
	v_fmac_f32_e32 v21, v98, v61
	v_fmac_f32_e32 v22, v98, v62
	v_fmac_f32_e32 v23, v98, v63
	v_fmac_f32_e32 v24, v99, v60
	v_fmac_f32_e32 v25, v99, v61
	v_fmac_f32_e32 v26, v99, v62
	v_fmac_f32_e32 v27, v99, v63
	v_fmac_f32_e32 v28, v100, v60
	v_fmac_f32_e32 v29, v100, v61
	v_fmac_f32_e32 v30, v100, v62
	v_fmac_f32_e32 v31, v100, v63
	global_load_dwordx4 v[60:63], v11, s[10:11]
	s_add_u32 s10, s10, 0x18000
	s_addc_u32 s11, s11, 0
	ds_read_b32 v96, v10 offset:704
	ds_read_b32 v97, v10 offset:8896
	ds_read_b32 v98, v10 offset:17088
	ds_read_b32 v99, v10 offset:25280
	ds_read_b32 v100, v10 offset:33472
	s_waitcnt vmcnt(15) lgkmcnt(0)
	v_fmac_f32_e32 v12, v96, v64
	v_fmac_f32_e32 v13, v96, v65
	v_fmac_f32_e32 v14, v96, v66
	v_fmac_f32_e32 v15, v96, v67
	v_fmac_f32_e32 v16, v97, v64
	v_fmac_f32_e32 v17, v97, v65
	v_fmac_f32_e32 v18, v97, v66
	v_fmac_f32_e32 v19, v97, v67
	v_fmac_f32_e32 v20, v98, v64
	v_fmac_f32_e32 v21, v98, v65
	v_fmac_f32_e32 v22, v98, v66
	v_fmac_f32_e32 v23, v98, v67
	v_fmac_f32_e32 v24, v99, v64
	v_fmac_f32_e32 v25, v99, v65
	v_fmac_f32_e32 v26, v99, v66
	v_fmac_f32_e32 v27, v99, v67
	v_fmac_f32_e32 v28, v100, v64
	v_fmac_f32_e32 v29, v100, v65
	v_fmac_f32_e32 v30, v100, v66
	v_fmac_f32_e32 v31, v100, v67
	global_load_dwordx4 v[64:67], v11, s[10:11]
	s_add_u32 s10, s10, 0x18000
	s_addc_u32 s11, s11, 0
	ds_read_b32 v96, v10 offset:712
	ds_read_b32 v97, v10 offset:8904
	ds_read_b32 v98, v10 offset:17096
	ds_read_b32 v99, v10 offset:25288
	ds_read_b32 v100, v10 offset:33480
	s_waitcnt vmcnt(15) lgkmcnt(0)
	v_fmac_f32_e32 v12, v96, v68
	v_fmac_f32_e32 v13, v96, v69
	v_fmac_f32_e32 v14, v96, v70
	v_fmac_f32_e32 v15, v96, v71
	v_fmac_f32_e32 v16, v97, v68
	v_fmac_f32_e32 v17, v97, v69
	v_fmac_f32_e32 v18, v97, v70
	v_fmac_f32_e32 v19, v97, v71
	v_fmac_f32_e32 v20, v98, v68
	v_fmac_f32_e32 v21, v98, v69
	v_fmac_f32_e32 v22, v98, v70
	v_fmac_f32_e32 v23, v98, v71
	v_fmac_f32_e32 v24, v99, v68
	v_fmac_f32_e32 v25, v99, v69
	v_fmac_f32_e32 v26, v99, v70
	v_fmac_f32_e32 v27, v99, v71
	v_fmac_f32_e32 v28, v100, v68
	v_fmac_f32_e32 v29, v100, v69
	v_fmac_f32_e32 v30, v100, v70
	v_fmac_f32_e32 v31, v100, v71
	global_load_dwordx4 v[68:71], v11, s[10:11]
	s_add_u32 s10, s10, 0x18000
	s_addc_u32 s11, s11, 0
	ds_read_b32 v96, v10 offset:720
	ds_read_b32 v97, v10 offset:8912
	ds_read_b32 v98, v10 offset:17104
	ds_read_b32 v99, v10 offset:25296
	ds_read_b32 v100, v10 offset:33488
	s_waitcnt vmcnt(15) lgkmcnt(0)
	v_fmac_f32_e32 v12, v96, v72
	v_fmac_f32_e32 v13, v96, v73
	v_fmac_f32_e32 v14, v96, v74
	v_fmac_f32_e32 v15, v96, v75
	v_fmac_f32_e32 v16, v97, v72
	v_fmac_f32_e32 v17, v97, v73
	v_fmac_f32_e32 v18, v97, v74
	v_fmac_f32_e32 v19, v97, v75
	v_fmac_f32_e32 v20, v98, v72
	v_fmac_f32_e32 v21, v98, v73
	v_fmac_f32_e32 v22, v98, v74
	v_fmac_f32_e32 v23, v98, v75
	v_fmac_f32_e32 v24, v99, v72
	v_fmac_f32_e32 v25, v99, v73
	v_fmac_f32_e32 v26, v99, v74
	v_fmac_f32_e32 v27, v99, v75
	v_fmac_f32_e32 v28, v100, v72
	v_fmac_f32_e32 v29, v100, v73
	v_fmac_f32_e32 v30, v100, v74
	v_fmac_f32_e32 v31, v100, v75
	global_load_dwordx4 v[72:75], v11, s[10:11]
	s_add_u32 s10, s10, 0x18000
	s_addc_u32 s11, s11, 0
	ds_read_b32 v96, v10 offset:728
	ds_read_b32 v97, v10 offset:8920
	ds_read_b32 v98, v10 offset:17112
	ds_read_b32 v99, v10 offset:25304
	ds_read_b32 v100, v10 offset:33496
	s_waitcnt vmcnt(15) lgkmcnt(0)
	v_fmac_f32_e32 v12, v96, v76
	v_fmac_f32_e32 v13, v96, v77
	v_fmac_f32_e32 v14, v96, v78
	v_fmac_f32_e32 v15, v96, v79
	v_fmac_f32_e32 v16, v97, v76
	v_fmac_f32_e32 v17, v97, v77
	v_fmac_f32_e32 v18, v97, v78
	v_fmac_f32_e32 v19, v97, v79
	v_fmac_f32_e32 v20, v98, v76
	v_fmac_f32_e32 v21, v98, v77
	v_fmac_f32_e32 v22, v98, v78
	v_fmac_f32_e32 v23, v98, v79
	v_fmac_f32_e32 v24, v99, v76
	v_fmac_f32_e32 v25, v99, v77
	v_fmac_f32_e32 v26, v99, v78
	v_fmac_f32_e32 v27, v99, v79
	v_fmac_f32_e32 v28, v100, v76
	v_fmac_f32_e32 v29, v100, v77
	v_fmac_f32_e32 v30, v100, v78
	v_fmac_f32_e32 v31, v100, v79
	global_load_dwordx4 v[76:79], v11, s[10:11]
	s_add_u32 s10, s10, 0x18000
	s_addc_u32 s11, s11, 0
	ds_read_b32 v96, v10 offset:736
	ds_read_b32 v97, v10 offset:8928
	ds_read_b32 v98, v10 offset:17120
	ds_read_b32 v99, v10 offset:25312
	ds_read_b32 v100, v10 offset:33504
	s_waitcnt vmcnt(15) lgkmcnt(0)
	v_fmac_f32_e32 v12, v96, v80
	v_fmac_f32_e32 v13, v96, v81
	v_fmac_f32_e32 v14, v96, v82
	v_fmac_f32_e32 v15, v96, v83
	v_fmac_f32_e32 v16, v97, v80
	v_fmac_f32_e32 v17, v97, v81
	v_fmac_f32_e32 v18, v97, v82
	v_fmac_f32_e32 v19, v97, v83
	v_fmac_f32_e32 v20, v98, v80
	v_fmac_f32_e32 v21, v98, v81
	v_fmac_f32_e32 v22, v98, v82
	v_fmac_f32_e32 v23, v98, v83
	v_fmac_f32_e32 v24, v99, v80
	v_fmac_f32_e32 v25, v99, v81
	v_fmac_f32_e32 v26, v99, v82
	v_fmac_f32_e32 v27, v99, v83
	v_fmac_f32_e32 v28, v100, v80
	v_fmac_f32_e32 v29, v100, v81
	v_fmac_f32_e32 v30, v100, v82
	v_fmac_f32_e32 v31, v100, v83
	global_load_dwordx4 v[80:83], v11, s[10:11]
	s_add_u32 s10, s10, 0x18000
	s_addc_u32 s11, s11, 0
	ds_read_b32 v96, v10 offset:744
	ds_read_b32 v97, v10 offset:8936
	ds_read_b32 v98, v10 offset:17128
	ds_read_b32 v99, v10 offset:25320
	ds_read_b32 v100, v10 offset:33512
	s_waitcnt vmcnt(15) lgkmcnt(0)
	v_fmac_f32_e32 v12, v96, v84
	v_fmac_f32_e32 v13, v96, v85
	v_fmac_f32_e32 v14, v96, v86
	v_fmac_f32_e32 v15, v96, v87
	v_fmac_f32_e32 v16, v97, v84
	v_fmac_f32_e32 v17, v97, v85
	v_fmac_f32_e32 v18, v97, v86
	v_fmac_f32_e32 v19, v97, v87
	v_fmac_f32_e32 v20, v98, v84
	v_fmac_f32_e32 v21, v98, v85
	v_fmac_f32_e32 v22, v98, v86
	v_fmac_f32_e32 v23, v98, v87
	v_fmac_f32_e32 v24, v99, v84
	v_fmac_f32_e32 v25, v99, v85
	v_fmac_f32_e32 v26, v99, v86
	v_fmac_f32_e32 v27, v99, v87
	v_fmac_f32_e32 v28, v100, v84
	v_fmac_f32_e32 v29, v100, v85
	v_fmac_f32_e32 v30, v100, v86
	v_fmac_f32_e32 v31, v100, v87
	global_load_dwordx4 v[84:87], v11, s[10:11]
	s_add_u32 s10, s10, 0x18000
	s_addc_u32 s11, s11, 0
	ds_read_b32 v96, v10 offset:752
	ds_read_b32 v97, v10 offset:8944
	ds_read_b32 v98, v10 offset:17136
	ds_read_b32 v99, v10 offset:25328
	ds_read_b32 v100, v10 offset:33520
	s_waitcnt vmcnt(15) lgkmcnt(0)
	v_fmac_f32_e32 v12, v96, v88
	v_fmac_f32_e32 v13, v96, v89
	v_fmac_f32_e32 v14, v96, v90
	v_fmac_f32_e32 v15, v96, v91
	v_fmac_f32_e32 v16, v97, v88
	v_fmac_f32_e32 v17, v97, v89
	v_fmac_f32_e32 v18, v97, v90
	v_fmac_f32_e32 v19, v97, v91
	v_fmac_f32_e32 v20, v98, v88
	v_fmac_f32_e32 v21, v98, v89
	v_fmac_f32_e32 v22, v98, v90
	v_fmac_f32_e32 v23, v98, v91
	v_fmac_f32_e32 v24, v99, v88
	v_fmac_f32_e32 v25, v99, v89
	v_fmac_f32_e32 v26, v99, v90
	v_fmac_f32_e32 v27, v99, v91
	v_fmac_f32_e32 v28, v100, v88
	v_fmac_f32_e32 v29, v100, v89
	v_fmac_f32_e32 v30, v100, v90
	v_fmac_f32_e32 v31, v100, v91
	global_load_dwordx4 v[88:91], v11, s[10:11]
	s_add_u32 s10, s10, 0x18000
	s_addc_u32 s11, s11, 0
	ds_read_b32 v96, v10 offset:760
	ds_read_b32 v97, v10 offset:8952
	ds_read_b32 v98, v10 offset:17144
	ds_read_b32 v99, v10 offset:25336
	ds_read_b32 v100, v10 offset:33528
	s_waitcnt vmcnt(15) lgkmcnt(0)
	v_fmac_f32_e32 v12, v96, v92
	v_fmac_f32_e32 v13, v96, v93
	v_fmac_f32_e32 v14, v96, v94
	v_fmac_f32_e32 v15, v96, v95
	v_fmac_f32_e32 v16, v97, v92
	v_fmac_f32_e32 v17, v97, v93
	v_fmac_f32_e32 v18, v97, v94
	v_fmac_f32_e32 v19, v97, v95
	v_fmac_f32_e32 v20, v98, v92
	v_fmac_f32_e32 v21, v98, v93
	v_fmac_f32_e32 v22, v98, v94
	v_fmac_f32_e32 v23, v98, v95
	v_fmac_f32_e32 v24, v99, v92
	v_fmac_f32_e32 v25, v99, v93
	v_fmac_f32_e32 v26, v99, v94
	v_fmac_f32_e32 v27, v99, v95
	v_fmac_f32_e32 v28, v100, v92
	v_fmac_f32_e32 v29, v100, v93
	v_fmac_f32_e32 v30, v100, v94
	v_fmac_f32_e32 v31, v100, v95
	global_load_dwordx4 v[92:95], v11, s[10:11]
	s_add_u32 s10, s10, 0x18000
	s_addc_u32 s11, s11, 0
	ds_read_b32 v96, v10 offset:768
	ds_read_b32 v97, v10 offset:8960
	ds_read_b32 v98, v10 offset:17152
	ds_read_b32 v99, v10 offset:25344
	ds_read_b32 v100, v10 offset:33536
	s_waitcnt vmcnt(15) lgkmcnt(0)
	v_fmac_f32_e32 v12, v96, v32
	v_fmac_f32_e32 v13, v96, v33
	v_fmac_f32_e32 v14, v96, v34
	v_fmac_f32_e32 v15, v96, v35
	v_fmac_f32_e32 v16, v97, v32
	v_fmac_f32_e32 v17, v97, v33
	v_fmac_f32_e32 v18, v97, v34
	v_fmac_f32_e32 v19, v97, v35
	v_fmac_f32_e32 v20, v98, v32
	v_fmac_f32_e32 v21, v98, v33
	v_fmac_f32_e32 v22, v98, v34
	v_fmac_f32_e32 v23, v98, v35
	v_fmac_f32_e32 v24, v99, v32
	v_fmac_f32_e32 v25, v99, v33
	v_fmac_f32_e32 v26, v99, v34
	v_fmac_f32_e32 v27, v99, v35
	v_fmac_f32_e32 v28, v100, v32
	v_fmac_f32_e32 v29, v100, v33
	v_fmac_f32_e32 v30, v100, v34
	v_fmac_f32_e32 v31, v100, v35
	global_load_dwordx4 v[32:35], v11, s[10:11]
	s_add_u32 s10, s10, 0x18000
	s_addc_u32 s11, s11, 0
	ds_read_b32 v96, v10 offset:776
	ds_read_b32 v97, v10 offset:8968
	ds_read_b32 v98, v10 offset:17160
	ds_read_b32 v99, v10 offset:25352
	ds_read_b32 v100, v10 offset:33544
	s_waitcnt vmcnt(15) lgkmcnt(0)
	v_fmac_f32_e32 v12, v96, v36
	v_fmac_f32_e32 v13, v96, v37
	v_fmac_f32_e32 v14, v96, v38
	v_fmac_f32_e32 v15, v96, v39
	v_fmac_f32_e32 v16, v97, v36
	v_fmac_f32_e32 v17, v97, v37
	v_fmac_f32_e32 v18, v97, v38
	v_fmac_f32_e32 v19, v97, v39
	v_fmac_f32_e32 v20, v98, v36
	v_fmac_f32_e32 v21, v98, v37
	v_fmac_f32_e32 v22, v98, v38
	v_fmac_f32_e32 v23, v98, v39
	v_fmac_f32_e32 v24, v99, v36
	v_fmac_f32_e32 v25, v99, v37
	v_fmac_f32_e32 v26, v99, v38
	v_fmac_f32_e32 v27, v99, v39
	v_fmac_f32_e32 v28, v100, v36
	v_fmac_f32_e32 v29, v100, v37
	v_fmac_f32_e32 v30, v100, v38
	v_fmac_f32_e32 v31, v100, v39
	global_load_dwordx4 v[36:39], v11, s[10:11]
	s_add_u32 s10, s10, 0x18000
	s_addc_u32 s11, s11, 0
	ds_read_b32 v96, v10 offset:784
	ds_read_b32 v97, v10 offset:8976
	ds_read_b32 v98, v10 offset:17168
	ds_read_b32 v99, v10 offset:25360
	ds_read_b32 v100, v10 offset:33552
	s_waitcnt vmcnt(15) lgkmcnt(0)
	v_fmac_f32_e32 v12, v96, v40
	v_fmac_f32_e32 v13, v96, v41
	v_fmac_f32_e32 v14, v96, v42
	v_fmac_f32_e32 v15, v96, v43
	v_fmac_f32_e32 v16, v97, v40
	v_fmac_f32_e32 v17, v97, v41
	v_fmac_f32_e32 v18, v97, v42
	v_fmac_f32_e32 v19, v97, v43
	v_fmac_f32_e32 v20, v98, v40
	v_fmac_f32_e32 v21, v98, v41
	v_fmac_f32_e32 v22, v98, v42
	v_fmac_f32_e32 v23, v98, v43
	v_fmac_f32_e32 v24, v99, v40
	v_fmac_f32_e32 v25, v99, v41
	v_fmac_f32_e32 v26, v99, v42
	v_fmac_f32_e32 v27, v99, v43
	v_fmac_f32_e32 v28, v100, v40
	v_fmac_f32_e32 v29, v100, v41
	v_fmac_f32_e32 v30, v100, v42
	v_fmac_f32_e32 v31, v100, v43
	global_load_dwordx4 v[40:43], v11, s[10:11]
	s_add_u32 s10, s10, 0x18000
	s_addc_u32 s11, s11, 0
	ds_read_b32 v96, v10 offset:792
	ds_read_b32 v97, v10 offset:8984
	ds_read_b32 v98, v10 offset:17176
	ds_read_b32 v99, v10 offset:25368
	ds_read_b32 v100, v10 offset:33560
	s_waitcnt vmcnt(15) lgkmcnt(0)
	v_fmac_f32_e32 v12, v96, v44
	v_fmac_f32_e32 v13, v96, v45
	v_fmac_f32_e32 v14, v96, v46
	v_fmac_f32_e32 v15, v96, v47
	v_fmac_f32_e32 v16, v97, v44
	v_fmac_f32_e32 v17, v97, v45
	v_fmac_f32_e32 v18, v97, v46
	v_fmac_f32_e32 v19, v97, v47
	v_fmac_f32_e32 v20, v98, v44
	v_fmac_f32_e32 v21, v98, v45
	v_fmac_f32_e32 v22, v98, v46
	v_fmac_f32_e32 v23, v98, v47
	v_fmac_f32_e32 v24, v99, v44
	v_fmac_f32_e32 v25, v99, v45
	v_fmac_f32_e32 v26, v99, v46
	v_fmac_f32_e32 v27, v99, v47
	v_fmac_f32_e32 v28, v100, v44
	v_fmac_f32_e32 v29, v100, v45
	v_fmac_f32_e32 v30, v100, v46
	v_fmac_f32_e32 v31, v100, v47
	global_load_dwordx4 v[44:47], v11, s[10:11]
	s_add_u32 s10, s10, 0x18000
	s_addc_u32 s11, s11, 0
	ds_read_b32 v96, v10 offset:800
	ds_read_b32 v97, v10 offset:8992
	ds_read_b32 v98, v10 offset:17184
	ds_read_b32 v99, v10 offset:25376
	ds_read_b32 v100, v10 offset:33568
	s_waitcnt vmcnt(15) lgkmcnt(0)
	v_fmac_f32_e32 v12, v96, v48
	v_fmac_f32_e32 v13, v96, v49
	v_fmac_f32_e32 v14, v96, v50
	v_fmac_f32_e32 v15, v96, v51
	v_fmac_f32_e32 v16, v97, v48
	v_fmac_f32_e32 v17, v97, v49
	v_fmac_f32_e32 v18, v97, v50
	v_fmac_f32_e32 v19, v97, v51
	v_fmac_f32_e32 v20, v98, v48
	v_fmac_f32_e32 v21, v98, v49
	v_fmac_f32_e32 v22, v98, v50
	v_fmac_f32_e32 v23, v98, v51
	v_fmac_f32_e32 v24, v99, v48
	v_fmac_f32_e32 v25, v99, v49
	v_fmac_f32_e32 v26, v99, v50
	v_fmac_f32_e32 v27, v99, v51
	v_fmac_f32_e32 v28, v100, v48
	v_fmac_f32_e32 v29, v100, v49
	v_fmac_f32_e32 v30, v100, v50
	v_fmac_f32_e32 v31, v100, v51
	global_load_dwordx4 v[48:51], v11, s[10:11]
	s_add_u32 s10, s10, 0x18000
	s_addc_u32 s11, s11, 0
	ds_read_b32 v96, v10 offset:808
	ds_read_b32 v97, v10 offset:9000
	ds_read_b32 v98, v10 offset:17192
	ds_read_b32 v99, v10 offset:25384
	ds_read_b32 v100, v10 offset:33576
	s_waitcnt vmcnt(15) lgkmcnt(0)
	v_fmac_f32_e32 v12, v96, v52
	v_fmac_f32_e32 v13, v96, v53
	v_fmac_f32_e32 v14, v96, v54
	v_fmac_f32_e32 v15, v96, v55
	v_fmac_f32_e32 v16, v97, v52
	v_fmac_f32_e32 v17, v97, v53
	v_fmac_f32_e32 v18, v97, v54
	v_fmac_f32_e32 v19, v97, v55
	v_fmac_f32_e32 v20, v98, v52
	v_fmac_f32_e32 v21, v98, v53
	v_fmac_f32_e32 v22, v98, v54
	v_fmac_f32_e32 v23, v98, v55
	v_fmac_f32_e32 v24, v99, v52
	v_fmac_f32_e32 v25, v99, v53
	v_fmac_f32_e32 v26, v99, v54
	v_fmac_f32_e32 v27, v99, v55
	v_fmac_f32_e32 v28, v100, v52
	v_fmac_f32_e32 v29, v100, v53
	v_fmac_f32_e32 v30, v100, v54
	v_fmac_f32_e32 v31, v100, v55
	global_load_dwordx4 v[52:55], v11, s[10:11]
	s_add_u32 s10, s10, 0x18000
	s_addc_u32 s11, s11, 0
	ds_read_b32 v96, v10 offset:816
	ds_read_b32 v97, v10 offset:9008
	ds_read_b32 v98, v10 offset:17200
	ds_read_b32 v99, v10 offset:25392
	ds_read_b32 v100, v10 offset:33584
	s_waitcnt vmcnt(15) lgkmcnt(0)
	v_fmac_f32_e32 v12, v96, v56
	v_fmac_f32_e32 v13, v96, v57
	v_fmac_f32_e32 v14, v96, v58
	v_fmac_f32_e32 v15, v96, v59
	v_fmac_f32_e32 v16, v97, v56
	v_fmac_f32_e32 v17, v97, v57
	v_fmac_f32_e32 v18, v97, v58
	v_fmac_f32_e32 v19, v97, v59
	v_fmac_f32_e32 v20, v98, v56
	v_fmac_f32_e32 v21, v98, v57
	v_fmac_f32_e32 v22, v98, v58
	v_fmac_f32_e32 v23, v98, v59
	v_fmac_f32_e32 v24, v99, v56
	v_fmac_f32_e32 v25, v99, v57
	v_fmac_f32_e32 v26, v99, v58
	v_fmac_f32_e32 v27, v99, v59
	v_fmac_f32_e32 v28, v100, v56
	v_fmac_f32_e32 v29, v100, v57
	v_fmac_f32_e32 v30, v100, v58
	v_fmac_f32_e32 v31, v100, v59
	global_load_dwordx4 v[56:59], v11, s[10:11]
	s_add_u32 s10, s10, 0x18000
	s_addc_u32 s11, s11, 0
	ds_read_b32 v96, v10 offset:824
	ds_read_b32 v97, v10 offset:9016
	ds_read_b32 v98, v10 offset:17208
	ds_read_b32 v99, v10 offset:25400
	ds_read_b32 v100, v10 offset:33592
	s_waitcnt vmcnt(15) lgkmcnt(0)
	v_fmac_f32_e32 v12, v96, v60
	v_fmac_f32_e32 v13, v96, v61
	v_fmac_f32_e32 v14, v96, v62
	v_fmac_f32_e32 v15, v96, v63
	v_fmac_f32_e32 v16, v97, v60
	v_fmac_f32_e32 v17, v97, v61
	v_fmac_f32_e32 v18, v97, v62
	v_fmac_f32_e32 v19, v97, v63
	v_fmac_f32_e32 v20, v98, v60
	v_fmac_f32_e32 v21, v98, v61
	v_fmac_f32_e32 v22, v98, v62
	v_fmac_f32_e32 v23, v98, v63
	v_fmac_f32_e32 v24, v99, v60
	v_fmac_f32_e32 v25, v99, v61
	v_fmac_f32_e32 v26, v99, v62
	v_fmac_f32_e32 v27, v99, v63
	v_fmac_f32_e32 v28, v100, v60
	v_fmac_f32_e32 v29, v100, v61
	v_fmac_f32_e32 v30, v100, v62
	v_fmac_f32_e32 v31, v100, v63
	global_load_dwordx4 v[60:63], v11, s[10:11]
	s_add_u32 s10, s10, 0x18000
	s_addc_u32 s11, s11, 0
	ds_read_b32 v96, v10 offset:832
	ds_read_b32 v97, v10 offset:9024
	ds_read_b32 v98, v10 offset:17216
	ds_read_b32 v99, v10 offset:25408
	ds_read_b32 v100, v10 offset:33600
	s_waitcnt vmcnt(15) lgkmcnt(0)
	v_fmac_f32_e32 v12, v96, v64
	v_fmac_f32_e32 v13, v96, v65
	v_fmac_f32_e32 v14, v96, v66
	v_fmac_f32_e32 v15, v96, v67
	v_fmac_f32_e32 v16, v97, v64
	v_fmac_f32_e32 v17, v97, v65
	v_fmac_f32_e32 v18, v97, v66
	v_fmac_f32_e32 v19, v97, v67
	v_fmac_f32_e32 v20, v98, v64
	v_fmac_f32_e32 v21, v98, v65
	v_fmac_f32_e32 v22, v98, v66
	v_fmac_f32_e32 v23, v98, v67
	v_fmac_f32_e32 v24, v99, v64
	v_fmac_f32_e32 v25, v99, v65
	v_fmac_f32_e32 v26, v99, v66
	v_fmac_f32_e32 v27, v99, v67
	v_fmac_f32_e32 v28, v100, v64
	v_fmac_f32_e32 v29, v100, v65
	v_fmac_f32_e32 v30, v100, v66
	v_fmac_f32_e32 v31, v100, v67
	global_load_dwordx4 v[64:67], v11, s[10:11]
	s_add_u32 s10, s10, 0x18000
	s_addc_u32 s11, s11, 0
	ds_read_b32 v96, v10 offset:840
	ds_read_b32 v97, v10 offset:9032
	ds_read_b32 v98, v10 offset:17224
	ds_read_b32 v99, v10 offset:25416
	ds_read_b32 v100, v10 offset:33608
	s_waitcnt vmcnt(15) lgkmcnt(0)
	v_fmac_f32_e32 v12, v96, v68
	v_fmac_f32_e32 v13, v96, v69
	v_fmac_f32_e32 v14, v96, v70
	v_fmac_f32_e32 v15, v96, v71
	v_fmac_f32_e32 v16, v97, v68
	v_fmac_f32_e32 v17, v97, v69
	v_fmac_f32_e32 v18, v97, v70
	v_fmac_f32_e32 v19, v97, v71
	v_fmac_f32_e32 v20, v98, v68
	v_fmac_f32_e32 v21, v98, v69
	v_fmac_f32_e32 v22, v98, v70
	v_fmac_f32_e32 v23, v98, v71
	v_fmac_f32_e32 v24, v99, v68
	v_fmac_f32_e32 v25, v99, v69
	v_fmac_f32_e32 v26, v99, v70
	v_fmac_f32_e32 v27, v99, v71
	v_fmac_f32_e32 v28, v100, v68
	v_fmac_f32_e32 v29, v100, v69
	v_fmac_f32_e32 v30, v100, v70
	v_fmac_f32_e32 v31, v100, v71
	global_load_dwordx4 v[68:71], v11, s[10:11]
	s_add_u32 s10, s10, 0x18000
	s_addc_u32 s11, s11, 0
	ds_read_b32 v96, v10 offset:848
	ds_read_b32 v97, v10 offset:9040
	ds_read_b32 v98, v10 offset:17232
	ds_read_b32 v99, v10 offset:25424
	ds_read_b32 v100, v10 offset:33616
	s_waitcnt vmcnt(15) lgkmcnt(0)
	v_fmac_f32_e32 v12, v96, v72
	v_fmac_f32_e32 v13, v96, v73
	v_fmac_f32_e32 v14, v96, v74
	v_fmac_f32_e32 v15, v96, v75
	v_fmac_f32_e32 v16, v97, v72
	v_fmac_f32_e32 v17, v97, v73
	v_fmac_f32_e32 v18, v97, v74
	v_fmac_f32_e32 v19, v97, v75
	v_fmac_f32_e32 v20, v98, v72
	v_fmac_f32_e32 v21, v98, v73
	v_fmac_f32_e32 v22, v98, v74
	v_fmac_f32_e32 v23, v98, v75
	v_fmac_f32_e32 v24, v99, v72
	v_fmac_f32_e32 v25, v99, v73
	v_fmac_f32_e32 v26, v99, v74
	v_fmac_f32_e32 v27, v99, v75
	v_fmac_f32_e32 v28, v100, v72
	v_fmac_f32_e32 v29, v100, v73
	v_fmac_f32_e32 v30, v100, v74
	v_fmac_f32_e32 v31, v100, v75
	global_load_dwordx4 v[72:75], v11, s[10:11]
	s_add_u32 s10, s10, 0x18000
	s_addc_u32 s11, s11, 0
	ds_read_b32 v96, v10 offset:856
	ds_read_b32 v97, v10 offset:9048
	ds_read_b32 v98, v10 offset:17240
	ds_read_b32 v99, v10 offset:25432
	ds_read_b32 v100, v10 offset:33624
	s_waitcnt vmcnt(15) lgkmcnt(0)
	v_fmac_f32_e32 v12, v96, v76
	v_fmac_f32_e32 v13, v96, v77
	v_fmac_f32_e32 v14, v96, v78
	v_fmac_f32_e32 v15, v96, v79
	v_fmac_f32_e32 v16, v97, v76
	v_fmac_f32_e32 v17, v97, v77
	v_fmac_f32_e32 v18, v97, v78
	v_fmac_f32_e32 v19, v97, v79
	v_fmac_f32_e32 v20, v98, v76
	v_fmac_f32_e32 v21, v98, v77
	v_fmac_f32_e32 v22, v98, v78
	v_fmac_f32_e32 v23, v98, v79
	v_fmac_f32_e32 v24, v99, v76
	v_fmac_f32_e32 v25, v99, v77
	v_fmac_f32_e32 v26, v99, v78
	v_fmac_f32_e32 v27, v99, v79
	v_fmac_f32_e32 v28, v100, v76
	v_fmac_f32_e32 v29, v100, v77
	v_fmac_f32_e32 v30, v100, v78
	v_fmac_f32_e32 v31, v100, v79
	global_load_dwordx4 v[76:79], v11, s[10:11]
	s_add_u32 s10, s10, 0x18000
	s_addc_u32 s11, s11, 0
	ds_read_b32 v96, v10 offset:864
	ds_read_b32 v97, v10 offset:9056
	ds_read_b32 v98, v10 offset:17248
	ds_read_b32 v99, v10 offset:25440
	ds_read_b32 v100, v10 offset:33632
	s_waitcnt vmcnt(15) lgkmcnt(0)
	v_fmac_f32_e32 v12, v96, v80
	v_fmac_f32_e32 v13, v96, v81
	v_fmac_f32_e32 v14, v96, v82
	v_fmac_f32_e32 v15, v96, v83
	v_fmac_f32_e32 v16, v97, v80
	v_fmac_f32_e32 v17, v97, v81
	v_fmac_f32_e32 v18, v97, v82
	v_fmac_f32_e32 v19, v97, v83
	v_fmac_f32_e32 v20, v98, v80
	v_fmac_f32_e32 v21, v98, v81
	v_fmac_f32_e32 v22, v98, v82
	v_fmac_f32_e32 v23, v98, v83
	v_fmac_f32_e32 v24, v99, v80
	v_fmac_f32_e32 v25, v99, v81
	v_fmac_f32_e32 v26, v99, v82
	v_fmac_f32_e32 v27, v99, v83
	v_fmac_f32_e32 v28, v100, v80
	v_fmac_f32_e32 v29, v100, v81
	v_fmac_f32_e32 v30, v100, v82
	v_fmac_f32_e32 v31, v100, v83
	global_load_dwordx4 v[80:83], v11, s[10:11]
	s_add_u32 s10, s10, 0x18000
	s_addc_u32 s11, s11, 0
	ds_read_b32 v96, v10 offset:872
	ds_read_b32 v97, v10 offset:9064
	ds_read_b32 v98, v10 offset:17256
	ds_read_b32 v99, v10 offset:25448
	ds_read_b32 v100, v10 offset:33640
	s_waitcnt vmcnt(15) lgkmcnt(0)
	v_fmac_f32_e32 v12, v96, v84
	v_fmac_f32_e32 v13, v96, v85
	v_fmac_f32_e32 v14, v96, v86
	v_fmac_f32_e32 v15, v96, v87
	v_fmac_f32_e32 v16, v97, v84
	v_fmac_f32_e32 v17, v97, v85
	v_fmac_f32_e32 v18, v97, v86
	v_fmac_f32_e32 v19, v97, v87
	v_fmac_f32_e32 v20, v98, v84
	v_fmac_f32_e32 v21, v98, v85
	v_fmac_f32_e32 v22, v98, v86
	v_fmac_f32_e32 v23, v98, v87
	v_fmac_f32_e32 v24, v99, v84
	v_fmac_f32_e32 v25, v99, v85
	v_fmac_f32_e32 v26, v99, v86
	v_fmac_f32_e32 v27, v99, v87
	v_fmac_f32_e32 v28, v100, v84
	v_fmac_f32_e32 v29, v100, v85
	v_fmac_f32_e32 v30, v100, v86
	v_fmac_f32_e32 v31, v100, v87
	global_load_dwordx4 v[84:87], v11, s[10:11]
	s_add_u32 s10, s10, 0x18000
	s_addc_u32 s11, s11, 0
	ds_read_b32 v96, v10 offset:880
	ds_read_b32 v97, v10 offset:9072
	ds_read_b32 v98, v10 offset:17264
	ds_read_b32 v99, v10 offset:25456
	ds_read_b32 v100, v10 offset:33648
	s_waitcnt vmcnt(15) lgkmcnt(0)
	v_fmac_f32_e32 v12, v96, v88
	v_fmac_f32_e32 v13, v96, v89
	v_fmac_f32_e32 v14, v96, v90
	v_fmac_f32_e32 v15, v96, v91
	v_fmac_f32_e32 v16, v97, v88
	v_fmac_f32_e32 v17, v97, v89
	v_fmac_f32_e32 v18, v97, v90
	v_fmac_f32_e32 v19, v97, v91
	v_fmac_f32_e32 v20, v98, v88
	v_fmac_f32_e32 v21, v98, v89
	v_fmac_f32_e32 v22, v98, v90
	v_fmac_f32_e32 v23, v98, v91
	v_fmac_f32_e32 v24, v99, v88
	v_fmac_f32_e32 v25, v99, v89
	v_fmac_f32_e32 v26, v99, v90
	v_fmac_f32_e32 v27, v99, v91
	v_fmac_f32_e32 v28, v100, v88
	v_fmac_f32_e32 v29, v100, v89
	v_fmac_f32_e32 v30, v100, v90
	v_fmac_f32_e32 v31, v100, v91
	global_load_dwordx4 v[88:91], v11, s[10:11]
	s_add_u32 s10, s10, 0x18000
	s_addc_u32 s11, s11, 0
	ds_read_b32 v96, v10 offset:888
	ds_read_b32 v97, v10 offset:9080
	ds_read_b32 v98, v10 offset:17272
	ds_read_b32 v99, v10 offset:25464
	ds_read_b32 v100, v10 offset:33656
	s_waitcnt vmcnt(15) lgkmcnt(0)
	v_fmac_f32_e32 v12, v96, v92
	v_fmac_f32_e32 v13, v96, v93
	v_fmac_f32_e32 v14, v96, v94
	v_fmac_f32_e32 v15, v96, v95
	v_fmac_f32_e32 v16, v97, v92
	v_fmac_f32_e32 v17, v97, v93
	v_fmac_f32_e32 v18, v97, v94
	v_fmac_f32_e32 v19, v97, v95
	v_fmac_f32_e32 v20, v98, v92
	v_fmac_f32_e32 v21, v98, v93
	v_fmac_f32_e32 v22, v98, v94
	v_fmac_f32_e32 v23, v98, v95
	v_fmac_f32_e32 v24, v99, v92
	v_fmac_f32_e32 v25, v99, v93
	v_fmac_f32_e32 v26, v99, v94
	v_fmac_f32_e32 v27, v99, v95
	v_fmac_f32_e32 v28, v100, v92
	v_fmac_f32_e32 v29, v100, v93
	v_fmac_f32_e32 v30, v100, v94
	v_fmac_f32_e32 v31, v100, v95
	global_load_dwordx4 v[92:95], v11, s[10:11]
	s_add_u32 s10, s10, 0x18000
	s_addc_u32 s11, s11, 0
	ds_read_b32 v96, v10 offset:896
	ds_read_b32 v97, v10 offset:9088
	ds_read_b32 v98, v10 offset:17280
	ds_read_b32 v99, v10 offset:25472
	ds_read_b32 v100, v10 offset:33664
	s_waitcnt vmcnt(15) lgkmcnt(0)
	v_fmac_f32_e32 v12, v96, v32
	v_fmac_f32_e32 v13, v96, v33
	v_fmac_f32_e32 v14, v96, v34
	v_fmac_f32_e32 v15, v96, v35
	v_fmac_f32_e32 v16, v97, v32
	v_fmac_f32_e32 v17, v97, v33
	v_fmac_f32_e32 v18, v97, v34
	v_fmac_f32_e32 v19, v97, v35
	v_fmac_f32_e32 v20, v98, v32
	v_fmac_f32_e32 v21, v98, v33
	v_fmac_f32_e32 v22, v98, v34
	v_fmac_f32_e32 v23, v98, v35
	v_fmac_f32_e32 v24, v99, v32
	v_fmac_f32_e32 v25, v99, v33
	v_fmac_f32_e32 v26, v99, v34
	v_fmac_f32_e32 v27, v99, v35
	v_fmac_f32_e32 v28, v100, v32
	v_fmac_f32_e32 v29, v100, v33
	v_fmac_f32_e32 v30, v100, v34
	v_fmac_f32_e32 v31, v100, v35
	ds_read_b32 v96, v10 offset:904
	ds_read_b32 v97, v10 offset:9096
	ds_read_b32 v98, v10 offset:17288
	ds_read_b32 v99, v10 offset:25480
	ds_read_b32 v100, v10 offset:33672
	s_waitcnt vmcnt(14) lgkmcnt(0)
	v_fmac_f32_e32 v12, v96, v36
	v_fmac_f32_e32 v13, v96, v37
	v_fmac_f32_e32 v14, v96, v38
	v_fmac_f32_e32 v15, v96, v39
	v_fmac_f32_e32 v16, v97, v36
	v_fmac_f32_e32 v17, v97, v37
	v_fmac_f32_e32 v18, v97, v38
	v_fmac_f32_e32 v19, v97, v39
	v_fmac_f32_e32 v20, v98, v36
	v_fmac_f32_e32 v21, v98, v37
	v_fmac_f32_e32 v22, v98, v38
	v_fmac_f32_e32 v23, v98, v39
	v_fmac_f32_e32 v24, v99, v36
	v_fmac_f32_e32 v25, v99, v37
	v_fmac_f32_e32 v26, v99, v38
	v_fmac_f32_e32 v27, v99, v39
	v_fmac_f32_e32 v28, v100, v36
	v_fmac_f32_e32 v29, v100, v37
	v_fmac_f32_e32 v30, v100, v38
	v_fmac_f32_e32 v31, v100, v39
	ds_read_b32 v96, v10 offset:912
	ds_read_b32 v97, v10 offset:9104
	ds_read_b32 v98, v10 offset:17296
	ds_read_b32 v99, v10 offset:25488
	ds_read_b32 v100, v10 offset:33680
	s_waitcnt vmcnt(13) lgkmcnt(0)
	v_fmac_f32_e32 v12, v96, v40
	v_fmac_f32_e32 v13, v96, v41
	v_fmac_f32_e32 v14, v96, v42
	v_fmac_f32_e32 v15, v96, v43
	v_fmac_f32_e32 v16, v97, v40
	v_fmac_f32_e32 v17, v97, v41
	v_fmac_f32_e32 v18, v97, v42
	v_fmac_f32_e32 v19, v97, v43
	v_fmac_f32_e32 v20, v98, v40
	v_fmac_f32_e32 v21, v98, v41
	v_fmac_f32_e32 v22, v98, v42
	v_fmac_f32_e32 v23, v98, v43
	v_fmac_f32_e32 v24, v99, v40
	v_fmac_f32_e32 v25, v99, v41
	v_fmac_f32_e32 v26, v99, v42
	v_fmac_f32_e32 v27, v99, v43
	v_fmac_f32_e32 v28, v100, v40
	v_fmac_f32_e32 v29, v100, v41
	v_fmac_f32_e32 v30, v100, v42
	v_fmac_f32_e32 v31, v100, v43
	ds_read_b32 v96, v10 offset:920
	ds_read_b32 v97, v10 offset:9112
	ds_read_b32 v98, v10 offset:17304
	ds_read_b32 v99, v10 offset:25496
	ds_read_b32 v100, v10 offset:33688
	s_waitcnt vmcnt(12) lgkmcnt(0)
	v_fmac_f32_e32 v12, v96, v44
	v_fmac_f32_e32 v13, v96, v45
	v_fmac_f32_e32 v14, v96, v46
	v_fmac_f32_e32 v15, v96, v47
	v_fmac_f32_e32 v16, v97, v44
	v_fmac_f32_e32 v17, v97, v45
	v_fmac_f32_e32 v18, v97, v46
	v_fmac_f32_e32 v19, v97, v47
	v_fmac_f32_e32 v20, v98, v44
	v_fmac_f32_e32 v21, v98, v45
	v_fmac_f32_e32 v22, v98, v46
	v_fmac_f32_e32 v23, v98, v47
	v_fmac_f32_e32 v24, v99, v44
	v_fmac_f32_e32 v25, v99, v45
	v_fmac_f32_e32 v26, v99, v46
	v_fmac_f32_e32 v27, v99, v47
	v_fmac_f32_e32 v28, v100, v44
	v_fmac_f32_e32 v29, v100, v45
	v_fmac_f32_e32 v30, v100, v46
	v_fmac_f32_e32 v31, v100, v47
	ds_read_b32 v96, v10 offset:928
	ds_read_b32 v97, v10 offset:9120
	ds_read_b32 v98, v10 offset:17312
	ds_read_b32 v99, v10 offset:25504
	ds_read_b32 v100, v10 offset:33696
	s_waitcnt vmcnt(11) lgkmcnt(0)
	v_fmac_f32_e32 v12, v96, v48
	v_fmac_f32_e32 v13, v96, v49
	v_fmac_f32_e32 v14, v96, v50
	v_fmac_f32_e32 v15, v96, v51
	v_fmac_f32_e32 v16, v97, v48
	v_fmac_f32_e32 v17, v97, v49
	v_fmac_f32_e32 v18, v97, v50
	v_fmac_f32_e32 v19, v97, v51
	v_fmac_f32_e32 v20, v98, v48
	v_fmac_f32_e32 v21, v98, v49
	v_fmac_f32_e32 v22, v98, v50
	v_fmac_f32_e32 v23, v98, v51
	v_fmac_f32_e32 v24, v99, v48
	v_fmac_f32_e32 v25, v99, v49
	v_fmac_f32_e32 v26, v99, v50
	v_fmac_f32_e32 v27, v99, v51
	v_fmac_f32_e32 v28, v100, v48
	v_fmac_f32_e32 v29, v100, v49
	v_fmac_f32_e32 v30, v100, v50
	v_fmac_f32_e32 v31, v100, v51
	ds_read_b32 v96, v10 offset:936
	ds_read_b32 v97, v10 offset:9128
	ds_read_b32 v98, v10 offset:17320
	ds_read_b32 v99, v10 offset:25512
	ds_read_b32 v100, v10 offset:33704
	s_waitcnt vmcnt(10) lgkmcnt(0)
	v_fmac_f32_e32 v12, v96, v52
	v_fmac_f32_e32 v13, v96, v53
	v_fmac_f32_e32 v14, v96, v54
	v_fmac_f32_e32 v15, v96, v55
	v_fmac_f32_e32 v16, v97, v52
	v_fmac_f32_e32 v17, v97, v53
	v_fmac_f32_e32 v18, v97, v54
	v_fmac_f32_e32 v19, v97, v55
	v_fmac_f32_e32 v20, v98, v52
	v_fmac_f32_e32 v21, v98, v53
	v_fmac_f32_e32 v22, v98, v54
	v_fmac_f32_e32 v23, v98, v55
	v_fmac_f32_e32 v24, v99, v52
	v_fmac_f32_e32 v25, v99, v53
	v_fmac_f32_e32 v26, v99, v54
	v_fmac_f32_e32 v27, v99, v55
	v_fmac_f32_e32 v28, v100, v52
	v_fmac_f32_e32 v29, v100, v53
	v_fmac_f32_e32 v30, v100, v54
	v_fmac_f32_e32 v31, v100, v55
	ds_read_b32 v96, v10 offset:944
	ds_read_b32 v97, v10 offset:9136
	ds_read_b32 v98, v10 offset:17328
	ds_read_b32 v99, v10 offset:25520
	ds_read_b32 v100, v10 offset:33712
	s_waitcnt vmcnt(9) lgkmcnt(0)
	v_fmac_f32_e32 v12, v96, v56
	v_fmac_f32_e32 v13, v96, v57
	v_fmac_f32_e32 v14, v96, v58
	v_fmac_f32_e32 v15, v96, v59
	v_fmac_f32_e32 v16, v97, v56
	v_fmac_f32_e32 v17, v97, v57
	v_fmac_f32_e32 v18, v97, v58
	v_fmac_f32_e32 v19, v97, v59
	v_fmac_f32_e32 v20, v98, v56
	v_fmac_f32_e32 v21, v98, v57
	v_fmac_f32_e32 v22, v98, v58
	v_fmac_f32_e32 v23, v98, v59
	v_fmac_f32_e32 v24, v99, v56
	v_fmac_f32_e32 v25, v99, v57
	v_fmac_f32_e32 v26, v99, v58
	v_fmac_f32_e32 v27, v99, v59
	v_fmac_f32_e32 v28, v100, v56
	v_fmac_f32_e32 v29, v100, v57
	v_fmac_f32_e32 v30, v100, v58
	v_fmac_f32_e32 v31, v100, v59
	ds_read_b32 v96, v10 offset:952
	ds_read_b32 v97, v10 offset:9144
	ds_read_b32 v98, v10 offset:17336
	ds_read_b32 v99, v10 offset:25528
	ds_read_b32 v100, v10 offset:33720
	s_waitcnt vmcnt(8) lgkmcnt(0)
	v_fmac_f32_e32 v12, v96, v60
	v_fmac_f32_e32 v13, v96, v61
	v_fmac_f32_e32 v14, v96, v62
	v_fmac_f32_e32 v15, v96, v63
	v_fmac_f32_e32 v16, v97, v60
	v_fmac_f32_e32 v17, v97, v61
	v_fmac_f32_e32 v18, v97, v62
	v_fmac_f32_e32 v19, v97, v63
	v_fmac_f32_e32 v20, v98, v60
	v_fmac_f32_e32 v21, v98, v61
	v_fmac_f32_e32 v22, v98, v62
	v_fmac_f32_e32 v23, v98, v63
	v_fmac_f32_e32 v24, v99, v60
	v_fmac_f32_e32 v25, v99, v61
	v_fmac_f32_e32 v26, v99, v62
	v_fmac_f32_e32 v27, v99, v63
	v_fmac_f32_e32 v28, v100, v60
	v_fmac_f32_e32 v29, v100, v61
	v_fmac_f32_e32 v30, v100, v62
	v_fmac_f32_e32 v31, v100, v63
	ds_read_b32 v96, v10 offset:960
	ds_read_b32 v97, v10 offset:9152
	ds_read_b32 v98, v10 offset:17344
	ds_read_b32 v99, v10 offset:25536
	ds_read_b32 v100, v10 offset:33728
	s_waitcnt vmcnt(7) lgkmcnt(0)
	v_fmac_f32_e32 v12, v96, v64
	v_fmac_f32_e32 v13, v96, v65
	v_fmac_f32_e32 v14, v96, v66
	v_fmac_f32_e32 v15, v96, v67
	v_fmac_f32_e32 v16, v97, v64
	v_fmac_f32_e32 v17, v97, v65
	v_fmac_f32_e32 v18, v97, v66
	v_fmac_f32_e32 v19, v97, v67
	v_fmac_f32_e32 v20, v98, v64
	v_fmac_f32_e32 v21, v98, v65
	v_fmac_f32_e32 v22, v98, v66
	v_fmac_f32_e32 v23, v98, v67
	v_fmac_f32_e32 v24, v99, v64
	v_fmac_f32_e32 v25, v99, v65
	v_fmac_f32_e32 v26, v99, v66
	v_fmac_f32_e32 v27, v99, v67
	v_fmac_f32_e32 v28, v100, v64
	v_fmac_f32_e32 v29, v100, v65
	v_fmac_f32_e32 v30, v100, v66
	v_fmac_f32_e32 v31, v100, v67
	ds_read_b32 v96, v10 offset:968
	ds_read_b32 v97, v10 offset:9160
	ds_read_b32 v98, v10 offset:17352
	ds_read_b32 v99, v10 offset:25544
	ds_read_b32 v100, v10 offset:33736
	s_waitcnt vmcnt(6) lgkmcnt(0)
	v_fmac_f32_e32 v12, v96, v68
	v_fmac_f32_e32 v13, v96, v69
	v_fmac_f32_e32 v14, v96, v70
	v_fmac_f32_e32 v15, v96, v71
	v_fmac_f32_e32 v16, v97, v68
	v_fmac_f32_e32 v17, v97, v69
	v_fmac_f32_e32 v18, v97, v70
	v_fmac_f32_e32 v19, v97, v71
	v_fmac_f32_e32 v20, v98, v68
	v_fmac_f32_e32 v21, v98, v69
	v_fmac_f32_e32 v22, v98, v70
	v_fmac_f32_e32 v23, v98, v71
	v_fmac_f32_e32 v24, v99, v68
	v_fmac_f32_e32 v25, v99, v69
	v_fmac_f32_e32 v26, v99, v70
	v_fmac_f32_e32 v27, v99, v71
	v_fmac_f32_e32 v28, v100, v68
	v_fmac_f32_e32 v29, v100, v69
	v_fmac_f32_e32 v30, v100, v70
	v_fmac_f32_e32 v31, v100, v71
	ds_read_b32 v96, v10 offset:976
	ds_read_b32 v97, v10 offset:9168
	ds_read_b32 v98, v10 offset:17360
	ds_read_b32 v99, v10 offset:25552
	ds_read_b32 v100, v10 offset:33744
	s_waitcnt vmcnt(5) lgkmcnt(0)
	v_fmac_f32_e32 v12, v96, v72
	v_fmac_f32_e32 v13, v96, v73
	v_fmac_f32_e32 v14, v96, v74
	v_fmac_f32_e32 v15, v96, v75
	v_fmac_f32_e32 v16, v97, v72
	v_fmac_f32_e32 v17, v97, v73
	v_fmac_f32_e32 v18, v97, v74
	v_fmac_f32_e32 v19, v97, v75
	v_fmac_f32_e32 v20, v98, v72
	v_fmac_f32_e32 v21, v98, v73
	v_fmac_f32_e32 v22, v98, v74
	v_fmac_f32_e32 v23, v98, v75
	v_fmac_f32_e32 v24, v99, v72
	v_fmac_f32_e32 v25, v99, v73
	v_fmac_f32_e32 v26, v99, v74
	v_fmac_f32_e32 v27, v99, v75
	v_fmac_f32_e32 v28, v100, v72
	v_fmac_f32_e32 v29, v100, v73
	v_fmac_f32_e32 v30, v100, v74
	v_fmac_f32_e32 v31, v100, v75
	ds_read_b32 v96, v10 offset:984
	ds_read_b32 v97, v10 offset:9176
	ds_read_b32 v98, v10 offset:17368
	ds_read_b32 v99, v10 offset:25560
	ds_read_b32 v100, v10 offset:33752
	s_waitcnt vmcnt(4) lgkmcnt(0)
	v_fmac_f32_e32 v12, v96, v76
	v_fmac_f32_e32 v13, v96, v77
	v_fmac_f32_e32 v14, v96, v78
	v_fmac_f32_e32 v15, v96, v79
	v_fmac_f32_e32 v16, v97, v76
	v_fmac_f32_e32 v17, v97, v77
	v_fmac_f32_e32 v18, v97, v78
	v_fmac_f32_e32 v19, v97, v79
	v_fmac_f32_e32 v20, v98, v76
	v_fmac_f32_e32 v21, v98, v77
	v_fmac_f32_e32 v22, v98, v78
	v_fmac_f32_e32 v23, v98, v79
	v_fmac_f32_e32 v24, v99, v76
	v_fmac_f32_e32 v25, v99, v77
	v_fmac_f32_e32 v26, v99, v78
	v_fmac_f32_e32 v27, v99, v79
	v_fmac_f32_e32 v28, v100, v76
	v_fmac_f32_e32 v29, v100, v77
	v_fmac_f32_e32 v30, v100, v78
	v_fmac_f32_e32 v31, v100, v79
	ds_read_b32 v96, v10 offset:992
	ds_read_b32 v97, v10 offset:9184
	ds_read_b32 v98, v10 offset:17376
	ds_read_b32 v99, v10 offset:25568
	ds_read_b32 v100, v10 offset:33760
	s_waitcnt vmcnt(3) lgkmcnt(0)
	v_fmac_f32_e32 v12, v96, v80
	v_fmac_f32_e32 v13, v96, v81
	v_fmac_f32_e32 v14, v96, v82
	v_fmac_f32_e32 v15, v96, v83
	v_fmac_f32_e32 v16, v97, v80
	v_fmac_f32_e32 v17, v97, v81
	v_fmac_f32_e32 v18, v97, v82
	v_fmac_f32_e32 v19, v97, v83
	v_fmac_f32_e32 v20, v98, v80
	v_fmac_f32_e32 v21, v98, v81
	v_fmac_f32_e32 v22, v98, v82
	v_fmac_f32_e32 v23, v98, v83
	v_fmac_f32_e32 v24, v99, v80
	v_fmac_f32_e32 v25, v99, v81
	v_fmac_f32_e32 v26, v99, v82
	v_fmac_f32_e32 v27, v99, v83
	v_fmac_f32_e32 v28, v100, v80
	v_fmac_f32_e32 v29, v100, v81
	v_fmac_f32_e32 v30, v100, v82
	v_fmac_f32_e32 v31, v100, v83
	ds_read_b32 v96, v10 offset:1000
	ds_read_b32 v97, v10 offset:9192
	ds_read_b32 v98, v10 offset:17384
	ds_read_b32 v99, v10 offset:25576
	ds_read_b32 v100, v10 offset:33768
	s_waitcnt vmcnt(2) lgkmcnt(0)
	v_fmac_f32_e32 v12, v96, v84
	v_fmac_f32_e32 v13, v96, v85
	v_fmac_f32_e32 v14, v96, v86
	v_fmac_f32_e32 v15, v96, v87
	v_fmac_f32_e32 v16, v97, v84
	v_fmac_f32_e32 v17, v97, v85
	v_fmac_f32_e32 v18, v97, v86
	v_fmac_f32_e32 v19, v97, v87
	v_fmac_f32_e32 v20, v98, v84
	v_fmac_f32_e32 v21, v98, v85
	v_fmac_f32_e32 v22, v98, v86
	v_fmac_f32_e32 v23, v98, v87
	v_fmac_f32_e32 v24, v99, v84
	v_fmac_f32_e32 v25, v99, v85
	v_fmac_f32_e32 v26, v99, v86
	v_fmac_f32_e32 v27, v99, v87
	v_fmac_f32_e32 v28, v100, v84
	v_fmac_f32_e32 v29, v100, v85
	v_fmac_f32_e32 v30, v100, v86
	v_fmac_f32_e32 v31, v100, v87
	ds_read_b32 v96, v10 offset:1008
	ds_read_b32 v97, v10 offset:9200
	ds_read_b32 v98, v10 offset:17392
	ds_read_b32 v99, v10 offset:25584
	ds_read_b32 v100, v10 offset:33776
	s_waitcnt vmcnt(1) lgkmcnt(0)
	v_fmac_f32_e32 v12, v96, v88
	v_fmac_f32_e32 v13, v96, v89
	v_fmac_f32_e32 v14, v96, v90
	v_fmac_f32_e32 v15, v96, v91
	v_fmac_f32_e32 v16, v97, v88
	v_fmac_f32_e32 v17, v97, v89
	v_fmac_f32_e32 v18, v97, v90
	v_fmac_f32_e32 v19, v97, v91
	v_fmac_f32_e32 v20, v98, v88
	v_fmac_f32_e32 v21, v98, v89
	v_fmac_f32_e32 v22, v98, v90
	v_fmac_f32_e32 v23, v98, v91
	v_fmac_f32_e32 v24, v99, v88
	v_fmac_f32_e32 v25, v99, v89
	v_fmac_f32_e32 v26, v99, v90
	v_fmac_f32_e32 v27, v99, v91
	v_fmac_f32_e32 v28, v100, v88
	v_fmac_f32_e32 v29, v100, v89
	v_fmac_f32_e32 v30, v100, v90
	v_fmac_f32_e32 v31, v100, v91
	ds_read_b32 v96, v10 offset:1016
	ds_read_b32 v97, v10 offset:9208
	ds_read_b32 v98, v10 offset:17400
	ds_read_b32 v99, v10 offset:25592
	ds_read_b32 v100, v10 offset:33784
	s_waitcnt vmcnt(0) lgkmcnt(0)
	v_fmac_f32_e32 v12, v96, v92
	v_fmac_f32_e32 v13, v96, v93
	v_fmac_f32_e32 v14, v96, v94
	v_fmac_f32_e32 v15, v96, v95
	v_fmac_f32_e32 v16, v97, v92
	v_fmac_f32_e32 v17, v97, v93
	v_fmac_f32_e32 v18, v97, v94
	v_fmac_f32_e32 v19, v97, v95
	v_fmac_f32_e32 v20, v98, v92
	v_fmac_f32_e32 v21, v98, v93
	v_fmac_f32_e32 v22, v98, v94
	v_fmac_f32_e32 v23, v98, v95
	v_fmac_f32_e32 v24, v99, v92
	v_fmac_f32_e32 v25, v99, v93
	v_fmac_f32_e32 v26, v99, v94
	v_fmac_f32_e32 v27, v99, v95
	v_fmac_f32_e32 v28, v100, v92
	v_fmac_f32_e32 v29, v100, v93
	v_fmac_f32_e32 v30, v100, v94
	v_fmac_f32_e32 v31, v100, v95
	v_lshl_add_u32 v5, v4, 1, v2
	v_mul_u32_u24_e32 v5, 24, v5
	v_add_u32_e32 v5, v5, v3
	v_mul_u32_u24_e32 v5, 80, v5
	v_add_u32_e32 v5, 0xa000, v5
	ds_write_b128 v5, v[12:15] offset:0
	ds_write_b128 v5, v[16:19] offset:16
	ds_write_b128 v5, v[20:23] offset:32
	ds_write_b128 v5, v[24:27] offset:48
	ds_write_b128 v5, v[28:31] offset:64
	s_mov_b64 exec, s[20:21]
	s_waitcnt lgkmcnt(0)
	s_barrier
	v_cmp_gt_u32_e32 vcc, 480, v154
	s_and_saveexec_b64 s[20:21], vcc
	v_mul_u32_u24_e32 v1, 0xccd, v154
	v_lshrrev_b32_e32 v1, 16, v1
	v_mul_u32_u24_e32 v2, 20, v1
	v_sub_u32_e32 v2, v154, v2
	v_mul_u32_u24_e32 v3, 80, v1
	v_lshl_add_u32 v3, v2, 2, v3
	v_add_u32_e32 v3, 0xa000, v3
	ds_read_b32 v32, v3 offset:0
	ds_read_b32 v33, v3 offset:1920
	ds_read_b32 v34, v3 offset:3840
	ds_read_b32 v35, v3 offset:5760
	ds_read_b32 v36, v3 offset:7680
	ds_read_b32 v37, v3 offset:9600
	ds_read_b32 v38, v3 offset:11520
	ds_read_b32 v39, v3 offset:13440
	ds_read_b32 v40, v3 offset:15360
	ds_read_b32 v41, v3 offset:17280
	ds_read_b32 v42, v3 offset:19200
	ds_read_b32 v43, v3 offset:21120
	ds_read_b32 v44, v3 offset:23040
	ds_read_b32 v45, v3 offset:24960
	ds_read_b32 v46, v3 offset:26880
	ds_read_b32 v47, v3 offset:28800
	v_lshrrev_b32_e32 v4, 2, v2
	v_and_b32_e32 v5, 3, v2
	v_lshl_add_u32 v5, v1, 2, v5
	v_add_u32_e32 v5, s9, v5
	s_mul_i32 s12, s8, 12288
	v_add_u32_e32 v6, s12, v5
	v_lshlrev_b32_e32 v6, 2, v6
	global_load_dword v7, v6, s[2:3]
	s_mul_i32 s12, s8, 5
	v_add_u32_e32 v4, s12, v4
	v_mul_u32_u24_e32 v4, 12288, v4
	v_add_u32_e32 v4, v4, v5
	v_lshlrev_b32_e32 v4, 2, v4
	s_add_u32 s12, s90, 0x10400000
	s_addc_u32 s13, s91, 0
	s_waitcnt lgkmcnt(0)
	v_mov_b32_e32 v8, 0
	v_add_f32_e32 v8, v8, v32
	v_add_f32_e32 v8, v8, v33
	v_add_f32_e32 v8, v8, v34
	v_add_f32_e32 v8, v8, v35
	v_add_f32_e32 v8, v8, v36
	v_add_f32_e32 v8, v8, v37
	v_add_f32_e32 v8, v8, v38
	v_add_f32_e32 v8, v8, v39
	v_add_f32_e32 v8, v8, v40
	v_add_f32_e32 v8, v8, v41
	v_add_f32_e32 v8, v8, v42
	v_add_f32_e32 v8, v8, v43
	v_add_f32_e32 v8, v8, v44
	v_add_f32_e32 v8, v8, v45
	v_add_f32_e32 v8, v8, v46
	v_add_f32_e32 v8, v8, v47
	s_waitcnt vmcnt(0)
	v_add_f32_e32 v8, v8, v7
	global_store_dword v4, v8, s[12:13]
	s_or_b64 exec, exec, s[20:21]
	s_waitcnt vmcnt(0)
	s_barrier
	v_mov_b32_e32 v22, v154
	s_branch .LBB0_97
